# K-loops: phases 4/8 folded into phases 3/7 (their DMA issued at the end of load segments 3/7, clean 32-MFMA bursts, 12 barriers per K iteration, vmcnt(6) at the close of load segments 3 and 7)
# speedup vs baseline: 1.0227x; 1.0227x over previous
.LBB0_124:
	s_nop 0
	s_ashr_i32 s79, s78, 31
	s_lshl_b64 s[10:11], s[78:79], 19
	s_add_u32 s80, s54, s10
	v_cmp_lt_i64_e32 vcc, s[72:73], v[178:179]
	s_addc_u32 s81, s55, s11
	s_and_b64 s[10:11], vcc, exec
	s_cselect_b32 s1, s81, s87
	s_cselect_b32 s10, s80, s86
	s_ashr_i32 s77, s76, 31
	s_lshl_b64 s[36:37], s[76:77], 19
	s_add_u32 s72, s66, s36
	s_addc_u32 s73, s59, s37
	s_and_b64 s[36:37], vcc, exec
	s_cselect_b32 s11, s73, s83
	s_cselect_b32 s25, s72, s82
	s_add_u32 s86, s86, 0x40080
	s_addc_u32 s87, s87, 0
	s_add_u32 s33, s82, 0x100
	s_addc_u32 s36, s83, 0
	s_mov_b32 s37, -2
	s_add_u32 s27, s86, 0xfffc0080
	s_addc_u32 s56, s87, -1
	s_add_i32 s57, 0, 0x10000
	ds_read_b128 v[64:67], v217
	ds_read_b128 v[68:71], v217 offset:1024
	ds_read_b128 v[72:75], v217 offset:2048
	ds_read_b128 v[76:79], v217 offset:3072
	s_cmp_eq_u32 s37, 12
	s_cselect_b32 vcc_hi, s1, s56
	s_cselect_b32 vcc_lo, s10, s27
	s_cselect_b32 s83, s11, s36
	s_cselect_b32 s82, s25, s33
	s_add_i32 m0, s75, 0xc000
	ds_read_b128 v[80:83], v220
	ds_read_b128 v[84:87], v220 offset:1024
	ds_read_b128 v[88:91], v220 offset:2048
	ds_read_b128 v[92:95], v220 offset:3072
	ds_read_b128 v[188:191], v220 offset:4096
	ds_read_b128 v[192:195], v220 offset:5120
	ds_read_b128 v[196:199], v220 offset:6144
	ds_read_b128 v[200:203], v220 offset:7168
	global_load_lds_dwordx4 v164, s[86:87]
	s_add_i32 m0, s75, 0xe000
	s_nop 0
	global_load_lds_dwordx4 v166, s[86:87]
	s_waitcnt lgkmcnt(0)
	s_barrier
	v_mfma_f32_16x16x32_bf16 v[146:149], v[64:67], v[80:83], 0
	v_mfma_f32_16x16x32_bf16 v[116:119], v[72:75], v[80:83], 0
	v_mfma_f32_16x16x32_bf16 v[158:161], v[64:67], v[88:91], 0
	v_mfma_f32_16x16x32_bf16 v[124:127], v[72:75], v[88:91], 0
	v_mfma_f32_16x16x32_bf16 v[154:157], v[64:67], v[188:191], 0
	v_mfma_f32_16x16x32_bf16 v[112:115], v[72:75], v[188:191], 0
	v_mfma_f32_16x16x32_bf16 v[150:153], v[64:67], v[196:199], 0
	v_mfma_f32_16x16x32_bf16 v[120:123], v[72:75], v[196:199], 0
	v_mfma_f32_16x16x32_bf16 v[146:149], v[68:71], v[84:87], v[146:149]
	v_mfma_f32_16x16x32_bf16 v[116:119], v[76:79], v[84:87], v[116:119]
	v_mfma_f32_16x16x32_bf16 v[158:161], v[68:71], v[92:95], v[158:161]
	v_mfma_f32_16x16x32_bf16 v[124:127], v[76:79], v[92:95], v[124:127]
	v_mfma_f32_16x16x32_bf16 v[154:157], v[68:71], v[192:195], v[154:157]
	v_mfma_f32_16x16x32_bf16 v[112:115], v[76:79], v[192:195], v[112:115]
	v_mfma_f32_16x16x32_bf16 v[150:153], v[68:71], v[200:203], v[150:153]
	v_mfma_f32_16x16x32_bf16 v[120:123], v[76:79], v[200:203], v[120:123]
	s_barrier
	s_add_i32 s27, 0, 0x14000
	s_add_i32 s56, s57, s74
	ds_read_b128 v[204:207], v217 offset:16384
	ds_read_b128 v[222:225], v217 offset:17408
	ds_read_b128 v[228:231], v217 offset:18432
	ds_read_b128 v[232:235], v217 offset:19456
	s_mov_b32 m0, s56
	global_load_lds_dwordx4 v144, s[82:83]
	s_add_i32 m0, s56, 0x2000
	s_nop 0
	global_load_lds_dwordx4 v162, s[82:83]
	s_waitcnt lgkmcnt(0)
	s_barrier
	v_mfma_f32_16x16x32_bf16 v[140:143], v[204:207], v[80:83], 0
	v_mfma_f32_16x16x32_bf16 v[80:83], v[228:231], v[80:83], 0
	v_mfma_f32_16x16x32_bf16 v[140:143], v[222:225], v[84:87], v[140:143]
	v_mfma_f32_16x16x32_bf16 v[80:83], v[232:235], v[84:87], v[80:83]
	v_mfma_f32_16x16x32_bf16 v[84:87], v[204:207], v[88:91], 0
	v_mfma_f32_16x16x32_bf16 v[88:91], v[228:231], v[88:91], 0
	v_mfma_f32_16x16x32_bf16 v[100:103], v[228:231], v[188:191], 0
	v_mfma_f32_16x16x32_bf16 v[104:107], v[204:207], v[196:199], 0
	v_mfma_f32_16x16x32_bf16 v[96:99], v[228:231], v[196:199], 0
	v_mfma_f32_16x16x32_bf16 v[84:87], v[222:225], v[92:95], v[84:87]
	v_mfma_f32_16x16x32_bf16 v[88:91], v[232:235], v[92:95], v[88:91]
	v_mfma_f32_16x16x32_bf16 v[92:95], v[204:207], v[188:191], 0
	v_mfma_f32_16x16x32_bf16 v[100:103], v[232:235], v[192:195], v[100:103]
	v_mfma_f32_16x16x32_bf16 v[128:131], v[222:225], v[200:203], v[104:107]
	v_mfma_f32_16x16x32_bf16 v[96:99], v[232:235], v[200:203], v[96:99]
	v_mfma_f32_16x16x32_bf16 v[92:95], v[222:225], v[192:195], v[92:95]
	s_barrier
	s_mov_b32 m0, s75
	ds_read_b128 v[104:107], v220 offset:16384
	ds_read_b128 v[108:111], v220 offset:17408
	ds_read_b128 v[132:135], v220 offset:18432
	ds_read_b128 v[136:139], v220 offset:19456
	ds_read_b128 v[188:191], v220 offset:20480
	ds_read_b128 v[192:195], v220 offset:21504
	ds_read_b128 v[196:199], v220 offset:22528
	ds_read_b128 v[200:203], v220 offset:23552
	global_load_lds_dwordx4 v144, vcc
	s_mov_b32 m0, s85
	s_nop 0
	global_load_lds_dwordx4 v162, vcc
	s_add_u32 s56, s82, 0x40000
	s_addc_u32 s57, s83, 0
	s_add_i32 s27, s27, s74
	s_mov_b32 m0, s27
	s_nop 0
	global_load_lds_dwordx4 v144, s[56:57]
	s_add_i32 m0, s27, 0x2000
	s_nop 0
	global_load_lds_dwordx4 v162, s[56:57]
	s_waitcnt lgkmcnt(0)
	s_waitcnt vmcnt(6)
	s_barrier
	v_mfma_f32_16x16x32_bf16 v[48:51], v[64:67], v[104:107], 0
	v_mfma_f32_16x16x32_bf16 v[20:23], v[72:75], v[104:107], 0
	v_mfma_f32_16x16x32_bf16 v[60:63], v[64:67], v[132:135], 0
	v_mfma_f32_16x16x32_bf16 v[28:31], v[72:75], v[132:135], 0
	v_mfma_f32_16x16x32_bf16 v[56:59], v[64:67], v[188:191], 0
	v_mfma_f32_16x16x32_bf16 v[16:19], v[72:75], v[188:191], 0
	v_mfma_f32_16x16x32_bf16 v[52:55], v[64:67], v[196:199], 0
	v_mfma_f32_16x16x32_bf16 v[24:27], v[72:75], v[196:199], 0
	v_mfma_f32_16x16x32_bf16 v[48:51], v[68:71], v[108:111], v[48:51]
	v_mfma_f32_16x16x32_bf16 v[20:23], v[76:79], v[108:111], v[20:23]
	v_mfma_f32_16x16x32_bf16 v[60:63], v[68:71], v[136:139], v[60:63]
	v_mfma_f32_16x16x32_bf16 v[28:31], v[76:79], v[136:139], v[28:31]
	v_mfma_f32_16x16x32_bf16 v[56:59], v[68:71], v[192:195], v[56:59]
	v_mfma_f32_16x16x32_bf16 v[16:19], v[76:79], v[192:195], v[16:19]
	v_mfma_f32_16x16x32_bf16 v[52:55], v[68:71], v[200:203], v[52:55]
	v_mfma_f32_16x16x32_bf16 v[24:27], v[76:79], v[200:203], v[24:27]
	v_mfma_f32_16x16x32_bf16 v[44:47], v[204:207], v[104:107], 0
	v_mfma_f32_16x16x32_bf16 v[12:15], v[228:231], v[104:107], 0
	v_mfma_f32_16x16x32_bf16 v[40:43], v[204:207], v[132:135], 0
	v_mfma_f32_16x16x32_bf16 v[8:11], v[228:231], v[132:135], 0
	v_mfma_f32_16x16x32_bf16 v[36:39], v[204:207], v[188:191], 0
	v_mfma_f32_16x16x32_bf16 v[4:7], v[228:231], v[188:191], 0
	v_mfma_f32_16x16x32_bf16 v[32:35], v[204:207], v[196:199], 0
	v_mfma_f32_16x16x32_bf16 v[0:3], v[228:231], v[196:199], 0
	v_mfma_f32_16x16x32_bf16 v[44:47], v[222:225], v[108:111], v[44:47]
	v_mfma_f32_16x16x32_bf16 v[12:15], v[232:235], v[108:111], v[12:15]
	v_mfma_f32_16x16x32_bf16 v[40:43], v[222:225], v[136:139], v[40:43]
	v_mfma_f32_16x16x32_bf16 v[8:11], v[232:235], v[136:139], v[8:11]
	v_mfma_f32_16x16x32_bf16 v[36:39], v[222:225], v[192:195], v[36:39]
	v_mfma_f32_16x16x32_bf16 v[4:7], v[232:235], v[192:195], v[4:7]
	v_mfma_f32_16x16x32_bf16 v[32:35], v[222:225], v[200:203], v[32:35]
	v_mfma_f32_16x16x32_bf16 v[0:3], v[232:235], v[200:203], v[0:3]
	s_barrier
	s_add_i32 s27, 0, 0x18000
	ds_read_b128 v[64:67], v217 offset:32768
	ds_read_b128 v[68:71], v217 offset:33792
	ds_read_b128 v[72:75], v217 offset:34816
	ds_read_b128 v[76:79], v217 offset:35840
	s_add_u32 s56, vcc_lo, 0x40000
	s_addc_u32 s57, vcc_hi, 0
	s_mov_b32 m0, s98
	ds_read_b128 v[104:107], v220 offset:32768
	ds_read_b128 v[108:111], v220 offset:33792
	ds_read_b128 v[132:135], v220 offset:34816
	ds_read_b128 v[188:191], v220 offset:35840
	ds_read_b128 v[192:195], v220 offset:36864
	ds_read_b128 v[196:199], v220 offset:37888
	ds_read_b128 v[200:203], v220 offset:38912
	ds_read_b128 v[204:207], v220 offset:39936
	global_load_lds_dwordx4 v144, s[56:57]
	s_mov_b32 m0, s29
	s_nop 0
	global_load_lds_dwordx4 v162, s[56:57]
	s_waitcnt lgkmcnt(0)
	s_barrier
	v_mfma_f32_16x16x32_bf16 v[136:139], v[64:67], v[104:107], v[146:149]
	v_mfma_f32_16x16x32_bf16 v[146:149], v[68:71], v[108:111], v[136:139]
	v_mfma_f32_16x16x32_bf16 v[136:139], v[64:67], v[132:135], v[158:161]
	v_mfma_f32_16x16x32_bf16 v[158:161], v[68:71], v[188:191], v[136:139]
	v_mfma_f32_16x16x32_bf16 v[136:139], v[64:67], v[192:195], v[154:157]
	v_mfma_f32_16x16x32_bf16 v[116:119], v[72:75], v[104:107], v[116:119]
	v_mfma_f32_16x16x32_bf16 v[124:127], v[72:75], v[132:135], v[124:127]
	v_mfma_f32_16x16x32_bf16 v[154:157], v[68:71], v[196:199], v[136:139]
	v_mfma_f32_16x16x32_bf16 v[112:115], v[72:75], v[192:195], v[112:115]
	v_mfma_f32_16x16x32_bf16 v[136:139], v[64:67], v[200:203], v[150:153]
	v_mfma_f32_16x16x32_bf16 v[120:123], v[72:75], v[200:203], v[120:123]
	v_mfma_f32_16x16x32_bf16 v[116:119], v[76:79], v[108:111], v[116:119]
	v_mfma_f32_16x16x32_bf16 v[124:127], v[76:79], v[188:191], v[124:127]
	v_mfma_f32_16x16x32_bf16 v[112:115], v[76:79], v[196:199], v[112:115]
	v_mfma_f32_16x16x32_bf16 v[150:153], v[68:71], v[204:207], v[136:139]
	v_mfma_f32_16x16x32_bf16 v[120:123], v[76:79], v[204:207], v[120:123]
	s_barrier
	s_nop 0
	s_add_i32 s58, 0, 0x1c000
	s_add_i32 s27, s27, s74
	ds_read_b128 v[222:225], v217 offset:49152
	ds_read_b128 v[228:231], v217 offset:50176
	ds_read_b128 v[232:235], v217 offset:51200
	ds_read_b128 v[236:239], v217 offset:52224
	s_add_u32 s56, s82, s18
	s_addc_u32 s57, s83, s19
	s_mov_b32 m0, s27
	s_nop 0
	global_load_lds_dwordx4 v144, s[56:57]
	s_add_u32 s56, s82, s18
	s_addc_u32 s57, s83, s19
	s_add_i32 m0, s27, 0x2000
	s_nop 0
	global_load_lds_dwordx4 v162, s[56:57]
	s_waitcnt lgkmcnt(0)
	s_barrier
	v_mfma_f32_16x16x32_bf16 v[136:139], v[222:225], v[104:107], v[140:143]
	v_mfma_f32_16x16x32_bf16 v[80:83], v[232:235], v[104:107], v[80:83]
	v_mfma_f32_16x16x32_bf16 v[140:143], v[228:231], v[108:111], v[136:139]
	v_mfma_f32_16x16x32_bf16 v[108:111], v[236:239], v[108:111], v[80:83]
	v_mfma_f32_16x16x32_bf16 v[80:83], v[222:225], v[132:135], v[84:87]
	v_mfma_f32_16x16x32_bf16 v[136:139], v[228:231], v[188:191], v[80:83]
	v_mfma_f32_16x16x32_bf16 v[80:83], v[232:235], v[132:135], v[88:91]
	v_mfma_f32_16x16x32_bf16 v[104:107], v[236:239], v[188:191], v[80:83]
	v_mfma_f32_16x16x32_bf16 v[80:83], v[222:225], v[192:195], v[92:95]
	v_mfma_f32_16x16x32_bf16 v[132:135], v[228:231], v[196:199], v[80:83]
	v_mfma_f32_16x16x32_bf16 v[80:83], v[232:235], v[192:195], v[100:103]
	v_mfma_f32_16x16x32_bf16 v[100:103], v[236:239], v[196:199], v[80:83]
	v_mfma_f32_16x16x32_bf16 v[80:83], v[222:225], v[200:203], v[128:131]
	v_mfma_f32_16x16x32_bf16 v[128:131], v[228:231], v[204:207], v[80:83]
	v_mfma_f32_16x16x32_bf16 v[80:83], v[232:235], v[200:203], v[96:99]
	v_mfma_f32_16x16x32_bf16 v[96:99], v[236:239], v[204:207], v[80:83]
	s_barrier
	s_nop 0
	s_mov_b32 m0, s31
	s_add_u32 s56, vcc_lo, s18
	s_addc_u32 s57, vcc_hi, s19
	s_nop 2
	ds_read_b128 v[80:83], v220 offset:49152
	ds_read_b128 v[84:87], v220 offset:50176
	ds_read_b128 v[88:91], v220 offset:51200
	ds_read_b128 v[92:95], v220 offset:52224
	ds_read_b128 v[188:191], v220 offset:53248
	ds_read_b128 v[192:195], v220 offset:54272
	ds_read_b128 v[196:199], v220 offset:55296
	ds_read_b128 v[200:203], v220 offset:56320
	global_load_lds_dwordx4 v144, s[56:57]
	s_add_u32 s56, vcc_lo, s18
	s_addc_u32 s57, vcc_hi, s19
	s_mov_b32 m0, s34
	s_nop 0
	global_load_lds_dwordx4 v162, s[56:57]
	s_add_u32 s56, s82, 0x40080
	s_addc_u32 s57, s83, 0
	s_add_i32 s27, s58, s74
	s_mov_b32 m0, s27
	s_nop 0
	global_load_lds_dwordx4 v144, s[56:57]
	s_add_i32 m0, s27, 0x2000
	s_nop 0
	global_load_lds_dwordx4 v162, s[56:57]
	s_waitcnt lgkmcnt(0)
	s_waitcnt vmcnt(6)
	s_barrier
	v_mfma_f32_16x16x32_bf16 v[48:51], v[64:67], v[80:83], v[48:51]
	v_mfma_f32_16x16x32_bf16 v[20:23], v[72:75], v[80:83], v[20:23]
	v_mfma_f32_16x16x32_bf16 v[60:63], v[64:67], v[88:91], v[60:63]
	v_mfma_f32_16x16x32_bf16 v[28:31], v[72:75], v[88:91], v[28:31]
	v_mfma_f32_16x16x32_bf16 v[56:59], v[64:67], v[188:191], v[56:59]
	v_mfma_f32_16x16x32_bf16 v[16:19], v[72:75], v[188:191], v[16:19]
	v_mfma_f32_16x16x32_bf16 v[52:55], v[64:67], v[196:199], v[52:55]
	v_mfma_f32_16x16x32_bf16 v[24:27], v[72:75], v[196:199], v[24:27]
	v_mfma_f32_16x16x32_bf16 v[48:51], v[68:71], v[84:87], v[48:51]
	v_mfma_f32_16x16x32_bf16 v[20:23], v[76:79], v[84:87], v[20:23]
	v_mfma_f32_16x16x32_bf16 v[60:63], v[68:71], v[92:95], v[60:63]
	v_mfma_f32_16x16x32_bf16 v[28:31], v[76:79], v[92:95], v[28:31]
	v_mfma_f32_16x16x32_bf16 v[56:59], v[68:71], v[192:195], v[56:59]
	v_mfma_f32_16x16x32_bf16 v[16:19], v[76:79], v[192:195], v[16:19]
	v_mfma_f32_16x16x32_bf16 v[52:55], v[68:71], v[200:203], v[52:55]
	v_mfma_f32_16x16x32_bf16 v[24:27], v[76:79], v[200:203], v[24:27]
	v_mfma_f32_16x16x32_bf16 v[44:47], v[222:225], v[80:83], v[44:47]
	v_mfma_f32_16x16x32_bf16 v[12:15], v[232:235], v[80:83], v[12:15]
	v_mfma_f32_16x16x32_bf16 v[40:43], v[222:225], v[88:91], v[40:43]
	v_mfma_f32_16x16x32_bf16 v[8:11], v[232:235], v[88:91], v[8:11]
	v_mfma_f32_16x16x32_bf16 v[36:39], v[222:225], v[188:191], v[36:39]
	v_mfma_f32_16x16x32_bf16 v[4:7], v[232:235], v[188:191], v[4:7]
	v_mfma_f32_16x16x32_bf16 v[32:35], v[222:225], v[196:199], v[32:35]
	v_mfma_f32_16x16x32_bf16 v[0:3], v[232:235], v[196:199], v[0:3]
	v_mfma_f32_16x16x32_bf16 v[44:47], v[228:231], v[84:87], v[44:47]
	v_mfma_f32_16x16x32_bf16 v[12:15], v[236:239], v[84:87], v[12:15]
	v_mfma_f32_16x16x32_bf16 v[40:43], v[228:231], v[92:95], v[40:43]
	v_mfma_f32_16x16x32_bf16 v[8:11], v[236:239], v[92:95], v[8:11]
	v_mfma_f32_16x16x32_bf16 v[36:39], v[228:231], v[192:195], v[36:39]
	v_mfma_f32_16x16x32_bf16 v[4:7], v[236:239], v[192:195], v[4:7]
	v_mfma_f32_16x16x32_bf16 v[32:35], v[228:231], v[200:203], v[32:35]
	v_mfma_f32_16x16x32_bf16 v[0:3], v[236:239], v[200:203], v[0:3]
	s_barrier
	s_add_i32 s37, s37, 2
	s_add_u32 s86, s86, 0x100
	s_addc_u32 s87, s87, 0
	s_add_u32 s33, s33, 0x100
	s_addc_u32 s36, s36, 0
	s_cmp_gt_u32 s37, 13
.LBB0_125:
	s_nop 0
	s_add_u32 s27, s86, 0xfffc0080
	s_addc_u32 s56, s87, -1
	s_add_i32 s57, 0, 0x10000
	ds_read_b128 v[64:67], v217
	ds_read_b128 v[68:71], v217 offset:1024
	ds_read_b128 v[72:75], v217 offset:2048
	ds_read_b128 v[76:79], v217 offset:3072
	s_cmp_eq_u32 s37, 12
	s_cselect_b32 vcc_hi, s1, s56
	s_cselect_b32 vcc_lo, s10, s27
	s_cselect_b32 s83, s11, s36
	s_cselect_b32 s82, s25, s33
	s_add_i32 m0, s75, 0xc000
	ds_read_b128 v[80:83], v220
	ds_read_b128 v[84:87], v220 offset:1024
	ds_read_b128 v[88:91], v220 offset:2048
	ds_read_b128 v[92:95], v220 offset:3072
	ds_read_b128 v[188:191], v220 offset:4096
	ds_read_b128 v[192:195], v220 offset:5120
	ds_read_b128 v[196:199], v220 offset:6144
	ds_read_b128 v[200:203], v220 offset:7168
	global_load_lds_dwordx4 v164, s[86:87]
	s_add_i32 m0, s75, 0xe000
	s_nop 0
	global_load_lds_dwordx4 v166, s[86:87]
	s_waitcnt lgkmcnt(0)
	s_barrier
	v_mfma_f32_16x16x32_bf16 v[146:149], v[64:67], v[80:83], v[146:149]
	v_mfma_f32_16x16x32_bf16 v[116:119], v[72:75], v[80:83], v[116:119]
	v_mfma_f32_16x16x32_bf16 v[158:161], v[64:67], v[88:91], v[158:161]
	v_mfma_f32_16x16x32_bf16 v[124:127], v[72:75], v[88:91], v[124:127]
	v_mfma_f32_16x16x32_bf16 v[154:157], v[64:67], v[188:191], v[154:157]
	v_mfma_f32_16x16x32_bf16 v[112:115], v[72:75], v[188:191], v[112:115]
	v_mfma_f32_16x16x32_bf16 v[150:153], v[64:67], v[196:199], v[150:153]
	v_mfma_f32_16x16x32_bf16 v[120:123], v[72:75], v[196:199], v[120:123]
	v_mfma_f32_16x16x32_bf16 v[146:149], v[68:71], v[84:87], v[146:149]
	v_mfma_f32_16x16x32_bf16 v[116:119], v[76:79], v[84:87], v[116:119]
	v_mfma_f32_16x16x32_bf16 v[158:161], v[68:71], v[92:95], v[158:161]
	v_mfma_f32_16x16x32_bf16 v[124:127], v[76:79], v[92:95], v[124:127]
	v_mfma_f32_16x16x32_bf16 v[154:157], v[68:71], v[192:195], v[154:157]
	v_mfma_f32_16x16x32_bf16 v[112:115], v[76:79], v[192:195], v[112:115]
	v_mfma_f32_16x16x32_bf16 v[150:153], v[68:71], v[200:203], v[150:153]
	v_mfma_f32_16x16x32_bf16 v[120:123], v[76:79], v[200:203], v[120:123]
	s_barrier
	s_add_i32 s27, 0, 0x14000
	s_add_i32 s56, s57, s74
	ds_read_b128 v[204:207], v217 offset:16384
	ds_read_b128 v[222:225], v217 offset:17408
	ds_read_b128 v[228:231], v217 offset:18432
	ds_read_b128 v[232:235], v217 offset:19456
	s_mov_b32 m0, s56
	global_load_lds_dwordx4 v144, s[82:83]
	s_add_i32 m0, s56, 0x2000
	s_nop 0
	global_load_lds_dwordx4 v162, s[82:83]
	s_waitcnt lgkmcnt(0)
	s_barrier
	v_mfma_f32_16x16x32_bf16 v[140:143], v[204:207], v[80:83], v[140:143]
	v_mfma_f32_16x16x32_bf16 v[80:83], v[228:231], v[80:83], v[108:111]
	v_mfma_f32_16x16x32_bf16 v[140:143], v[222:225], v[84:87], v[140:143]
	v_mfma_f32_16x16x32_bf16 v[80:83], v[232:235], v[84:87], v[80:83]
	v_mfma_f32_16x16x32_bf16 v[84:87], v[204:207], v[88:91], v[136:139]
	v_mfma_f32_16x16x32_bf16 v[88:91], v[228:231], v[88:91], v[104:107]
	v_mfma_f32_16x16x32_bf16 v[100:103], v[228:231], v[188:191], v[100:103]
	v_mfma_f32_16x16x32_bf16 v[104:107], v[204:207], v[196:199], v[128:131]
	v_mfma_f32_16x16x32_bf16 v[96:99], v[228:231], v[196:199], v[96:99]
	v_mfma_f32_16x16x32_bf16 v[84:87], v[222:225], v[92:95], v[84:87]
	v_mfma_f32_16x16x32_bf16 v[88:91], v[232:235], v[92:95], v[88:91]
	v_mfma_f32_16x16x32_bf16 v[92:95], v[204:207], v[188:191], v[132:135]
	v_mfma_f32_16x16x32_bf16 v[100:103], v[232:235], v[192:195], v[100:103]
	v_mfma_f32_16x16x32_bf16 v[128:131], v[222:225], v[200:203], v[104:107]
	v_mfma_f32_16x16x32_bf16 v[96:99], v[232:235], v[200:203], v[96:99]
	v_mfma_f32_16x16x32_bf16 v[92:95], v[222:225], v[192:195], v[92:95]
	s_barrier
	s_mov_b32 m0, s75
	ds_read_b128 v[104:107], v220 offset:16384
	ds_read_b128 v[108:111], v220 offset:17408
	ds_read_b128 v[132:135], v220 offset:18432
	ds_read_b128 v[136:139], v220 offset:19456
	ds_read_b128 v[188:191], v220 offset:20480
	ds_read_b128 v[192:195], v220 offset:21504
	ds_read_b128 v[196:199], v220 offset:22528
	ds_read_b128 v[200:203], v220 offset:23552
	global_load_lds_dwordx4 v144, vcc
	s_mov_b32 m0, s85
	s_nop 0
	global_load_lds_dwordx4 v162, vcc
	s_add_u32 s56, s82, 0x40000
	s_addc_u32 s57, s83, 0
	s_add_i32 s27, s27, s74
	s_mov_b32 m0, s27
	s_nop 0
	global_load_lds_dwordx4 v144, s[56:57]
	s_add_i32 m0, s27, 0x2000
	s_nop 0
	global_load_lds_dwordx4 v162, s[56:57]
	s_waitcnt lgkmcnt(0)
	s_waitcnt vmcnt(6)
	s_barrier
	v_mfma_f32_16x16x32_bf16 v[48:51], v[64:67], v[104:107], v[48:51]
	v_mfma_f32_16x16x32_bf16 v[20:23], v[72:75], v[104:107], v[20:23]
	v_mfma_f32_16x16x32_bf16 v[60:63], v[64:67], v[132:135], v[60:63]
	v_mfma_f32_16x16x32_bf16 v[28:31], v[72:75], v[132:135], v[28:31]
	v_mfma_f32_16x16x32_bf16 v[56:59], v[64:67], v[188:191], v[56:59]
	v_mfma_f32_16x16x32_bf16 v[16:19], v[72:75], v[188:191], v[16:19]
	v_mfma_f32_16x16x32_bf16 v[52:55], v[64:67], v[196:199], v[52:55]
	v_mfma_f32_16x16x32_bf16 v[24:27], v[72:75], v[196:199], v[24:27]
	v_mfma_f32_16x16x32_bf16 v[48:51], v[68:71], v[108:111], v[48:51]
	v_mfma_f32_16x16x32_bf16 v[20:23], v[76:79], v[108:111], v[20:23]
	v_mfma_f32_16x16x32_bf16 v[60:63], v[68:71], v[136:139], v[60:63]
	v_mfma_f32_16x16x32_bf16 v[28:31], v[76:79], v[136:139], v[28:31]
	v_mfma_f32_16x16x32_bf16 v[56:59], v[68:71], v[192:195], v[56:59]
	v_mfma_f32_16x16x32_bf16 v[16:19], v[76:79], v[192:195], v[16:19]
	v_mfma_f32_16x16x32_bf16 v[52:55], v[68:71], v[200:203], v[52:55]
	v_mfma_f32_16x16x32_bf16 v[24:27], v[76:79], v[200:203], v[24:27]
	v_mfma_f32_16x16x32_bf16 v[44:47], v[204:207], v[104:107], v[44:47]
	v_mfma_f32_16x16x32_bf16 v[12:15], v[228:231], v[104:107], v[12:15]
	v_mfma_f32_16x16x32_bf16 v[40:43], v[204:207], v[132:135], v[40:43]
	v_mfma_f32_16x16x32_bf16 v[8:11], v[228:231], v[132:135], v[8:11]
	v_mfma_f32_16x16x32_bf16 v[36:39], v[204:207], v[188:191], v[36:39]
	v_mfma_f32_16x16x32_bf16 v[4:7], v[228:231], v[188:191], v[4:7]
	v_mfma_f32_16x16x32_bf16 v[32:35], v[204:207], v[196:199], v[32:35]
	v_mfma_f32_16x16x32_bf16 v[0:3], v[228:231], v[196:199], v[0:3]
	v_mfma_f32_16x16x32_bf16 v[44:47], v[222:225], v[108:111], v[44:47]
	v_mfma_f32_16x16x32_bf16 v[12:15], v[232:235], v[108:111], v[12:15]
	v_mfma_f32_16x16x32_bf16 v[40:43], v[222:225], v[136:139], v[40:43]
	v_mfma_f32_16x16x32_bf16 v[8:11], v[232:235], v[136:139], v[8:11]
	v_mfma_f32_16x16x32_bf16 v[36:39], v[222:225], v[192:195], v[36:39]
	v_mfma_f32_16x16x32_bf16 v[4:7], v[232:235], v[192:195], v[4:7]
	v_mfma_f32_16x16x32_bf16 v[32:35], v[222:225], v[200:203], v[32:35]
	v_mfma_f32_16x16x32_bf16 v[0:3], v[232:235], v[200:203], v[0:3]
	s_barrier
	s_add_i32 s27, 0, 0x18000
	ds_read_b128 v[64:67], v217 offset:32768
	ds_read_b128 v[68:71], v217 offset:33792
	ds_read_b128 v[72:75], v217 offset:34816
	ds_read_b128 v[76:79], v217 offset:35840
	s_add_u32 s56, vcc_lo, 0x40000
	s_addc_u32 s57, vcc_hi, 0
	s_mov_b32 m0, s98
	ds_read_b128 v[104:107], v220 offset:32768
	ds_read_b128 v[108:111], v220 offset:33792
	ds_read_b128 v[132:135], v220 offset:34816
	ds_read_b128 v[188:191], v220 offset:35840
	ds_read_b128 v[192:195], v220 offset:36864
	ds_read_b128 v[196:199], v220 offset:37888
	ds_read_b128 v[200:203], v220 offset:38912
	ds_read_b128 v[204:207], v220 offset:39936
	global_load_lds_dwordx4 v144, s[56:57]
	s_mov_b32 m0, s29
	s_nop 0
	global_load_lds_dwordx4 v162, s[56:57]
	s_waitcnt lgkmcnt(0)
	s_barrier
	v_mfma_f32_16x16x32_bf16 v[136:139], v[64:67], v[104:107], v[146:149]
	v_mfma_f32_16x16x32_bf16 v[146:149], v[68:71], v[108:111], v[136:139]
	v_mfma_f32_16x16x32_bf16 v[136:139], v[64:67], v[132:135], v[158:161]
	v_mfma_f32_16x16x32_bf16 v[158:161], v[68:71], v[188:191], v[136:139]
	v_mfma_f32_16x16x32_bf16 v[136:139], v[64:67], v[192:195], v[154:157]
	v_mfma_f32_16x16x32_bf16 v[116:119], v[72:75], v[104:107], v[116:119]
	v_mfma_f32_16x16x32_bf16 v[124:127], v[72:75], v[132:135], v[124:127]
	v_mfma_f32_16x16x32_bf16 v[154:157], v[68:71], v[196:199], v[136:139]
	v_mfma_f32_16x16x32_bf16 v[112:115], v[72:75], v[192:195], v[112:115]
	v_mfma_f32_16x16x32_bf16 v[136:139], v[64:67], v[200:203], v[150:153]
	v_mfma_f32_16x16x32_bf16 v[120:123], v[72:75], v[200:203], v[120:123]
	v_mfma_f32_16x16x32_bf16 v[116:119], v[76:79], v[108:111], v[116:119]
	v_mfma_f32_16x16x32_bf16 v[124:127], v[76:79], v[188:191], v[124:127]
	v_mfma_f32_16x16x32_bf16 v[112:115], v[76:79], v[196:199], v[112:115]
	v_mfma_f32_16x16x32_bf16 v[150:153], v[68:71], v[204:207], v[136:139]
	v_mfma_f32_16x16x32_bf16 v[120:123], v[76:79], v[204:207], v[120:123]
	s_barrier
	s_nop 0
	s_add_i32 s58, 0, 0x1c000
	s_add_i32 s27, s27, s74
	ds_read_b128 v[222:225], v217 offset:49152
	ds_read_b128 v[228:231], v217 offset:50176
	ds_read_b128 v[232:235], v217 offset:51200
	ds_read_b128 v[236:239], v217 offset:52224
	s_add_u32 s56, s82, s18
	s_addc_u32 s57, s83, s19
	s_mov_b32 m0, s27
	s_nop 0
	global_load_lds_dwordx4 v144, s[56:57]
	s_add_u32 s56, s82, s18
	s_addc_u32 s57, s83, s19
	s_add_i32 m0, s27, 0x2000
	s_nop 0
	global_load_lds_dwordx4 v162, s[56:57]
	s_waitcnt lgkmcnt(0)
	s_barrier
	v_mfma_f32_16x16x32_bf16 v[136:139], v[222:225], v[104:107], v[140:143]
	v_mfma_f32_16x16x32_bf16 v[80:83], v[232:235], v[104:107], v[80:83]
	v_mfma_f32_16x16x32_bf16 v[140:143], v[228:231], v[108:111], v[136:139]
	v_mfma_f32_16x16x32_bf16 v[108:111], v[236:239], v[108:111], v[80:83]
	v_mfma_f32_16x16x32_bf16 v[80:83], v[222:225], v[132:135], v[84:87]
	v_mfma_f32_16x16x32_bf16 v[136:139], v[228:231], v[188:191], v[80:83]
	v_mfma_f32_16x16x32_bf16 v[80:83], v[232:235], v[132:135], v[88:91]
	v_mfma_f32_16x16x32_bf16 v[104:107], v[236:239], v[188:191], v[80:83]
	v_mfma_f32_16x16x32_bf16 v[80:83], v[222:225], v[192:195], v[92:95]
	v_mfma_f32_16x16x32_bf16 v[132:135], v[228:231], v[196:199], v[80:83]
	v_mfma_f32_16x16x32_bf16 v[80:83], v[232:235], v[192:195], v[100:103]
	v_mfma_f32_16x16x32_bf16 v[100:103], v[236:239], v[196:199], v[80:83]
	v_mfma_f32_16x16x32_bf16 v[80:83], v[222:225], v[200:203], v[128:131]
	v_mfma_f32_16x16x32_bf16 v[128:131], v[228:231], v[204:207], v[80:83]
	v_mfma_f32_16x16x32_bf16 v[80:83], v[232:235], v[200:203], v[96:99]
	v_mfma_f32_16x16x32_bf16 v[96:99], v[236:239], v[204:207], v[80:83]
	s_barrier
	s_nop 0
	s_mov_b32 m0, s31
	s_add_u32 s56, vcc_lo, s18
	s_addc_u32 s57, vcc_hi, s19
	s_nop 2
	ds_read_b128 v[80:83], v220 offset:49152
	ds_read_b128 v[84:87], v220 offset:50176
	ds_read_b128 v[88:91], v220 offset:51200
	ds_read_b128 v[92:95], v220 offset:52224
	ds_read_b128 v[188:191], v220 offset:53248
	ds_read_b128 v[192:195], v220 offset:54272
	ds_read_b128 v[196:199], v220 offset:55296
	ds_read_b128 v[200:203], v220 offset:56320
	global_load_lds_dwordx4 v144, s[56:57]
	s_add_u32 s56, vcc_lo, s18
	s_addc_u32 s57, vcc_hi, s19
	s_mov_b32 m0, s34
	s_nop 0
	global_load_lds_dwordx4 v162, s[56:57]
	s_add_u32 s56, s82, 0x40080
	s_addc_u32 s57, s83, 0
	s_add_i32 s27, s58, s74
	s_mov_b32 m0, s27
	s_nop 0
	global_load_lds_dwordx4 v144, s[56:57]
	s_add_i32 m0, s27, 0x2000
	s_nop 0
	global_load_lds_dwordx4 v162, s[56:57]
	s_waitcnt lgkmcnt(0)
	s_waitcnt vmcnt(6)
	s_barrier
	v_mfma_f32_16x16x32_bf16 v[48:51], v[64:67], v[80:83], v[48:51]
	v_mfma_f32_16x16x32_bf16 v[20:23], v[72:75], v[80:83], v[20:23]
	v_mfma_f32_16x16x32_bf16 v[60:63], v[64:67], v[88:91], v[60:63]
	v_mfma_f32_16x16x32_bf16 v[28:31], v[72:75], v[88:91], v[28:31]
	v_mfma_f32_16x16x32_bf16 v[56:59], v[64:67], v[188:191], v[56:59]
	v_mfma_f32_16x16x32_bf16 v[16:19], v[72:75], v[188:191], v[16:19]
	v_mfma_f32_16x16x32_bf16 v[52:55], v[64:67], v[196:199], v[52:55]
	v_mfma_f32_16x16x32_bf16 v[24:27], v[72:75], v[196:199], v[24:27]
	v_mfma_f32_16x16x32_bf16 v[48:51], v[68:71], v[84:87], v[48:51]
	v_mfma_f32_16x16x32_bf16 v[20:23], v[76:79], v[84:87], v[20:23]
	v_mfma_f32_16x16x32_bf16 v[60:63], v[68:71], v[92:95], v[60:63]
	v_mfma_f32_16x16x32_bf16 v[28:31], v[76:79], v[92:95], v[28:31]
	v_mfma_f32_16x16x32_bf16 v[56:59], v[68:71], v[192:195], v[56:59]
	v_mfma_f32_16x16x32_bf16 v[16:19], v[76:79], v[192:195], v[16:19]
	v_mfma_f32_16x16x32_bf16 v[52:55], v[68:71], v[200:203], v[52:55]
	v_mfma_f32_16x16x32_bf16 v[24:27], v[76:79], v[200:203], v[24:27]
	v_mfma_f32_16x16x32_bf16 v[44:47], v[222:225], v[80:83], v[44:47]
	v_mfma_f32_16x16x32_bf16 v[12:15], v[232:235], v[80:83], v[12:15]
	v_mfma_f32_16x16x32_bf16 v[40:43], v[222:225], v[88:91], v[40:43]
	v_mfma_f32_16x16x32_bf16 v[8:11], v[232:235], v[88:91], v[8:11]
	v_mfma_f32_16x16x32_bf16 v[36:39], v[222:225], v[188:191], v[36:39]
	v_mfma_f32_16x16x32_bf16 v[4:7], v[232:235], v[188:191], v[4:7]
	v_mfma_f32_16x16x32_bf16 v[32:35], v[222:225], v[196:199], v[32:35]
	v_mfma_f32_16x16x32_bf16 v[0:3], v[232:235], v[196:199], v[0:3]
	v_mfma_f32_16x16x32_bf16 v[44:47], v[228:231], v[84:87], v[44:47]
	v_mfma_f32_16x16x32_bf16 v[12:15], v[236:239], v[84:87], v[12:15]
	v_mfma_f32_16x16x32_bf16 v[40:43], v[228:231], v[92:95], v[40:43]
	v_mfma_f32_16x16x32_bf16 v[8:11], v[236:239], v[92:95], v[8:11]
	v_mfma_f32_16x16x32_bf16 v[36:39], v[228:231], v[192:195], v[36:39]
	v_mfma_f32_16x16x32_bf16 v[4:7], v[236:239], v[192:195], v[4:7]
	v_mfma_f32_16x16x32_bf16 v[32:35], v[228:231], v[200:203], v[32:35]
	v_mfma_f32_16x16x32_bf16 v[0:3], v[236:239], v[200:203], v[0:3]
	s_barrier
	s_add_i32 s37, s37, 2
	s_add_u32 s86, s86, 0x100
	s_addc_u32 s87, s87, 0
	s_add_u32 s33, s33, 0x100
	s_addc_u32 s36, s36, 0
	s_cmp_gt_u32 s37, 13
	s_cbranch_scc0 .LBB0_125
	s_lshl_b32 s1, s84, 8
	v_readlane_b32 s10, v254, 61
	s_add_i32 s1, s1, s10
	v_or_b32_e32 v198, s1, v216
	s_add_i32 s10, s1, 0x80
	v_or_b32_e32 v168, s10, v216
	v_lshl_or_b32 v188, s0, 7, v219
	v_lshlrev_b32_e32 v190, 2, v188
	v_lshlrev_b32_e32 v189, 1, v188
	s_ashr_i32 s11, s1, 5
	s_movk_i32 s10, 0xb00
	s_movk_i32 s20, 0x1600
	s_mov_b32 s101, 0xbfb8aa3b
	s_cmp_eq_u32 s84, s100
	s_cbranch_scc1 .Ldepi_w
	v_ashrrev_i32_e32 v199, 31, v198
	v_ashrrev_i32_e32 v169, 31, v168
	v_lshl_add_u64 v[170:171], v[198:199], 3, s[48:49]
	v_lshl_add_u64 v[172:173], v[168:169], 3, s[48:49]
	global_load_dwordx2 v[176:177], v[170:171], off
	global_load_dwordx2 v[202:203], v[170:171], off offset:128
	global_load_dwordx2 v[206:207], v[170:171], off offset:256
	global_load_dwordx2 v[222:223], v[170:171], off offset:384
	global_load_dwordx2 v[200:201], v[172:173], off
	global_load_dwordx2 v[196:197], v[172:173], off offset:128
	global_load_dwordx2 v[194:195], v[172:173], off offset:256
	global_load_dwordx2 v[192:193], v[172:173], off offset:384

.LBB0_195:
	s_add_u32 s42, s78, 0x80
	s_addc_u32 s43, s79, 0
	s_add_u32 s33, s44, 0x100
	s_addc_u32 s37, s45, 0
	s_mov_b32 s27, 0
	s_waitcnt lgkmcnt(0)
	s_add_i32 s56, s27, 2
	s_add_u32 s44, s42, 0x80
	s_addc_u32 s45, s43, 0
	s_add_i32 s57, 0, 0x10000
	ds_read_b128 v[128:131], v207
	ds_read_b128 v[132:135], v207 offset:1024
	ds_read_b128 v[136:139], v207 offset:2048
	ds_read_b128 v[140:143], v207 offset:3072
	s_cmp_eq_u32 s82, s27
	s_cselect_b32 s45, s77, s45
	s_cselect_b32 s44, s76, s44
	s_cselect_b32 s79, s1, s37
	s_cselect_b32 s78, s0, s33
	v_lshl_add_u64 v[176:177], s[42:43], 0, v[190:191]
	s_add_i32 m0, s85, 0xc000
	ds_read_b128 v[146:149], v217
	ds_read_b128 v[150:153], v217 offset:1024
	ds_read_b128 v[154:157], v217 offset:2048
	ds_read_b128 v[158:161], v217 offset:3072
	ds_read_b128 v[162:165], v217 offset:4096
	ds_read_b128 v[166:169], v217 offset:5120
	ds_read_b128 v[194:197], v217 offset:6144
	ds_read_b128 v[198:201], v217 offset:7168
	global_load_lds_dwordx4 v[176:177], off
	v_lshl_add_u64 v[176:177], s[42:43], 0, v[192:193]
	s_add_i32 m0, s85, 0xe000
	s_nop 0
	global_load_lds_dwordx4 v[176:177], off
	s_waitcnt lgkmcnt(0)
	s_barrier
	v_mfma_f32_16x16x32_bf16 v[124:127], v[128:131], v[146:149], 0
	v_mfma_f32_16x16x32_bf16 v[120:123], v[136:139], v[146:149], 0
	v_mfma_f32_16x16x32_bf16 v[108:111], v[128:131], v[154:157], 0
	v_mfma_f32_16x16x32_bf16 v[104:107], v[136:139], v[154:157], 0
	v_mfma_f32_16x16x32_bf16 v[92:95], v[128:131], v[162:165], 0
	v_mfma_f32_16x16x32_bf16 v[88:91], v[136:139], v[162:165], 0
	v_mfma_f32_16x16x32_bf16 v[76:79], v[128:131], v[194:197], 0
	v_mfma_f32_16x16x32_bf16 v[72:75], v[136:139], v[194:197], 0
	v_mfma_f32_16x16x32_bf16 v[124:127], v[132:135], v[150:153], v[124:127]
	v_mfma_f32_16x16x32_bf16 v[120:123], v[140:143], v[150:153], v[120:123]
	v_mfma_f32_16x16x32_bf16 v[108:111], v[132:135], v[158:161], v[108:111]
	v_mfma_f32_16x16x32_bf16 v[104:107], v[140:143], v[158:161], v[104:107]
	v_mfma_f32_16x16x32_bf16 v[92:95], v[132:135], v[166:169], v[92:95]
	v_mfma_f32_16x16x32_bf16 v[88:91], v[140:143], v[166:169], v[88:91]
	v_mfma_f32_16x16x32_bf16 v[76:79], v[132:135], v[198:201], v[76:79]
	v_mfma_f32_16x16x32_bf16 v[72:75], v[140:143], v[198:201], v[72:75]
	s_barrier
	s_add_i32 s27, 0, 0x14000
	s_add_i32 s57, s57, s84
	ds_read_b128 v[202:205], v207 offset:16384
	ds_read_b128 v[218:221], v207 offset:17408
	ds_read_b128 v[222:225], v207 offset:18432
	ds_read_b128 v[228:231], v207 offset:19456
	v_lshl_add_u64 v[176:177], s[78:79], 0, v[144:145]
	s_mov_b32 m0, s57
	v_lshl_add_u64 v[232:233], s[78:79], 0, v[188:189]
	global_load_lds_dwordx4 v[176:177], off
	s_add_i32 m0, s57, 0x2000
	s_nop 0
	global_load_lds_dwordx4 v[232:233], off
	s_waitcnt lgkmcnt(0)
	s_barrier
	v_mfma_f32_16x16x32_bf16 v[116:119], v[202:205], v[146:149], 0
	v_mfma_f32_16x16x32_bf16 v[112:115], v[222:225], v[146:149], 0
	v_mfma_f32_16x16x32_bf16 v[100:103], v[202:205], v[154:157], 0
	v_mfma_f32_16x16x32_bf16 v[96:99], v[222:225], v[154:157], 0
	v_mfma_f32_16x16x32_bf16 v[84:87], v[202:205], v[162:165], 0
	v_mfma_f32_16x16x32_bf16 v[80:83], v[222:225], v[162:165], 0
	v_mfma_f32_16x16x32_bf16 v[68:71], v[202:205], v[194:197], 0
	v_mfma_f32_16x16x32_bf16 v[64:67], v[222:225], v[194:197], 0
	v_mfma_f32_16x16x32_bf16 v[116:119], v[218:221], v[150:153], v[116:119]
	v_mfma_f32_16x16x32_bf16 v[112:115], v[228:231], v[150:153], v[112:115]
	v_mfma_f32_16x16x32_bf16 v[100:103], v[218:221], v[158:161], v[100:103]
	v_mfma_f32_16x16x32_bf16 v[96:99], v[228:231], v[158:161], v[96:99]
	v_mfma_f32_16x16x32_bf16 v[84:87], v[218:221], v[166:169], v[84:87]
	v_mfma_f32_16x16x32_bf16 v[80:83], v[228:231], v[166:169], v[80:83]
	v_mfma_f32_16x16x32_bf16 v[68:71], v[218:221], v[198:201], v[68:71]
	v_mfma_f32_16x16x32_bf16 v[64:67], v[228:231], v[198:201], v[64:67]
	s_barrier
	s_mov_b32 m0, s85
	v_lshl_add_u64 v[234:235], s[44:45], 0, v[144:145]
	ds_read_b128 v[146:149], v217 offset:16384
	ds_read_b128 v[150:153], v217 offset:17408
	ds_read_b128 v[154:157], v217 offset:18432
	ds_read_b128 v[158:161], v217 offset:19456
	ds_read_b128 v[162:165], v217 offset:20480
	ds_read_b128 v[166:169], v217 offset:21504
	ds_read_b128 v[194:197], v217 offset:22528
	ds_read_b128 v[198:201], v217 offset:23552
	global_load_lds_dwordx4 v[234:235], off
	v_lshl_add_u64 v[236:237], s[44:45], 0, v[188:189]
	s_mov_b32 m0, s86
	s_nop 0
	global_load_lds_dwordx4 v[236:237], off
	s_add_u32 s58, s78, s98
	s_addc_u32 s59, s79, 0
	s_add_i32 s27, s27, s84
	v_lshl_add_u64 v[238:239], s[58:59], 0, v[144:145]
	s_mov_b32 m0, s27
	v_lshl_add_u64 v[240:241], s[58:59], 0, v[188:189]
	global_load_lds_dwordx4 v[238:239], off
	s_add_i32 m0, s27, 0x2000
	s_nop 0
	global_load_lds_dwordx4 v[240:241], off
	s_waitcnt lgkmcnt(0)
	s_waitcnt vmcnt(6)
	s_barrier
	v_mfma_f32_16x16x32_bf16 v[60:63], v[128:131], v[146:149], 0
	v_mfma_f32_16x16x32_bf16 v[56:59], v[136:139], v[146:149], 0
	v_mfma_f32_16x16x32_bf16 v[44:47], v[128:131], v[154:157], 0
	v_mfma_f32_16x16x32_bf16 v[40:43], v[136:139], v[154:157], 0
	v_mfma_f32_16x16x32_bf16 v[28:31], v[128:131], v[162:165], 0
	v_mfma_f32_16x16x32_bf16 v[24:27], v[136:139], v[162:165], 0
	v_mfma_f32_16x16x32_bf16 v[12:15], v[128:131], v[194:197], 0
	v_mfma_f32_16x16x32_bf16 v[8:11], v[136:139], v[194:197], 0
	v_mfma_f32_16x16x32_bf16 v[60:63], v[132:135], v[150:153], v[60:63]
	v_mfma_f32_16x16x32_bf16 v[56:59], v[140:143], v[150:153], v[56:59]
	v_mfma_f32_16x16x32_bf16 v[44:47], v[132:135], v[158:161], v[44:47]
	v_mfma_f32_16x16x32_bf16 v[40:43], v[140:143], v[158:161], v[40:43]
	v_mfma_f32_16x16x32_bf16 v[28:31], v[132:135], v[166:169], v[28:31]
	v_mfma_f32_16x16x32_bf16 v[24:27], v[140:143], v[166:169], v[24:27]
	v_mfma_f32_16x16x32_bf16 v[12:15], v[132:135], v[198:201], v[12:15]
	v_mfma_f32_16x16x32_bf16 v[8:11], v[140:143], v[198:201], v[8:11]
	v_mfma_f32_16x16x32_bf16 v[52:55], v[202:205], v[146:149], 0
	v_mfma_f32_16x16x32_bf16 v[48:51], v[222:225], v[146:149], 0
	v_mfma_f32_16x16x32_bf16 v[36:39], v[202:205], v[154:157], 0
	v_mfma_f32_16x16x32_bf16 v[32:35], v[222:225], v[154:157], 0
	v_mfma_f32_16x16x32_bf16 v[20:23], v[202:205], v[162:165], 0
	v_mfma_f32_16x16x32_bf16 v[16:19], v[222:225], v[162:165], 0
	v_mfma_f32_16x16x32_bf16 v[4:7], v[202:205], v[194:197], 0
	v_mfma_f32_16x16x32_bf16 v[0:3], v[222:225], v[194:197], 0
	v_mfma_f32_16x16x32_bf16 v[52:55], v[218:221], v[150:153], v[52:55]
	v_mfma_f32_16x16x32_bf16 v[48:51], v[228:231], v[150:153], v[48:51]
	v_mfma_f32_16x16x32_bf16 v[36:39], v[218:221], v[158:161], v[36:39]
	v_mfma_f32_16x16x32_bf16 v[32:35], v[228:231], v[158:161], v[32:35]
	v_mfma_f32_16x16x32_bf16 v[20:23], v[218:221], v[166:169], v[20:23]
	v_mfma_f32_16x16x32_bf16 v[16:19], v[228:231], v[166:169], v[16:19]
	v_mfma_f32_16x16x32_bf16 v[4:7], v[218:221], v[198:201], v[4:7]
	v_mfma_f32_16x16x32_bf16 v[0:3], v[228:231], v[198:201], v[0:3]
	s_barrier
	s_nop 0
	s_add_i32 s27, 0, 0x18000
	ds_read_b128 v[128:131], v207 offset:32768
	ds_read_b128 v[132:135], v207 offset:33792
	ds_read_b128 v[136:139], v207 offset:34816
	ds_read_b128 v[140:143], v207 offset:35840
	s_add_u32 s44, s44, s98
	s_addc_u32 s45, s45, 0
	s_mov_b32 m0, s87
	ds_read_b128 v[146:149], v217 offset:32768
	ds_read_b128 v[150:153], v217 offset:33792
	ds_read_b128 v[154:157], v217 offset:34816
	ds_read_b128 v[158:161], v217 offset:35840
	ds_read_b128 v[162:165], v217 offset:36864
	ds_read_b128 v[166:169], v217 offset:37888
	ds_read_b128 v[194:197], v217 offset:38912
	ds_read_b128 v[198:201], v217 offset:39936
	global_load_lds_dwordx4 v144, s[44:45]
	s_mov_b32 m0, s80
	s_nop 0
	global_load_lds_dwordx4 v188, s[44:45]
	s_waitcnt lgkmcnt(0)
	s_barrier
	v_mfma_f32_16x16x32_bf16 v[124:127], v[128:131], v[146:149], v[124:127]
	v_mfma_f32_16x16x32_bf16 v[120:123], v[136:139], v[146:149], v[120:123]
	v_mfma_f32_16x16x32_bf16 v[108:111], v[128:131], v[154:157], v[108:111]
	v_mfma_f32_16x16x32_bf16 v[104:107], v[136:139], v[154:157], v[104:107]
	v_mfma_f32_16x16x32_bf16 v[92:95], v[128:131], v[162:165], v[92:95]
	v_mfma_f32_16x16x32_bf16 v[88:91], v[136:139], v[162:165], v[88:91]
	v_mfma_f32_16x16x32_bf16 v[76:79], v[128:131], v[194:197], v[76:79]
	v_mfma_f32_16x16x32_bf16 v[72:75], v[136:139], v[194:197], v[72:75]
	v_mfma_f32_16x16x32_bf16 v[124:127], v[132:135], v[150:153], v[124:127]
	v_mfma_f32_16x16x32_bf16 v[120:123], v[140:143], v[150:153], v[120:123]
	v_mfma_f32_16x16x32_bf16 v[108:111], v[132:135], v[158:161], v[108:111]
	v_mfma_f32_16x16x32_bf16 v[104:107], v[140:143], v[158:161], v[104:107]
	v_mfma_f32_16x16x32_bf16 v[92:95], v[132:135], v[166:169], v[92:95]
	v_mfma_f32_16x16x32_bf16 v[88:91], v[140:143], v[166:169], v[88:91]
	v_mfma_f32_16x16x32_bf16 v[76:79], v[132:135], v[198:201], v[76:79]
	v_mfma_f32_16x16x32_bf16 v[72:75], v[140:143], v[198:201], v[72:75]
	s_barrier
	s_add_i32 s44, 0, 0x1c000
	s_add_i32 s27, s27, s84
	v_lshl_add_u64 v[176:177], v[176:177], 0, s[18:19]
	s_mov_b32 m0, s27
	ds_read_b128 v[202:205], v207 offset:49152
	ds_read_b128 v[218:221], v207 offset:50176
	ds_read_b128 v[222:225], v207 offset:51200
	ds_read_b128 v[228:231], v207 offset:52224
	global_load_lds_dwordx4 v[176:177], off
	v_lshl_add_u64 v[176:177], v[232:233], 0, s[18:19]
	s_add_i32 m0, s27, 0x2000
	s_nop 0
	global_load_lds_dwordx4 v[176:177], off
	s_waitcnt lgkmcnt(0)
	s_barrier
	v_mfma_f32_16x16x32_bf16 v[116:119], v[202:205], v[146:149], v[116:119]
	v_mfma_f32_16x16x32_bf16 v[112:115], v[222:225], v[146:149], v[112:115]
	v_mfma_f32_16x16x32_bf16 v[100:103], v[202:205], v[154:157], v[100:103]
	v_mfma_f32_16x16x32_bf16 v[96:99], v[222:225], v[154:157], v[96:99]
	v_mfma_f32_16x16x32_bf16 v[84:87], v[202:205], v[162:165], v[84:87]
	v_mfma_f32_16x16x32_bf16 v[80:83], v[222:225], v[162:165], v[80:83]
	v_mfma_f32_16x16x32_bf16 v[68:71], v[202:205], v[194:197], v[68:71]
	v_mfma_f32_16x16x32_bf16 v[64:67], v[222:225], v[194:197], v[64:67]
	v_mfma_f32_16x16x32_bf16 v[116:119], v[218:221], v[150:153], v[116:119]
	v_mfma_f32_16x16x32_bf16 v[112:115], v[228:231], v[150:153], v[112:115]
	v_mfma_f32_16x16x32_bf16 v[100:103], v[218:221], v[158:161], v[100:103]
	v_mfma_f32_16x16x32_bf16 v[96:99], v[228:231], v[158:161], v[96:99]
	v_mfma_f32_16x16x32_bf16 v[84:87], v[218:221], v[166:169], v[84:87]
	v_mfma_f32_16x16x32_bf16 v[80:83], v[228:231], v[166:169], v[80:83]
	v_mfma_f32_16x16x32_bf16 v[68:71], v[218:221], v[198:201], v[68:71]
	v_mfma_f32_16x16x32_bf16 v[64:67], v[228:231], v[198:201], v[64:67]
	s_barrier
	s_mov_b32 m0, s30
	v_lshl_add_u64 v[176:177], v[234:235], 0, s[18:19]
	ds_read_b128 v[146:149], v217 offset:49152
	ds_read_b128 v[150:153], v217 offset:50176
	ds_read_b128 v[154:157], v217 offset:51200
	ds_read_b128 v[158:161], v217 offset:52224
	ds_read_b128 v[162:165], v217 offset:53248
	ds_read_b128 v[166:169], v217 offset:54272
	ds_read_b128 v[194:197], v217 offset:55296
	ds_read_b128 v[198:201], v217 offset:56320
	global_load_lds_dwordx4 v[176:177], off
	v_lshl_add_u64 v[176:177], v[236:237], 0, s[18:19]
	s_mov_b32 m0, s31
	s_nop 0
	global_load_lds_dwordx4 v[176:177], off
	s_nop 0
	s_add_i32 s27, s44, s84
	v_lshl_add_u64 v[238:239], v[238:239], 0, s[18:19]
	s_mov_b32 m0, s27
	s_nop 0
	global_load_lds_dwordx4 v[238:239], off
	v_lshl_add_u64 v[240:241], v[240:241], 0, s[18:19]
	s_add_i32 m0, s27, 0x2000
	s_nop 0
	global_load_lds_dwordx4 v[240:241], off
	s_waitcnt lgkmcnt(0)
	s_waitcnt vmcnt(6)
	s_barrier
	v_mfma_f32_16x16x32_bf16 v[60:63], v[128:131], v[146:149], v[60:63]
	v_mfma_f32_16x16x32_bf16 v[56:59], v[136:139], v[146:149], v[56:59]
	v_mfma_f32_16x16x32_bf16 v[44:47], v[128:131], v[154:157], v[44:47]
	v_mfma_f32_16x16x32_bf16 v[40:43], v[136:139], v[154:157], v[40:43]
	v_mfma_f32_16x16x32_bf16 v[28:31], v[128:131], v[162:165], v[28:31]
	v_mfma_f32_16x16x32_bf16 v[24:27], v[136:139], v[162:165], v[24:27]
	v_mfma_f32_16x16x32_bf16 v[12:15], v[128:131], v[194:197], v[12:15]
	v_mfma_f32_16x16x32_bf16 v[8:11], v[136:139], v[194:197], v[8:11]
	v_mfma_f32_16x16x32_bf16 v[60:63], v[132:135], v[150:153], v[60:63]
	v_mfma_f32_16x16x32_bf16 v[56:59], v[140:143], v[150:153], v[56:59]
	v_mfma_f32_16x16x32_bf16 v[44:47], v[132:135], v[158:161], v[44:47]
	v_mfma_f32_16x16x32_bf16 v[40:43], v[140:143], v[158:161], v[40:43]
	v_mfma_f32_16x16x32_bf16 v[28:31], v[132:135], v[166:169], v[28:31]
	v_mfma_f32_16x16x32_bf16 v[24:27], v[140:143], v[166:169], v[24:27]
	v_mfma_f32_16x16x32_bf16 v[12:15], v[132:135], v[198:201], v[12:15]
	v_mfma_f32_16x16x32_bf16 v[8:11], v[140:143], v[198:201], v[8:11]
	v_mfma_f32_16x16x32_bf16 v[52:55], v[202:205], v[146:149], v[52:55]
	v_mfma_f32_16x16x32_bf16 v[48:51], v[222:225], v[146:149], v[48:51]
	v_mfma_f32_16x16x32_bf16 v[36:39], v[202:205], v[154:157], v[36:39]
	v_mfma_f32_16x16x32_bf16 v[32:35], v[222:225], v[154:157], v[32:35]
	v_mfma_f32_16x16x32_bf16 v[20:23], v[202:205], v[162:165], v[20:23]
	v_mfma_f32_16x16x32_bf16 v[16:19], v[222:225], v[162:165], v[16:19]
	v_mfma_f32_16x16x32_bf16 v[4:7], v[202:205], v[194:197], v[4:7]
	v_mfma_f32_16x16x32_bf16 v[0:3], v[222:225], v[194:197], v[0:3]
	v_mfma_f32_16x16x32_bf16 v[52:55], v[218:221], v[150:153], v[52:55]
	v_mfma_f32_16x16x32_bf16 v[48:51], v[228:231], v[150:153], v[48:51]
	v_mfma_f32_16x16x32_bf16 v[36:39], v[218:221], v[158:161], v[36:39]
	v_mfma_f32_16x16x32_bf16 v[32:35], v[228:231], v[158:161], v[32:35]
	v_mfma_f32_16x16x32_bf16 v[20:23], v[218:221], v[166:169], v[20:23]
	v_mfma_f32_16x16x32_bf16 v[16:19], v[228:231], v[166:169], v[16:19]
	v_mfma_f32_16x16x32_bf16 v[4:7], v[218:221], v[198:201], v[4:7]
	v_mfma_f32_16x16x32_bf16 v[0:3], v[228:231], v[198:201], v[0:3]
	s_barrier
	s_add_u32 s42, s42, 0x100
	s_addc_u32 s43, s43, 0
	s_add_u32 s33, s33, 0x100
	s_addc_u32 s37, s37, 0
	s_cmp_ge_u32 s56, s34
	s_mov_b32 s27, s56
.LBB0_196:
	s_add_i32 s56, s27, 2
	s_add_u32 s44, s42, 0x80
	s_addc_u32 s45, s43, 0
	s_add_i32 s57, 0, 0x10000
	ds_read_b128 v[128:131], v207
	ds_read_b128 v[132:135], v207 offset:1024
	ds_read_b128 v[136:139], v207 offset:2048
	ds_read_b128 v[140:143], v207 offset:3072
	s_cmp_eq_u32 s82, s27
	s_cselect_b32 s45, s77, s45
	s_cselect_b32 s44, s76, s44
	s_cselect_b32 s79, s1, s37
	s_cselect_b32 s78, s0, s33
	v_lshl_add_u64 v[176:177], s[42:43], 0, v[190:191]
	s_add_i32 m0, s85, 0xc000
	ds_read_b128 v[146:149], v217
	ds_read_b128 v[150:153], v217 offset:1024
	ds_read_b128 v[154:157], v217 offset:2048
	ds_read_b128 v[158:161], v217 offset:3072
	ds_read_b128 v[162:165], v217 offset:4096
	ds_read_b128 v[166:169], v217 offset:5120
	ds_read_b128 v[194:197], v217 offset:6144
	ds_read_b128 v[198:201], v217 offset:7168
	global_load_lds_dwordx4 v[176:177], off
	v_lshl_add_u64 v[176:177], s[42:43], 0, v[192:193]
	s_add_i32 m0, s85, 0xe000
	s_nop 0
	global_load_lds_dwordx4 v[176:177], off
	s_waitcnt lgkmcnt(0)
	s_barrier
	v_mfma_f32_16x16x32_bf16 v[124:127], v[128:131], v[146:149], v[124:127]
	v_mfma_f32_16x16x32_bf16 v[120:123], v[136:139], v[146:149], v[120:123]
	v_mfma_f32_16x16x32_bf16 v[108:111], v[128:131], v[154:157], v[108:111]
	v_mfma_f32_16x16x32_bf16 v[104:107], v[136:139], v[154:157], v[104:107]
	v_mfma_f32_16x16x32_bf16 v[92:95], v[128:131], v[162:165], v[92:95]
	v_mfma_f32_16x16x32_bf16 v[88:91], v[136:139], v[162:165], v[88:91]
	v_mfma_f32_16x16x32_bf16 v[76:79], v[128:131], v[194:197], v[76:79]
	v_mfma_f32_16x16x32_bf16 v[72:75], v[136:139], v[194:197], v[72:75]
	v_mfma_f32_16x16x32_bf16 v[124:127], v[132:135], v[150:153], v[124:127]
	v_mfma_f32_16x16x32_bf16 v[120:123], v[140:143], v[150:153], v[120:123]
	v_mfma_f32_16x16x32_bf16 v[108:111], v[132:135], v[158:161], v[108:111]
	v_mfma_f32_16x16x32_bf16 v[104:107], v[140:143], v[158:161], v[104:107]
	v_mfma_f32_16x16x32_bf16 v[92:95], v[132:135], v[166:169], v[92:95]
	v_mfma_f32_16x16x32_bf16 v[88:91], v[140:143], v[166:169], v[88:91]
	v_mfma_f32_16x16x32_bf16 v[76:79], v[132:135], v[198:201], v[76:79]
	v_mfma_f32_16x16x32_bf16 v[72:75], v[140:143], v[198:201], v[72:75]
	s_barrier
	s_add_i32 s27, 0, 0x14000
	s_add_i32 s57, s57, s84
	ds_read_b128 v[202:205], v207 offset:16384
	ds_read_b128 v[218:221], v207 offset:17408
	ds_read_b128 v[222:225], v207 offset:18432
	ds_read_b128 v[228:231], v207 offset:19456
	v_lshl_add_u64 v[176:177], s[78:79], 0, v[144:145]
	s_mov_b32 m0, s57
	v_lshl_add_u64 v[232:233], s[78:79], 0, v[188:189]
	global_load_lds_dwordx4 v[176:177], off
	s_add_i32 m0, s57, 0x2000
	s_nop 0
	global_load_lds_dwordx4 v[232:233], off
	s_waitcnt lgkmcnt(0)
	s_barrier
	v_mfma_f32_16x16x32_bf16 v[116:119], v[202:205], v[146:149], v[116:119]
	v_mfma_f32_16x16x32_bf16 v[112:115], v[222:225], v[146:149], v[112:115]
	v_mfma_f32_16x16x32_bf16 v[100:103], v[202:205], v[154:157], v[100:103]
	v_mfma_f32_16x16x32_bf16 v[96:99], v[222:225], v[154:157], v[96:99]
	v_mfma_f32_16x16x32_bf16 v[84:87], v[202:205], v[162:165], v[84:87]
	v_mfma_f32_16x16x32_bf16 v[80:83], v[222:225], v[162:165], v[80:83]
	v_mfma_f32_16x16x32_bf16 v[68:71], v[202:205], v[194:197], v[68:71]
	v_mfma_f32_16x16x32_bf16 v[64:67], v[222:225], v[194:197], v[64:67]
	v_mfma_f32_16x16x32_bf16 v[116:119], v[218:221], v[150:153], v[116:119]
	v_mfma_f32_16x16x32_bf16 v[112:115], v[228:231], v[150:153], v[112:115]
	v_mfma_f32_16x16x32_bf16 v[100:103], v[218:221], v[158:161], v[100:103]
	v_mfma_f32_16x16x32_bf16 v[96:99], v[228:231], v[158:161], v[96:99]
	v_mfma_f32_16x16x32_bf16 v[84:87], v[218:221], v[166:169], v[84:87]
	v_mfma_f32_16x16x32_bf16 v[80:83], v[228:231], v[166:169], v[80:83]
	v_mfma_f32_16x16x32_bf16 v[68:71], v[218:221], v[198:201], v[68:71]
	v_mfma_f32_16x16x32_bf16 v[64:67], v[228:231], v[198:201], v[64:67]
	s_barrier
	s_mov_b32 m0, s85
	v_lshl_add_u64 v[234:235], s[44:45], 0, v[144:145]
	ds_read_b128 v[146:149], v217 offset:16384
	ds_read_b128 v[150:153], v217 offset:17408
	ds_read_b128 v[154:157], v217 offset:18432
	ds_read_b128 v[158:161], v217 offset:19456
	ds_read_b128 v[162:165], v217 offset:20480
	ds_read_b128 v[166:169], v217 offset:21504
	ds_read_b128 v[194:197], v217 offset:22528
	ds_read_b128 v[198:201], v217 offset:23552
	global_load_lds_dwordx4 v[234:235], off
	v_lshl_add_u64 v[236:237], s[44:45], 0, v[188:189]
	s_mov_b32 m0, s86
	s_nop 0
	global_load_lds_dwordx4 v[236:237], off
	s_add_u32 s58, s78, s98
	s_addc_u32 s59, s79, 0
	s_add_i32 s27, s27, s84
	v_lshl_add_u64 v[238:239], s[58:59], 0, v[144:145]
	s_mov_b32 m0, s27
	v_lshl_add_u64 v[240:241], s[58:59], 0, v[188:189]
	global_load_lds_dwordx4 v[238:239], off
	s_add_i32 m0, s27, 0x2000
	s_nop 0
	global_load_lds_dwordx4 v[240:241], off
	s_waitcnt lgkmcnt(0)
	s_waitcnt vmcnt(6)
	s_barrier
	v_mfma_f32_16x16x32_bf16 v[60:63], v[128:131], v[146:149], v[60:63]
	v_mfma_f32_16x16x32_bf16 v[56:59], v[136:139], v[146:149], v[56:59]
	v_mfma_f32_16x16x32_bf16 v[44:47], v[128:131], v[154:157], v[44:47]
	v_mfma_f32_16x16x32_bf16 v[40:43], v[136:139], v[154:157], v[40:43]
	v_mfma_f32_16x16x32_bf16 v[28:31], v[128:131], v[162:165], v[28:31]
	v_mfma_f32_16x16x32_bf16 v[24:27], v[136:139], v[162:165], v[24:27]
	v_mfma_f32_16x16x32_bf16 v[12:15], v[128:131], v[194:197], v[12:15]
	v_mfma_f32_16x16x32_bf16 v[8:11], v[136:139], v[194:197], v[8:11]
	v_mfma_f32_16x16x32_bf16 v[60:63], v[132:135], v[150:153], v[60:63]
	v_mfma_f32_16x16x32_bf16 v[56:59], v[140:143], v[150:153], v[56:59]
	v_mfma_f32_16x16x32_bf16 v[44:47], v[132:135], v[158:161], v[44:47]
	v_mfma_f32_16x16x32_bf16 v[40:43], v[140:143], v[158:161], v[40:43]
	v_mfma_f32_16x16x32_bf16 v[28:31], v[132:135], v[166:169], v[28:31]
	v_mfma_f32_16x16x32_bf16 v[24:27], v[140:143], v[166:169], v[24:27]
	v_mfma_f32_16x16x32_bf16 v[12:15], v[132:135], v[198:201], v[12:15]
	v_mfma_f32_16x16x32_bf16 v[8:11], v[140:143], v[198:201], v[8:11]
	v_mfma_f32_16x16x32_bf16 v[52:55], v[202:205], v[146:149], v[52:55]
	v_mfma_f32_16x16x32_bf16 v[48:51], v[222:225], v[146:149], v[48:51]
	v_mfma_f32_16x16x32_bf16 v[36:39], v[202:205], v[154:157], v[36:39]
	v_mfma_f32_16x16x32_bf16 v[32:35], v[222:225], v[154:157], v[32:35]
	v_mfma_f32_16x16x32_bf16 v[20:23], v[202:205], v[162:165], v[20:23]
	v_mfma_f32_16x16x32_bf16 v[16:19], v[222:225], v[162:165], v[16:19]
	v_mfma_f32_16x16x32_bf16 v[4:7], v[202:205], v[194:197], v[4:7]
	v_mfma_f32_16x16x32_bf16 v[0:3], v[222:225], v[194:197], v[0:3]
	v_mfma_f32_16x16x32_bf16 v[52:55], v[218:221], v[150:153], v[52:55]
	v_mfma_f32_16x16x32_bf16 v[48:51], v[228:231], v[150:153], v[48:51]
	v_mfma_f32_16x16x32_bf16 v[36:39], v[218:221], v[158:161], v[36:39]
	v_mfma_f32_16x16x32_bf16 v[32:35], v[228:231], v[158:161], v[32:35]
	v_mfma_f32_16x16x32_bf16 v[20:23], v[218:221], v[166:169], v[20:23]
	v_mfma_f32_16x16x32_bf16 v[16:19], v[228:231], v[166:169], v[16:19]
	v_mfma_f32_16x16x32_bf16 v[4:7], v[218:221], v[198:201], v[4:7]
	v_mfma_f32_16x16x32_bf16 v[0:3], v[228:231], v[198:201], v[0:3]
	s_barrier
	s_nop 0
	s_add_i32 s27, 0, 0x18000
	ds_read_b128 v[128:131], v207 offset:32768
	ds_read_b128 v[132:135], v207 offset:33792
	ds_read_b128 v[136:139], v207 offset:34816
	ds_read_b128 v[140:143], v207 offset:35840
	s_add_u32 s44, s44, s98
	s_addc_u32 s45, s45, 0
	s_mov_b32 m0, s87
	ds_read_b128 v[146:149], v217 offset:32768
	ds_read_b128 v[150:153], v217 offset:33792
	ds_read_b128 v[154:157], v217 offset:34816
	ds_read_b128 v[158:161], v217 offset:35840
	ds_read_b128 v[162:165], v217 offset:36864
	ds_read_b128 v[166:169], v217 offset:37888
	ds_read_b128 v[194:197], v217 offset:38912
	ds_read_b128 v[198:201], v217 offset:39936
	global_load_lds_dwordx4 v144, s[44:45]
	s_mov_b32 m0, s80
	s_nop 0
	global_load_lds_dwordx4 v188, s[44:45]
	s_waitcnt lgkmcnt(0)
	s_barrier
	v_mfma_f32_16x16x32_bf16 v[124:127], v[128:131], v[146:149], v[124:127]
	v_mfma_f32_16x16x32_bf16 v[120:123], v[136:139], v[146:149], v[120:123]
	v_mfma_f32_16x16x32_bf16 v[108:111], v[128:131], v[154:157], v[108:111]
	v_mfma_f32_16x16x32_bf16 v[104:107], v[136:139], v[154:157], v[104:107]
	v_mfma_f32_16x16x32_bf16 v[92:95], v[128:131], v[162:165], v[92:95]
	v_mfma_f32_16x16x32_bf16 v[88:91], v[136:139], v[162:165], v[88:91]
	v_mfma_f32_16x16x32_bf16 v[76:79], v[128:131], v[194:197], v[76:79]
	v_mfma_f32_16x16x32_bf16 v[72:75], v[136:139], v[194:197], v[72:75]
	v_mfma_f32_16x16x32_bf16 v[124:127], v[132:135], v[150:153], v[124:127]
	v_mfma_f32_16x16x32_bf16 v[120:123], v[140:143], v[150:153], v[120:123]
	v_mfma_f32_16x16x32_bf16 v[108:111], v[132:135], v[158:161], v[108:111]
	v_mfma_f32_16x16x32_bf16 v[104:107], v[140:143], v[158:161], v[104:107]
	v_mfma_f32_16x16x32_bf16 v[92:95], v[132:135], v[166:169], v[92:95]
	v_mfma_f32_16x16x32_bf16 v[88:91], v[140:143], v[166:169], v[88:91]
	v_mfma_f32_16x16x32_bf16 v[76:79], v[132:135], v[198:201], v[76:79]
	v_mfma_f32_16x16x32_bf16 v[72:75], v[140:143], v[198:201], v[72:75]
	s_barrier
	s_add_i32 s44, 0, 0x1c000
	s_add_i32 s27, s27, s84
	v_lshl_add_u64 v[176:177], v[176:177], 0, s[18:19]
	s_mov_b32 m0, s27
	ds_read_b128 v[202:205], v207 offset:49152
	ds_read_b128 v[218:221], v207 offset:50176
	ds_read_b128 v[222:225], v207 offset:51200
	ds_read_b128 v[228:231], v207 offset:52224
	global_load_lds_dwordx4 v[176:177], off
	v_lshl_add_u64 v[176:177], v[232:233], 0, s[18:19]
	s_add_i32 m0, s27, 0x2000
	s_nop 0
	global_load_lds_dwordx4 v[176:177], off
	s_waitcnt lgkmcnt(0)
	s_barrier
	v_mfma_f32_16x16x32_bf16 v[116:119], v[202:205], v[146:149], v[116:119]
	v_mfma_f32_16x16x32_bf16 v[112:115], v[222:225], v[146:149], v[112:115]
	v_mfma_f32_16x16x32_bf16 v[100:103], v[202:205], v[154:157], v[100:103]
	v_mfma_f32_16x16x32_bf16 v[96:99], v[222:225], v[154:157], v[96:99]
	v_mfma_f32_16x16x32_bf16 v[84:87], v[202:205], v[162:165], v[84:87]
	v_mfma_f32_16x16x32_bf16 v[80:83], v[222:225], v[162:165], v[80:83]
	v_mfma_f32_16x16x32_bf16 v[68:71], v[202:205], v[194:197], v[68:71]
	v_mfma_f32_16x16x32_bf16 v[64:67], v[222:225], v[194:197], v[64:67]
	v_mfma_f32_16x16x32_bf16 v[116:119], v[218:221], v[150:153], v[116:119]
	v_mfma_f32_16x16x32_bf16 v[112:115], v[228:231], v[150:153], v[112:115]
	v_mfma_f32_16x16x32_bf16 v[100:103], v[218:221], v[158:161], v[100:103]
	v_mfma_f32_16x16x32_bf16 v[96:99], v[228:231], v[158:161], v[96:99]
	v_mfma_f32_16x16x32_bf16 v[84:87], v[218:221], v[166:169], v[84:87]
	v_mfma_f32_16x16x32_bf16 v[80:83], v[228:231], v[166:169], v[80:83]
	v_mfma_f32_16x16x32_bf16 v[68:71], v[218:221], v[198:201], v[68:71]
	v_mfma_f32_16x16x32_bf16 v[64:67], v[228:231], v[198:201], v[64:67]
	s_barrier
	s_mov_b32 m0, s30
	v_lshl_add_u64 v[176:177], v[234:235], 0, s[18:19]
	ds_read_b128 v[146:149], v217 offset:49152
	ds_read_b128 v[150:153], v217 offset:50176
	ds_read_b128 v[154:157], v217 offset:51200
	ds_read_b128 v[158:161], v217 offset:52224
	ds_read_b128 v[162:165], v217 offset:53248
	ds_read_b128 v[166:169], v217 offset:54272
	ds_read_b128 v[194:197], v217 offset:55296
	ds_read_b128 v[198:201], v217 offset:56320
	global_load_lds_dwordx4 v[176:177], off
	v_lshl_add_u64 v[176:177], v[236:237], 0, s[18:19]
	s_mov_b32 m0, s31
	s_nop 0
	global_load_lds_dwordx4 v[176:177], off
	s_nop 0
	s_add_i32 s27, s44, s84
	v_lshl_add_u64 v[238:239], v[238:239], 0, s[18:19]
	s_mov_b32 m0, s27
	s_nop 0
	global_load_lds_dwordx4 v[238:239], off
	v_lshl_add_u64 v[240:241], v[240:241], 0, s[18:19]
	s_add_i32 m0, s27, 0x2000
	s_nop 0
	global_load_lds_dwordx4 v[240:241], off
	s_waitcnt lgkmcnt(0)
	s_waitcnt vmcnt(6)
	s_barrier
	v_mfma_f32_16x16x32_bf16 v[60:63], v[128:131], v[146:149], v[60:63]
	v_mfma_f32_16x16x32_bf16 v[56:59], v[136:139], v[146:149], v[56:59]
	v_mfma_f32_16x16x32_bf16 v[44:47], v[128:131], v[154:157], v[44:47]
	v_mfma_f32_16x16x32_bf16 v[40:43], v[136:139], v[154:157], v[40:43]
	v_mfma_f32_16x16x32_bf16 v[28:31], v[128:131], v[162:165], v[28:31]
	v_mfma_f32_16x16x32_bf16 v[24:27], v[136:139], v[162:165], v[24:27]
	v_mfma_f32_16x16x32_bf16 v[12:15], v[128:131], v[194:197], v[12:15]
	v_mfma_f32_16x16x32_bf16 v[8:11], v[136:139], v[194:197], v[8:11]
	v_mfma_f32_16x16x32_bf16 v[60:63], v[132:135], v[150:153], v[60:63]
	v_mfma_f32_16x16x32_bf16 v[56:59], v[140:143], v[150:153], v[56:59]
	v_mfma_f32_16x16x32_bf16 v[44:47], v[132:135], v[158:161], v[44:47]
	v_mfma_f32_16x16x32_bf16 v[40:43], v[140:143], v[158:161], v[40:43]
	v_mfma_f32_16x16x32_bf16 v[28:31], v[132:135], v[166:169], v[28:31]
	v_mfma_f32_16x16x32_bf16 v[24:27], v[140:143], v[166:169], v[24:27]
	v_mfma_f32_16x16x32_bf16 v[12:15], v[132:135], v[198:201], v[12:15]
	v_mfma_f32_16x16x32_bf16 v[8:11], v[140:143], v[198:201], v[8:11]
	v_mfma_f32_16x16x32_bf16 v[52:55], v[202:205], v[146:149], v[52:55]
	v_mfma_f32_16x16x32_bf16 v[48:51], v[222:225], v[146:149], v[48:51]
	v_mfma_f32_16x16x32_bf16 v[36:39], v[202:205], v[154:157], v[36:39]
	v_mfma_f32_16x16x32_bf16 v[32:35], v[222:225], v[154:157], v[32:35]
	v_mfma_f32_16x16x32_bf16 v[20:23], v[202:205], v[162:165], v[20:23]
	v_mfma_f32_16x16x32_bf16 v[16:19], v[222:225], v[162:165], v[16:19]
	v_mfma_f32_16x16x32_bf16 v[4:7], v[202:205], v[194:197], v[4:7]
	v_mfma_f32_16x16x32_bf16 v[0:3], v[222:225], v[194:197], v[0:3]
	v_mfma_f32_16x16x32_bf16 v[52:55], v[218:221], v[150:153], v[52:55]
	v_mfma_f32_16x16x32_bf16 v[48:51], v[228:231], v[150:153], v[48:51]
	v_mfma_f32_16x16x32_bf16 v[36:39], v[218:221], v[158:161], v[36:39]
	v_mfma_f32_16x16x32_bf16 v[32:35], v[228:231], v[158:161], v[32:35]
	v_mfma_f32_16x16x32_bf16 v[20:23], v[218:221], v[166:169], v[20:23]
	v_mfma_f32_16x16x32_bf16 v[16:19], v[228:231], v[166:169], v[16:19]
	v_mfma_f32_16x16x32_bf16 v[4:7], v[218:221], v[198:201], v[4:7]
	v_mfma_f32_16x16x32_bf16 v[0:3], v[228:231], v[198:201], v[0:3]
	s_barrier
	s_add_u32 s42, s42, 0x100
	s_addc_u32 s43, s43, 0
	s_add_u32 s33, s33, 0x100
	s_addc_u32 s37, s37, 0
	s_cmp_ge_u32 s56, s34
	s_mov_b32 s27, s56
	s_cbranch_scc0 .LBB0_196
	v_lshl_add_u32 v194, s11, 8, v206
	v_ashrrev_i32_e32 v195, 31, v194
	v_lshl_or_b32 v196, s10, 8, v216
	v_lshlrev_b64 v[128:129], 11, v[194:195]
	v_ashrrev_i32_e32 v197, 31, v196
	s_and_b64 vcc, exec, s[92:93]
	v_or_b32_e32 v198, 16, v194
	v_lshl_add_u64 v[200:201], s[54:55], 0, v[128:129]
	s_cbranch_vccz .LBB0_215
	v_lshlrev_b64 v[128:129], 12, v[194:195]
	v_lshl_add_u64 v[128:129], s[50:51], 0, v[128:129]
	v_lshlrev_b64 v[130:131], 2, v[196:197]
	v_lshl_add_u64 v[128:129], v[128:129], 0, v[130:131]
	global_load_dwordx4 v[146:149], v[128:129], off offset:16
	global_load_dwordx4 v[150:153], v[128:129], off
	global_load_dwordx4 v[154:157], v[128:129], off offset:528
	global_load_dwordx4 v[158:161], v[128:129], off offset:512
	v_ashrrev_i32_e32 v199, 31, v198
	v_lshlrev_b64 v[128:129], 12, v[198:199]
	v_lshl_add_u64 v[128:129], s[50:51], 0, v[128:129]
	v_lshl_add_u64 v[132:133], v[128:129], 0, v[130:131]
	global_load_dwordx4 v[136:139], v[132:133], off offset:16
	global_load_dwordx4 v[140:143], v[132:133], off
	global_load_dwordx4 v[128:131], v[132:133], off offset:528
	s_nop 0
	global_load_dwordx4 v[132:135], v[132:133], off offset:512
	v_lshl_add_u64 v[166:167], v[196:197], 1, v[200:201]
	s_waitcnt vmcnt(0)
	v_pk_add_f32 v[164:165], v[120:121], v[146:147]
	v_pk_add_f32 v[152:153], v[126:127], v[152:153]
	v_pk_add_f32 v[150:151], v[124:125], v[150:151]
	v_pk_add_f32 v[162:163], v[122:123], v[148:149]
	v_cvt_pk_bf16_f32 v146, v150, v151
	v_cvt_pk_bf16_f32 v147, v152, v153
	v_cvt_pk_bf16_f32 v148, v164, v165
	v_pk_add_f32 v[156:157], v[114:115], v[156:157]
	v_cvt_pk_bf16_f32 v149, v162, v163
	global_store_dwordx4 v[166:167], v[146:149], off
	v_pk_add_f32 v[154:155], v[112:113], v[154:155]
	s_nop 0
	v_mul_f32_e32 v146, v151, v151
	v_mul_f32_e32 v147, v153, v153
	v_fmac_f32_e32 v146, v150, v150
	v_fmac_f32_e32 v147, v152, v152
	v_add_f32_e32 v146, v146, v147
	v_mul_f32_e32 v147, v165, v165
	v_mul_f32_e32 v148, v163, v163
	v_fmac_f32_e32 v147, v164, v164
	v_fmac_f32_e32 v148, v162, v162
	v_add_f32_e32 v147, v147, v148
	v_add_f32_e32 v162, v146, v147
	v_pk_add_f32 v[150:151], v[118:119], v[160:161]
	v_pk_add_f32 v[152:153], v[116:117], v[158:159]
	s_nop 0
	v_cvt_pk_bf16_f32 v146, v152, v153
	v_cvt_pk_bf16_f32 v147, v150, v151
	v_cvt_pk_bf16_f32 v148, v154, v155
	v_cvt_pk_bf16_f32 v149, v156, v157
	global_store_dwordx4 v[166:167], v[146:149], off offset:256
	s_nop 1
	v_mul_f32_e32 v146, v153, v153
	v_mul_f32_e32 v147, v151, v151
	v_fmac_f32_e32 v146, v152, v152
	v_fmac_f32_e32 v147, v150, v150
	v_add_f32_e32 v146, v146, v147
	v_mul_f32_e32 v147, v155, v155
	v_mul_f32_e32 v148, v157, v157
	v_fmac_f32_e32 v147, v154, v154
	v_fmac_f32_e32 v148, v156, v156
	v_add_f32_e32 v147, v147, v148
	v_and_b32_e32 v148, 64, v214
	v_add_f32_e32 v146, v146, v147
	v_xor_b32_e32 v147, 16, v214
	v_add_u32_e32 v148, 64, v148
	v_cmp_lt_i32_e32 vcc, v147, v148
	v_add_f32_e32 v146, v162, v146
	s_nop 0
	v_cndmask_b32_e32 v147, v214, v147, vcc
	v_lshlrev_b32_e32 v218, 2, v147
	ds_bpermute_b32 v147, v218, v146
	s_waitcnt lgkmcnt(0)
	v_add_f32_e32 v146, v146, v147
	v_xor_b32_e32 v147, 32, v214
	v_cmp_lt_i32_e32 vcc, v147, v148
	s_nop 1
	v_cndmask_b32_e32 v147, v214, v147, vcc
	v_lshlrev_b32_e32 v219, 2, v147
	ds_bpermute_b32 v147, v219, v146
	s_and_saveexec_b64 s[42:43], s[38:39]
	s_cbranch_execz .LBB0_200
	s_waitcnt lgkmcnt(0)
	v_add_f32_e32 v146, v146, v147
	v_fma_f32 v146, v146, s91, 0.5
	v_trunc_f32_e32 v146, v146
	v_mul_f32_e32 v147, 0x2f800000, v146
	v_floor_f32_e32 v147, v147
	v_fmac_f32_e32 v146, 0xcf800000, v147
	v_cvt_u32_f32_e32 v146, v146
	v_cvt_u32_f32_e32 v147, v147
	v_lshl_add_u64 v[148:149], v[194:195], 3, s[52:53]
	global_atomic_add_x2 v[148:149], v[146:147], off

.LBB0_325:
	s_nop 0
	s_ashr_i32 s93, s92, 31
	s_lshl_b64 s[30:31], s[92:93], 19
	s_add_u32 s94, s54, s30
	v_cmp_lt_i64_e32 vcc, s[50:51], v[186:187]
	s_addc_u32 s95, s55, s31
	s_and_b64 s[30:31], vcc, exec
	s_cselect_b32 s1, s95, s53
	s_cselect_b32 s11, s94, s52
	s_ashr_i32 s9, s8, 31
	s_lshl_b64 s[30:31], s[8:9], 19
	s_add_u32 s28, s80, s30
	s_addc_u32 s29, s78, s31
	s_and_b64 s[30:31], vcc, exec
	s_cselect_b32 s25, s29, s73
	s_cselect_b32 s30, s28, s72
	s_add_u32 s52, s52, 0x40080
	s_addc_u32 s53, s53, 0
	s_add_u32 s31, s72, 0x100
	s_addc_u32 s33, s73, 0
	s_mov_b32 s34, -2
	s_add_u32 s27, s52, 0xfffc0080
	s_addc_u32 s35, s53, -1
	s_add_i32 s36, 0, 0x10000
	ds_read_b128 v[128:131], v216
	ds_read_b128 v[132:135], v216 offset:1024
	ds_read_b128 v[136:139], v216 offset:2048
	ds_read_b128 v[140:143], v216 offset:3072
	s_cmp_eq_u32 s34, 12
	s_cselect_b32 s75, s1, s35
	s_cselect_b32 s74, s11, s27
	s_cselect_b32 s73, s25, s33
	s_cselect_b32 s72, s30, s31
	s_add_i32 m0, s83, 0xc000
	ds_read_b128 v[156:159], v217
	ds_read_b128 v[160:163], v217 offset:1024
	ds_read_b128 v[164:167], v217 offset:2048
	ds_read_b128 v[188:191], v217 offset:3072
	ds_read_b128 v[192:195], v217 offset:4096
	ds_read_b128 v[196:199], v217 offset:5120
	ds_read_b128 v[200:203], v217 offset:6144
	ds_read_b128 v[204:207], v217 offset:7168
	global_load_lds_dwordx4 v152, s[52:53]
	s_add_i32 m0, s83, 0xe000
	s_nop 0
	global_load_lds_dwordx4 v154, s[52:53]
	s_waitcnt lgkmcnt(0)
	s_barrier
	v_mfma_f32_16x16x32_bf16 v[124:127], v[128:131], v[156:159], 0
	v_mfma_f32_16x16x32_bf16 v[120:123], v[136:139], v[156:159], 0
	v_mfma_f32_16x16x32_bf16 v[108:111], v[128:131], v[164:167], 0
	v_mfma_f32_16x16x32_bf16 v[104:107], v[136:139], v[164:167], 0
	v_mfma_f32_16x16x32_bf16 v[92:95], v[128:131], v[192:195], 0
	v_mfma_f32_16x16x32_bf16 v[88:91], v[136:139], v[192:195], 0
	v_mfma_f32_16x16x32_bf16 v[76:79], v[128:131], v[200:203], 0
	v_mfma_f32_16x16x32_bf16 v[72:75], v[136:139], v[200:203], 0
	v_mfma_f32_16x16x32_bf16 v[124:127], v[132:135], v[160:163], v[124:127]
	v_mfma_f32_16x16x32_bf16 v[120:123], v[140:143], v[160:163], v[120:123]
	v_mfma_f32_16x16x32_bf16 v[108:111], v[132:135], v[188:191], v[108:111]
	v_mfma_f32_16x16x32_bf16 v[104:107], v[140:143], v[188:191], v[104:107]
	v_mfma_f32_16x16x32_bf16 v[92:95], v[132:135], v[196:199], v[92:95]
	v_mfma_f32_16x16x32_bf16 v[88:91], v[140:143], v[196:199], v[88:91]
	v_mfma_f32_16x16x32_bf16 v[76:79], v[132:135], v[204:207], v[76:79]
	v_mfma_f32_16x16x32_bf16 v[72:75], v[140:143], v[204:207], v[72:75]
	s_barrier
	s_add_i32 s27, 0, 0x14000
	s_add_i32 s35, s36, s81
	s_mov_b32 m0, s35
	ds_read_b128 v[220:223], v216 offset:16384
	ds_read_b128 v[228:231], v216 offset:17408
	ds_read_b128 v[232:235], v216 offset:18432
	ds_read_b128 v[236:239], v216 offset:19456
	global_load_lds_dwordx4 v148, s[72:73]
	s_add_i32 m0, s35, 0x2000
	s_nop 0
	global_load_lds_dwordx4 v146, s[72:73]
	s_waitcnt lgkmcnt(0)
	s_barrier
	v_mfma_f32_16x16x32_bf16 v[116:119], v[220:223], v[156:159], 0
	v_mfma_f32_16x16x32_bf16 v[112:115], v[232:235], v[156:159], 0
	v_mfma_f32_16x16x32_bf16 v[100:103], v[220:223], v[164:167], 0
	v_mfma_f32_16x16x32_bf16 v[96:99], v[232:235], v[164:167], 0
	v_mfma_f32_16x16x32_bf16 v[84:87], v[220:223], v[192:195], 0
	v_mfma_f32_16x16x32_bf16 v[80:83], v[232:235], v[192:195], 0
	v_mfma_f32_16x16x32_bf16 v[68:71], v[220:223], v[200:203], 0
	v_mfma_f32_16x16x32_bf16 v[64:67], v[232:235], v[200:203], 0
	v_mfma_f32_16x16x32_bf16 v[116:119], v[228:231], v[160:163], v[116:119]
	v_mfma_f32_16x16x32_bf16 v[112:115], v[236:239], v[160:163], v[112:115]
	v_mfma_f32_16x16x32_bf16 v[100:103], v[228:231], v[188:191], v[100:103]
	v_mfma_f32_16x16x32_bf16 v[96:99], v[236:239], v[188:191], v[96:99]
	v_mfma_f32_16x16x32_bf16 v[84:87], v[228:231], v[196:199], v[84:87]
	v_mfma_f32_16x16x32_bf16 v[80:83], v[236:239], v[196:199], v[80:83]
	v_mfma_f32_16x16x32_bf16 v[68:71], v[228:231], v[204:207], v[68:71]
	v_mfma_f32_16x16x32_bf16 v[64:67], v[236:239], v[204:207], v[64:67]
	s_barrier
	s_mov_b32 m0, s83
	ds_read_b128 v[156:159], v217 offset:16384
	ds_read_b128 v[160:163], v217 offset:17408
	ds_read_b128 v[164:167], v217 offset:18432
	ds_read_b128 v[188:191], v217 offset:19456
	ds_read_b128 v[192:195], v217 offset:20480
	ds_read_b128 v[196:199], v217 offset:21504
	ds_read_b128 v[200:203], v217 offset:22528
	ds_read_b128 v[204:207], v217 offset:23552
	global_load_lds_dwordx4 v148, s[74:75]
	s_mov_b32 m0, s84
	s_nop 0
	global_load_lds_dwordx4 v146, s[74:75]
	s_add_u32 s36, s72, 0x40000
	s_addc_u32 s37, s73, 0
	s_add_i32 s27, s27, s81
	s_mov_b32 m0, s27
	s_nop 0
	global_load_lds_dwordx4 v148, s[36:37]
	s_add_i32 m0, s27, 0x2000
	s_nop 0
	global_load_lds_dwordx4 v146, s[36:37]
	s_waitcnt lgkmcnt(0)
	s_waitcnt vmcnt(6)
	s_barrier
	v_mfma_f32_16x16x32_bf16 v[60:63], v[128:131], v[156:159], 0
	v_mfma_f32_16x16x32_bf16 v[56:59], v[136:139], v[156:159], 0
	v_mfma_f32_16x16x32_bf16 v[44:47], v[128:131], v[164:167], 0
	v_mfma_f32_16x16x32_bf16 v[40:43], v[136:139], v[164:167], 0
	v_mfma_f32_16x16x32_bf16 v[28:31], v[128:131], v[192:195], 0
	v_mfma_f32_16x16x32_bf16 v[24:27], v[136:139], v[192:195], 0
	v_mfma_f32_16x16x32_bf16 v[12:15], v[128:131], v[200:203], 0
	v_mfma_f32_16x16x32_bf16 v[8:11], v[136:139], v[200:203], 0
	v_mfma_f32_16x16x32_bf16 v[60:63], v[132:135], v[160:163], v[60:63]
	v_mfma_f32_16x16x32_bf16 v[56:59], v[140:143], v[160:163], v[56:59]
	v_mfma_f32_16x16x32_bf16 v[44:47], v[132:135], v[188:191], v[44:47]
	v_mfma_f32_16x16x32_bf16 v[40:43], v[140:143], v[188:191], v[40:43]
	v_mfma_f32_16x16x32_bf16 v[28:31], v[132:135], v[196:199], v[28:31]
	v_mfma_f32_16x16x32_bf16 v[24:27], v[140:143], v[196:199], v[24:27]
	v_mfma_f32_16x16x32_bf16 v[12:15], v[132:135], v[204:207], v[12:15]
	v_mfma_f32_16x16x32_bf16 v[8:11], v[140:143], v[204:207], v[8:11]
	v_mfma_f32_16x16x32_bf16 v[52:55], v[220:223], v[156:159], 0
	v_mfma_f32_16x16x32_bf16 v[48:51], v[232:235], v[156:159], 0
	v_mfma_f32_16x16x32_bf16 v[36:39], v[220:223], v[164:167], 0
	v_mfma_f32_16x16x32_bf16 v[32:35], v[232:235], v[164:167], 0
	v_mfma_f32_16x16x32_bf16 v[20:23], v[220:223], v[192:195], 0
	v_mfma_f32_16x16x32_bf16 v[16:19], v[232:235], v[192:195], 0
	v_mfma_f32_16x16x32_bf16 v[4:7], v[220:223], v[200:203], 0
	v_mfma_f32_16x16x32_bf16 v[0:3], v[232:235], v[200:203], 0
	v_mfma_f32_16x16x32_bf16 v[52:55], v[228:231], v[160:163], v[52:55]
	v_mfma_f32_16x16x32_bf16 v[48:51], v[236:239], v[160:163], v[48:51]
	v_mfma_f32_16x16x32_bf16 v[36:39], v[228:231], v[188:191], v[36:39]
	v_mfma_f32_16x16x32_bf16 v[32:35], v[236:239], v[188:191], v[32:35]
	v_mfma_f32_16x16x32_bf16 v[20:23], v[228:231], v[196:199], v[20:23]
	v_mfma_f32_16x16x32_bf16 v[16:19], v[236:239], v[196:199], v[16:19]
	v_mfma_f32_16x16x32_bf16 v[4:7], v[228:231], v[204:207], v[4:7]
	v_mfma_f32_16x16x32_bf16 v[0:3], v[236:239], v[204:207], v[0:3]
	s_barrier
	s_add_i32 s27, 0, 0x18000
	ds_read_b128 v[128:131], v216 offset:32768
	ds_read_b128 v[132:135], v216 offset:33792
	ds_read_b128 v[136:139], v216 offset:34816
	ds_read_b128 v[140:143], v216 offset:35840
	s_add_u32 s36, s74, 0x40000
	s_addc_u32 s37, s75, 0
	s_mov_b32 m0, s85
	ds_read_b128 v[156:159], v217 offset:32768
	ds_read_b128 v[160:163], v217 offset:33792
	ds_read_b128 v[164:167], v217 offset:34816
	ds_read_b128 v[188:191], v217 offset:35840
	ds_read_b128 v[192:195], v217 offset:36864
	ds_read_b128 v[196:199], v217 offset:37888
	ds_read_b128 v[200:203], v217 offset:38912
	ds_read_b128 v[204:207], v217 offset:39936
	global_load_lds_dwordx4 v148, s[36:37]
	s_mov_b32 m0, s86
	s_nop 0
	global_load_lds_dwordx4 v146, s[36:37]
	s_waitcnt lgkmcnt(0)
	s_barrier
	v_mfma_f32_16x16x32_bf16 v[124:127], v[128:131], v[156:159], v[124:127]
	v_mfma_f32_16x16x32_bf16 v[120:123], v[136:139], v[156:159], v[120:123]
	v_mfma_f32_16x16x32_bf16 v[108:111], v[128:131], v[164:167], v[108:111]
	v_mfma_f32_16x16x32_bf16 v[104:107], v[136:139], v[164:167], v[104:107]
	v_mfma_f32_16x16x32_bf16 v[92:95], v[128:131], v[192:195], v[92:95]
	v_mfma_f32_16x16x32_bf16 v[88:91], v[136:139], v[192:195], v[88:91]
	v_mfma_f32_16x16x32_bf16 v[76:79], v[128:131], v[200:203], v[76:79]
	v_mfma_f32_16x16x32_bf16 v[72:75], v[136:139], v[200:203], v[72:75]
	v_mfma_f32_16x16x32_bf16 v[124:127], v[132:135], v[160:163], v[124:127]
	v_mfma_f32_16x16x32_bf16 v[120:123], v[140:143], v[160:163], v[120:123]
	v_mfma_f32_16x16x32_bf16 v[108:111], v[132:135], v[188:191], v[108:111]
	v_mfma_f32_16x16x32_bf16 v[104:107], v[140:143], v[188:191], v[104:107]
	v_mfma_f32_16x16x32_bf16 v[92:95], v[132:135], v[196:199], v[92:95]
	v_mfma_f32_16x16x32_bf16 v[88:91], v[140:143], v[196:199], v[88:91]
	v_mfma_f32_16x16x32_bf16 v[76:79], v[132:135], v[204:207], v[76:79]
	v_mfma_f32_16x16x32_bf16 v[72:75], v[140:143], v[204:207], v[72:75]
	s_barrier
	s_add_i32 s35, 0, 0x1c000
	s_add_i32 s27, s27, s81
	s_add_u32 s36, s72, s18
	s_addc_u32 s37, s73, s19
	s_mov_b32 m0, s27
	ds_read_b128 v[220:223], v216 offset:49152
	ds_read_b128 v[228:231], v216 offset:50176
	ds_read_b128 v[232:235], v216 offset:51200
	ds_read_b128 v[236:239], v216 offset:52224
	global_load_lds_dwordx4 v148, s[36:37]
	s_add_u32 s36, s72, s18
	s_addc_u32 s37, s73, s19
	s_add_i32 m0, s27, 0x2000
	s_nop 0
	global_load_lds_dwordx4 v146, s[36:37]
	s_waitcnt lgkmcnt(0)
	s_barrier
	v_mfma_f32_16x16x32_bf16 v[116:119], v[220:223], v[156:159], v[116:119]
	v_mfma_f32_16x16x32_bf16 v[112:115], v[232:235], v[156:159], v[112:115]
	v_mfma_f32_16x16x32_bf16 v[100:103], v[220:223], v[164:167], v[100:103]
	v_mfma_f32_16x16x32_bf16 v[96:99], v[232:235], v[164:167], v[96:99]
	v_mfma_f32_16x16x32_bf16 v[84:87], v[220:223], v[192:195], v[84:87]
	v_mfma_f32_16x16x32_bf16 v[80:83], v[232:235], v[192:195], v[80:83]
	v_mfma_f32_16x16x32_bf16 v[68:71], v[220:223], v[200:203], v[68:71]
	v_mfma_f32_16x16x32_bf16 v[64:67], v[232:235], v[200:203], v[64:67]
	v_mfma_f32_16x16x32_bf16 v[116:119], v[228:231], v[160:163], v[116:119]
	v_mfma_f32_16x16x32_bf16 v[112:115], v[236:239], v[160:163], v[112:115]
	v_mfma_f32_16x16x32_bf16 v[100:103], v[228:231], v[188:191], v[100:103]
	v_mfma_f32_16x16x32_bf16 v[96:99], v[236:239], v[188:191], v[96:99]
	v_mfma_f32_16x16x32_bf16 v[84:87], v[228:231], v[196:199], v[84:87]
	v_mfma_f32_16x16x32_bf16 v[80:83], v[236:239], v[196:199], v[80:83]
	v_mfma_f32_16x16x32_bf16 v[68:71], v[228:231], v[204:207], v[68:71]
	v_mfma_f32_16x16x32_bf16 v[64:67], v[236:239], v[204:207], v[64:67]
	s_barrier
	s_mov_b32 m0, s87
	s_add_u32 s36, s74, s18
	s_addc_u32 s37, s75, s19
	ds_read_b128 v[156:159], v217 offset:49152
	ds_read_b128 v[160:163], v217 offset:50176
	ds_read_b128 v[164:167], v217 offset:51200
	ds_read_b128 v[188:191], v217 offset:52224
	ds_read_b128 v[192:195], v217 offset:53248
	ds_read_b128 v[196:199], v217 offset:54272
	ds_read_b128 v[200:203], v217 offset:55296
	ds_read_b128 v[204:207], v217 offset:56320
	global_load_lds_dwordx4 v148, s[36:37]
	s_add_u32 s36, s74, s18
	s_addc_u32 s37, s75, s19
	s_mov_b32 m0, s79
	s_nop 0
	global_load_lds_dwordx4 v146, s[36:37]
	s_add_u32 s36, s72, 0x40080
	s_addc_u32 s37, s73, 0
	s_add_i32 s27, s35, s81
	s_mov_b32 m0, s27
	s_nop 0
	global_load_lds_dwordx4 v148, s[36:37]
	s_add_i32 m0, s27, 0x2000
	s_nop 0
	global_load_lds_dwordx4 v146, s[36:37]
	s_waitcnt lgkmcnt(0)
	s_waitcnt vmcnt(6)
	s_barrier
	v_mfma_f32_16x16x32_bf16 v[60:63], v[128:131], v[156:159], v[60:63]
	v_mfma_f32_16x16x32_bf16 v[56:59], v[136:139], v[156:159], v[56:59]
	v_mfma_f32_16x16x32_bf16 v[44:47], v[128:131], v[164:167], v[44:47]
	v_mfma_f32_16x16x32_bf16 v[40:43], v[136:139], v[164:167], v[40:43]
	v_mfma_f32_16x16x32_bf16 v[28:31], v[128:131], v[192:195], v[28:31]
	v_mfma_f32_16x16x32_bf16 v[24:27], v[136:139], v[192:195], v[24:27]
	v_mfma_f32_16x16x32_bf16 v[12:15], v[128:131], v[200:203], v[12:15]
	v_mfma_f32_16x16x32_bf16 v[8:11], v[136:139], v[200:203], v[8:11]
	v_mfma_f32_16x16x32_bf16 v[60:63], v[132:135], v[160:163], v[60:63]
	v_mfma_f32_16x16x32_bf16 v[56:59], v[140:143], v[160:163], v[56:59]
	v_mfma_f32_16x16x32_bf16 v[44:47], v[132:135], v[188:191], v[44:47]
	v_mfma_f32_16x16x32_bf16 v[40:43], v[140:143], v[188:191], v[40:43]
	v_mfma_f32_16x16x32_bf16 v[28:31], v[132:135], v[196:199], v[28:31]
	v_mfma_f32_16x16x32_bf16 v[24:27], v[140:143], v[196:199], v[24:27]
	v_mfma_f32_16x16x32_bf16 v[12:15], v[132:135], v[204:207], v[12:15]
	v_mfma_f32_16x16x32_bf16 v[8:11], v[140:143], v[204:207], v[8:11]
	v_mfma_f32_16x16x32_bf16 v[52:55], v[220:223], v[156:159], v[52:55]
	v_mfma_f32_16x16x32_bf16 v[48:51], v[232:235], v[156:159], v[48:51]
	v_mfma_f32_16x16x32_bf16 v[36:39], v[220:223], v[164:167], v[36:39]
	v_mfma_f32_16x16x32_bf16 v[32:35], v[232:235], v[164:167], v[32:35]
	v_mfma_f32_16x16x32_bf16 v[20:23], v[220:223], v[192:195], v[20:23]
	v_mfma_f32_16x16x32_bf16 v[16:19], v[232:235], v[192:195], v[16:19]
	v_mfma_f32_16x16x32_bf16 v[4:7], v[220:223], v[200:203], v[4:7]
	v_mfma_f32_16x16x32_bf16 v[0:3], v[232:235], v[200:203], v[0:3]
	v_mfma_f32_16x16x32_bf16 v[52:55], v[228:231], v[160:163], v[52:55]
	v_mfma_f32_16x16x32_bf16 v[48:51], v[236:239], v[160:163], v[48:51]
	v_mfma_f32_16x16x32_bf16 v[36:39], v[228:231], v[188:191], v[36:39]
	v_mfma_f32_16x16x32_bf16 v[32:35], v[236:239], v[188:191], v[32:35]
	v_mfma_f32_16x16x32_bf16 v[20:23], v[228:231], v[196:199], v[20:23]
	v_mfma_f32_16x16x32_bf16 v[16:19], v[236:239], v[196:199], v[16:19]
	v_mfma_f32_16x16x32_bf16 v[4:7], v[228:231], v[204:207], v[4:7]
	v_mfma_f32_16x16x32_bf16 v[0:3], v[236:239], v[204:207], v[0:3]
	s_barrier
	s_add_i32 s34, s34, 2
	s_add_u32 s52, s52, 0x100
	s_addc_u32 s53, s53, 0
	s_add_u32 s31, s31, 0x100
	s_addc_u32 s33, s33, 0
	s_cmp_gt_u32 s34, 13
.LBB0_326:
	s_nop 0
	s_add_u32 s27, s52, 0xfffc0080
	s_addc_u32 s35, s53, -1
	s_add_i32 s36, 0, 0x10000
	ds_read_b128 v[128:131], v216
	ds_read_b128 v[132:135], v216 offset:1024
	ds_read_b128 v[136:139], v216 offset:2048
	ds_read_b128 v[140:143], v216 offset:3072
	s_cmp_eq_u32 s34, 12
	s_cselect_b32 s75, s1, s35
	s_cselect_b32 s74, s11, s27
	s_cselect_b32 s73, s25, s33
	s_cselect_b32 s72, s30, s31
	s_add_i32 m0, s83, 0xc000
	ds_read_b128 v[156:159], v217
	ds_read_b128 v[160:163], v217 offset:1024
	ds_read_b128 v[164:167], v217 offset:2048
	ds_read_b128 v[188:191], v217 offset:3072
	ds_read_b128 v[192:195], v217 offset:4096
	ds_read_b128 v[196:199], v217 offset:5120
	ds_read_b128 v[200:203], v217 offset:6144
	ds_read_b128 v[204:207], v217 offset:7168
	global_load_lds_dwordx4 v152, s[52:53]
	s_add_i32 m0, s83, 0xe000
	s_nop 0
	global_load_lds_dwordx4 v154, s[52:53]
	s_waitcnt lgkmcnt(0)
	s_barrier
	v_mfma_f32_16x16x32_bf16 v[124:127], v[128:131], v[156:159], v[124:127]
	v_mfma_f32_16x16x32_bf16 v[120:123], v[136:139], v[156:159], v[120:123]
	v_mfma_f32_16x16x32_bf16 v[108:111], v[128:131], v[164:167], v[108:111]
	v_mfma_f32_16x16x32_bf16 v[104:107], v[136:139], v[164:167], v[104:107]
	v_mfma_f32_16x16x32_bf16 v[92:95], v[128:131], v[192:195], v[92:95]
	v_mfma_f32_16x16x32_bf16 v[88:91], v[136:139], v[192:195], v[88:91]
	v_mfma_f32_16x16x32_bf16 v[76:79], v[128:131], v[200:203], v[76:79]
	v_mfma_f32_16x16x32_bf16 v[72:75], v[136:139], v[200:203], v[72:75]
	v_mfma_f32_16x16x32_bf16 v[124:127], v[132:135], v[160:163], v[124:127]
	v_mfma_f32_16x16x32_bf16 v[120:123], v[140:143], v[160:163], v[120:123]
	v_mfma_f32_16x16x32_bf16 v[108:111], v[132:135], v[188:191], v[108:111]
	v_mfma_f32_16x16x32_bf16 v[104:107], v[140:143], v[188:191], v[104:107]
	v_mfma_f32_16x16x32_bf16 v[92:95], v[132:135], v[196:199], v[92:95]
	v_mfma_f32_16x16x32_bf16 v[88:91], v[140:143], v[196:199], v[88:91]
	v_mfma_f32_16x16x32_bf16 v[76:79], v[132:135], v[204:207], v[76:79]
	v_mfma_f32_16x16x32_bf16 v[72:75], v[140:143], v[204:207], v[72:75]
	s_barrier
	s_add_i32 s27, 0, 0x14000
	s_add_i32 s35, s36, s81
	s_mov_b32 m0, s35
	ds_read_b128 v[220:223], v216 offset:16384
	ds_read_b128 v[228:231], v216 offset:17408
	ds_read_b128 v[232:235], v216 offset:18432
	ds_read_b128 v[236:239], v216 offset:19456
	global_load_lds_dwordx4 v148, s[72:73]
	s_add_i32 m0, s35, 0x2000
	s_nop 0
	global_load_lds_dwordx4 v146, s[72:73]
	s_waitcnt lgkmcnt(0)
	s_barrier
	v_mfma_f32_16x16x32_bf16 v[116:119], v[220:223], v[156:159], v[116:119]
	v_mfma_f32_16x16x32_bf16 v[112:115], v[232:235], v[156:159], v[112:115]
	v_mfma_f32_16x16x32_bf16 v[100:103], v[220:223], v[164:167], v[100:103]
	v_mfma_f32_16x16x32_bf16 v[96:99], v[232:235], v[164:167], v[96:99]
	v_mfma_f32_16x16x32_bf16 v[84:87], v[220:223], v[192:195], v[84:87]
	v_mfma_f32_16x16x32_bf16 v[80:83], v[232:235], v[192:195], v[80:83]
	v_mfma_f32_16x16x32_bf16 v[68:71], v[220:223], v[200:203], v[68:71]
	v_mfma_f32_16x16x32_bf16 v[64:67], v[232:235], v[200:203], v[64:67]
	v_mfma_f32_16x16x32_bf16 v[116:119], v[228:231], v[160:163], v[116:119]
	v_mfma_f32_16x16x32_bf16 v[112:115], v[236:239], v[160:163], v[112:115]
	v_mfma_f32_16x16x32_bf16 v[100:103], v[228:231], v[188:191], v[100:103]
	v_mfma_f32_16x16x32_bf16 v[96:99], v[236:239], v[188:191], v[96:99]
	v_mfma_f32_16x16x32_bf16 v[84:87], v[228:231], v[196:199], v[84:87]
	v_mfma_f32_16x16x32_bf16 v[80:83], v[236:239], v[196:199], v[80:83]
	v_mfma_f32_16x16x32_bf16 v[68:71], v[228:231], v[204:207], v[68:71]
	v_mfma_f32_16x16x32_bf16 v[64:67], v[236:239], v[204:207], v[64:67]
	s_barrier
	s_mov_b32 m0, s83
	ds_read_b128 v[156:159], v217 offset:16384
	ds_read_b128 v[160:163], v217 offset:17408
	ds_read_b128 v[164:167], v217 offset:18432
	ds_read_b128 v[188:191], v217 offset:19456
	ds_read_b128 v[192:195], v217 offset:20480
	ds_read_b128 v[196:199], v217 offset:21504
	ds_read_b128 v[200:203], v217 offset:22528
	ds_read_b128 v[204:207], v217 offset:23552
	global_load_lds_dwordx4 v148, s[74:75]
	s_mov_b32 m0, s84
	s_nop 0
	global_load_lds_dwordx4 v146, s[74:75]
	s_add_u32 s36, s72, 0x40000
	s_addc_u32 s37, s73, 0
	s_add_i32 s27, s27, s81
	s_mov_b32 m0, s27
	s_nop 0
	global_load_lds_dwordx4 v148, s[36:37]
	s_add_i32 m0, s27, 0x2000
	s_nop 0
	global_load_lds_dwordx4 v146, s[36:37]
	s_waitcnt lgkmcnt(0)
	s_waitcnt vmcnt(6)
	s_barrier
	v_mfma_f32_16x16x32_bf16 v[60:63], v[128:131], v[156:159], v[60:63]
	v_mfma_f32_16x16x32_bf16 v[56:59], v[136:139], v[156:159], v[56:59]
	v_mfma_f32_16x16x32_bf16 v[44:47], v[128:131], v[164:167], v[44:47]
	v_mfma_f32_16x16x32_bf16 v[40:43], v[136:139], v[164:167], v[40:43]
	v_mfma_f32_16x16x32_bf16 v[28:31], v[128:131], v[192:195], v[28:31]
	v_mfma_f32_16x16x32_bf16 v[24:27], v[136:139], v[192:195], v[24:27]
	v_mfma_f32_16x16x32_bf16 v[12:15], v[128:131], v[200:203], v[12:15]
	v_mfma_f32_16x16x32_bf16 v[8:11], v[136:139], v[200:203], v[8:11]
	v_mfma_f32_16x16x32_bf16 v[60:63], v[132:135], v[160:163], v[60:63]
	v_mfma_f32_16x16x32_bf16 v[56:59], v[140:143], v[160:163], v[56:59]
	v_mfma_f32_16x16x32_bf16 v[44:47], v[132:135], v[188:191], v[44:47]
	v_mfma_f32_16x16x32_bf16 v[40:43], v[140:143], v[188:191], v[40:43]
	v_mfma_f32_16x16x32_bf16 v[28:31], v[132:135], v[196:199], v[28:31]
	v_mfma_f32_16x16x32_bf16 v[24:27], v[140:143], v[196:199], v[24:27]
	v_mfma_f32_16x16x32_bf16 v[12:15], v[132:135], v[204:207], v[12:15]
	v_mfma_f32_16x16x32_bf16 v[8:11], v[140:143], v[204:207], v[8:11]
	v_mfma_f32_16x16x32_bf16 v[52:55], v[220:223], v[156:159], v[52:55]
	v_mfma_f32_16x16x32_bf16 v[48:51], v[232:235], v[156:159], v[48:51]
	v_mfma_f32_16x16x32_bf16 v[36:39], v[220:223], v[164:167], v[36:39]
	v_mfma_f32_16x16x32_bf16 v[32:35], v[232:235], v[164:167], v[32:35]
	v_mfma_f32_16x16x32_bf16 v[20:23], v[220:223], v[192:195], v[20:23]
	v_mfma_f32_16x16x32_bf16 v[16:19], v[232:235], v[192:195], v[16:19]
	v_mfma_f32_16x16x32_bf16 v[4:7], v[220:223], v[200:203], v[4:7]
	v_mfma_f32_16x16x32_bf16 v[0:3], v[232:235], v[200:203], v[0:3]
	v_mfma_f32_16x16x32_bf16 v[52:55], v[228:231], v[160:163], v[52:55]
	v_mfma_f32_16x16x32_bf16 v[48:51], v[236:239], v[160:163], v[48:51]
	v_mfma_f32_16x16x32_bf16 v[36:39], v[228:231], v[188:191], v[36:39]
	v_mfma_f32_16x16x32_bf16 v[32:35], v[236:239], v[188:191], v[32:35]
	v_mfma_f32_16x16x32_bf16 v[20:23], v[228:231], v[196:199], v[20:23]
	v_mfma_f32_16x16x32_bf16 v[16:19], v[236:239], v[196:199], v[16:19]
	v_mfma_f32_16x16x32_bf16 v[4:7], v[228:231], v[204:207], v[4:7]
	v_mfma_f32_16x16x32_bf16 v[0:3], v[236:239], v[204:207], v[0:3]
	s_barrier
	s_add_i32 s27, 0, 0x18000
	ds_read_b128 v[128:131], v216 offset:32768
	ds_read_b128 v[132:135], v216 offset:33792
	ds_read_b128 v[136:139], v216 offset:34816
	ds_read_b128 v[140:143], v216 offset:35840
	s_add_u32 s36, s74, 0x40000
	s_addc_u32 s37, s75, 0
	s_mov_b32 m0, s85
	ds_read_b128 v[156:159], v217 offset:32768
	ds_read_b128 v[160:163], v217 offset:33792
	ds_read_b128 v[164:167], v217 offset:34816
	ds_read_b128 v[188:191], v217 offset:35840
	ds_read_b128 v[192:195], v217 offset:36864
	ds_read_b128 v[196:199], v217 offset:37888
	ds_read_b128 v[200:203], v217 offset:38912
	ds_read_b128 v[204:207], v217 offset:39936
	global_load_lds_dwordx4 v148, s[36:37]
	s_mov_b32 m0, s86
	s_nop 0
	global_load_lds_dwordx4 v146, s[36:37]
	s_waitcnt lgkmcnt(0)
	s_barrier
	v_mfma_f32_16x16x32_bf16 v[124:127], v[128:131], v[156:159], v[124:127]
	v_mfma_f32_16x16x32_bf16 v[120:123], v[136:139], v[156:159], v[120:123]
	v_mfma_f32_16x16x32_bf16 v[108:111], v[128:131], v[164:167], v[108:111]
	v_mfma_f32_16x16x32_bf16 v[104:107], v[136:139], v[164:167], v[104:107]
	v_mfma_f32_16x16x32_bf16 v[92:95], v[128:131], v[192:195], v[92:95]
	v_mfma_f32_16x16x32_bf16 v[88:91], v[136:139], v[192:195], v[88:91]
	v_mfma_f32_16x16x32_bf16 v[76:79], v[128:131], v[200:203], v[76:79]
	v_mfma_f32_16x16x32_bf16 v[72:75], v[136:139], v[200:203], v[72:75]
	v_mfma_f32_16x16x32_bf16 v[124:127], v[132:135], v[160:163], v[124:127]
	v_mfma_f32_16x16x32_bf16 v[120:123], v[140:143], v[160:163], v[120:123]
	v_mfma_f32_16x16x32_bf16 v[108:111], v[132:135], v[188:191], v[108:111]
	v_mfma_f32_16x16x32_bf16 v[104:107], v[140:143], v[188:191], v[104:107]
	v_mfma_f32_16x16x32_bf16 v[92:95], v[132:135], v[196:199], v[92:95]
	v_mfma_f32_16x16x32_bf16 v[88:91], v[140:143], v[196:199], v[88:91]
	v_mfma_f32_16x16x32_bf16 v[76:79], v[132:135], v[204:207], v[76:79]
	v_mfma_f32_16x16x32_bf16 v[72:75], v[140:143], v[204:207], v[72:75]
	s_barrier
	s_add_i32 s35, 0, 0x1c000
	s_add_i32 s27, s27, s81
	s_add_u32 s36, s72, s18
	s_addc_u32 s37, s73, s19
	s_mov_b32 m0, s27
	ds_read_b128 v[220:223], v216 offset:49152
	ds_read_b128 v[228:231], v216 offset:50176
	ds_read_b128 v[232:235], v216 offset:51200
	ds_read_b128 v[236:239], v216 offset:52224
	global_load_lds_dwordx4 v148, s[36:37]
	s_add_u32 s36, s72, s18
	s_addc_u32 s37, s73, s19
	s_add_i32 m0, s27, 0x2000
	s_nop 0
	global_load_lds_dwordx4 v146, s[36:37]
	s_waitcnt lgkmcnt(0)
	s_barrier
	v_mfma_f32_16x16x32_bf16 v[116:119], v[220:223], v[156:159], v[116:119]
	v_mfma_f32_16x16x32_bf16 v[112:115], v[232:235], v[156:159], v[112:115]
	v_mfma_f32_16x16x32_bf16 v[100:103], v[220:223], v[164:167], v[100:103]
	v_mfma_f32_16x16x32_bf16 v[96:99], v[232:235], v[164:167], v[96:99]
	v_mfma_f32_16x16x32_bf16 v[84:87], v[220:223], v[192:195], v[84:87]
	v_mfma_f32_16x16x32_bf16 v[80:83], v[232:235], v[192:195], v[80:83]
	v_mfma_f32_16x16x32_bf16 v[68:71], v[220:223], v[200:203], v[68:71]
	v_mfma_f32_16x16x32_bf16 v[64:67], v[232:235], v[200:203], v[64:67]
	v_mfma_f32_16x16x32_bf16 v[116:119], v[228:231], v[160:163], v[116:119]
	v_mfma_f32_16x16x32_bf16 v[112:115], v[236:239], v[160:163], v[112:115]
	v_mfma_f32_16x16x32_bf16 v[100:103], v[228:231], v[188:191], v[100:103]
	v_mfma_f32_16x16x32_bf16 v[96:99], v[236:239], v[188:191], v[96:99]
	v_mfma_f32_16x16x32_bf16 v[84:87], v[228:231], v[196:199], v[84:87]
	v_mfma_f32_16x16x32_bf16 v[80:83], v[236:239], v[196:199], v[80:83]
	v_mfma_f32_16x16x32_bf16 v[68:71], v[228:231], v[204:207], v[68:71]
	v_mfma_f32_16x16x32_bf16 v[64:67], v[236:239], v[204:207], v[64:67]
	s_barrier
	s_mov_b32 m0, s87
	s_add_u32 s36, s74, s18
	s_addc_u32 s37, s75, s19
	ds_read_b128 v[156:159], v217 offset:49152
	ds_read_b128 v[160:163], v217 offset:50176
	ds_read_b128 v[164:167], v217 offset:51200
	ds_read_b128 v[188:191], v217 offset:52224
	ds_read_b128 v[192:195], v217 offset:53248
	ds_read_b128 v[196:199], v217 offset:54272
	ds_read_b128 v[200:203], v217 offset:55296
	ds_read_b128 v[204:207], v217 offset:56320
	global_load_lds_dwordx4 v148, s[36:37]
	s_add_u32 s36, s74, s18
	s_addc_u32 s37, s75, s19
	s_mov_b32 m0, s79
	s_nop 0
	global_load_lds_dwordx4 v146, s[36:37]
	s_add_u32 s36, s72, 0x40080
	s_addc_u32 s37, s73, 0
	s_add_i32 s27, s35, s81
	s_mov_b32 m0, s27
	s_nop 0
	global_load_lds_dwordx4 v148, s[36:37]
	s_add_i32 m0, s27, 0x2000
	s_nop 0
	global_load_lds_dwordx4 v146, s[36:37]
	s_waitcnt lgkmcnt(0)
	s_waitcnt vmcnt(6)
	s_barrier
	v_mfma_f32_16x16x32_bf16 v[60:63], v[128:131], v[156:159], v[60:63]
	v_mfma_f32_16x16x32_bf16 v[56:59], v[136:139], v[156:159], v[56:59]
	v_mfma_f32_16x16x32_bf16 v[44:47], v[128:131], v[164:167], v[44:47]
	v_mfma_f32_16x16x32_bf16 v[40:43], v[136:139], v[164:167], v[40:43]
	v_mfma_f32_16x16x32_bf16 v[28:31], v[128:131], v[192:195], v[28:31]
	v_mfma_f32_16x16x32_bf16 v[24:27], v[136:139], v[192:195], v[24:27]
	v_mfma_f32_16x16x32_bf16 v[12:15], v[128:131], v[200:203], v[12:15]
	v_mfma_f32_16x16x32_bf16 v[8:11], v[136:139], v[200:203], v[8:11]
	v_mfma_f32_16x16x32_bf16 v[60:63], v[132:135], v[160:163], v[60:63]
	v_mfma_f32_16x16x32_bf16 v[56:59], v[140:143], v[160:163], v[56:59]
	v_mfma_f32_16x16x32_bf16 v[44:47], v[132:135], v[188:191], v[44:47]
	v_mfma_f32_16x16x32_bf16 v[40:43], v[140:143], v[188:191], v[40:43]
	v_mfma_f32_16x16x32_bf16 v[28:31], v[132:135], v[196:199], v[28:31]
	v_mfma_f32_16x16x32_bf16 v[24:27], v[140:143], v[196:199], v[24:27]
	v_mfma_f32_16x16x32_bf16 v[12:15], v[132:135], v[204:207], v[12:15]
	v_mfma_f32_16x16x32_bf16 v[8:11], v[140:143], v[204:207], v[8:11]
	v_mfma_f32_16x16x32_bf16 v[52:55], v[220:223], v[156:159], v[52:55]
	v_mfma_f32_16x16x32_bf16 v[48:51], v[232:235], v[156:159], v[48:51]
	v_mfma_f32_16x16x32_bf16 v[36:39], v[220:223], v[164:167], v[36:39]
	v_mfma_f32_16x16x32_bf16 v[32:35], v[232:235], v[164:167], v[32:35]
	v_mfma_f32_16x16x32_bf16 v[20:23], v[220:223], v[192:195], v[20:23]
	v_mfma_f32_16x16x32_bf16 v[16:19], v[232:235], v[192:195], v[16:19]
	v_mfma_f32_16x16x32_bf16 v[4:7], v[220:223], v[200:203], v[4:7]
	v_mfma_f32_16x16x32_bf16 v[0:3], v[232:235], v[200:203], v[0:3]
	v_mfma_f32_16x16x32_bf16 v[52:55], v[228:231], v[160:163], v[52:55]
	v_mfma_f32_16x16x32_bf16 v[48:51], v[236:239], v[160:163], v[48:51]
	v_mfma_f32_16x16x32_bf16 v[36:39], v[228:231], v[188:191], v[36:39]
	v_mfma_f32_16x16x32_bf16 v[32:35], v[236:239], v[188:191], v[32:35]
	v_mfma_f32_16x16x32_bf16 v[20:23], v[228:231], v[196:199], v[20:23]
	v_mfma_f32_16x16x32_bf16 v[16:19], v[236:239], v[196:199], v[16:19]
	v_mfma_f32_16x16x32_bf16 v[4:7], v[228:231], v[204:207], v[4:7]
	v_mfma_f32_16x16x32_bf16 v[0:3], v[236:239], v[204:207], v[0:3]
	s_barrier
	s_add_i32 s34, s34, 2
	s_add_u32 s52, s52, 0x100
	s_addc_u32 s53, s53, 0
	s_add_u32 s31, s31, 0x100
	s_addc_u32 s33, s33, 0
	s_cmp_gt_u32 s34, 13
	s_cbranch_scc0 .LBB0_326
	v_lshl_add_u32 v128, s0, 8, v151
	v_readlane_b32 s0, v252, 36
	v_ashrrev_i32_e32 v129, 31, v128
	v_readlane_b32 s1, v252, 37
	v_or_b32_e32 v132, 16, v128
	v_or_b32_e32 v136, 32, v128
	v_lshl_add_u64 v[130:131], v[128:129], 3, s[0:1]
	v_ashrrev_i32_e32 v133, 31, v132
	v_ashrrev_i32_e32 v137, 31, v136
	v_or_b32_e32 v140, 48, v128
	v_lshl_add_u64 v[134:135], v[132:133], 3, s[0:1]
	v_lshl_add_u64 v[138:139], v[136:137], 3, s[0:1]
	v_ashrrev_i32_e32 v141, 31, v140
	global_load_dwordx2 v[202:203], v[130:131], off
	global_load_dwordx2 v[200:201], v[134:135], off
	global_load_dwordx2 v[192:193], v[138:139], off
	global_load_dwordx2 v[166:167], v[130:131], off offset:1024
	v_add_u32_e32 v164, 0x90, v128
	v_add_u32_e32 v158, 0xa0, v128
	v_add_u32_e32 v156, 0xb0, v128
	v_lshl_add_u64 v[142:143], v[140:141], 3, s[0:1]
	v_ashrrev_i32_e32 v165, 31, v164
	v_ashrrev_i32_e32 v159, 31, v158
	v_ashrrev_i32_e32 v157, 31, v156
	v_lshl_add_u64 v[130:131], v[164:165], 3, s[0:1]
	v_lshl_add_u64 v[134:135], v[158:159], 3, s[0:1]
	v_lshl_add_u64 v[138:139], v[156:157], 3, s[0:1]
	global_load_dwordx2 v[196:197], v[142:143], off
	global_load_dwordx2 v[188:189], v[130:131], off
	global_load_dwordx2 v[162:163], v[134:135], off
	global_load_dwordx2 v[160:161], v[138:139], off
	v_add_u32_e32 v168, 0x80, v128
	s_mov_b64 s[0:1], -1
	s_cmp_gt_u32 s10, 1
	v_lshlrev_b32_e32 v144, 1, v150
	v_ashrrev_i32_e32 v169, 31, v168
	v_lshlrev_b64 v[204:205], 10, v[128:129]
	v_lshlrev_b64 v[198:199], 10, v[132:133]
	v_lshlrev_b64 v[194:195], 10, v[136:137]
	v_lshlrev_b64 v[190:191], 10, v[140:141]
	s_waitcnt vmcnt(0)
	v_ffbh_u32_e32 v222, v203
	v_ffbh_u32_e32 v221, v201
	v_ffbh_u32_e32 v220, v193
	v_ffbh_u32_e32 v219, v197
	s_cbranch_scc0 .LBB0_329
	s_cmp_lt_u32 s10, 4
	s_cselect_b64 vcc, -1, 0
	v_readlane_b32 s56, v254, 23
	s_and_b64 s[0:1], vcc, exec
	v_readlane_b32 s70, v254, 37
	v_readlane_b32 s36, v252, 15
	v_readlane_b32 s71, v254, 38
	v_readlane_b32 s37, v252, 16
	s_cselect_b32 s0, s70, s36
	s_mov_b32 s11, 0x4400000
	v_readlane_b32 s30, v254, 62
	s_cselect_b32 s1, s71, s37
	s_cselect_b32 s11, s11, 0x4800000
	v_readlane_b32 s31, v254, 63
	s_add_u32 s0, s0, s30
	s_addc_u32 s1, s1, s31
	global_load_dwordx4 v[136:139], v218, s[0:1] offset:16
	global_load_dwordx4 v[140:143], v218, s[0:1]
	global_load_dwordx4 v[128:131], v218, s[0:1] offset:144
	global_load_dwordx4 v[132:135], v218, s[0:1] offset:128
	v_and_b32_e32 v177, 64, v214
	v_xor_b32_e32 v176, 16, v214
	v_add_u32_e32 v177, 64, v177
	v_cndmask_b32_e32 v223, 1.0, v215, vcc
	v_cmp_lt_i32_e32 vcc, v176, v177
	v_readlane_b32 s9, v254, 52
	s_add_u32 s11, s9, s11
	v_cndmask_b32_e32 v176, v214, v176, vcc
	v_lshlrev_b32_e32 v225, 2, v176
	v_xor_b32_e32 v176, 32, v214
	v_cmp_lt_i32_e32 vcc, v176, v177
	v_readlane_b32 s9, v254, 61
	s_addc_u32 s25, s9, 0
	v_cndmask_b32_e32 v176, v214, v176, vcc
	v_lshlrev_b32_e32 v224, 2, v176
	v_min_u32_e32 v176, 32, v222
	v_lshlrev_b64 v[228:229], v176, v[202:203]
	v_min_u32_e32 v177, 1, v228
	v_or_b32_e32 v177, v229, v177
	v_cvt_f32_u32_e32 v177, v177
	v_sub_u32_e32 v176, 32, v176
	s_lshl_b32 s0, s10, 9
	s_and_b32 s0, s0, 0x200
	v_ldexp_f32 v176, v177, v176
	v_mul_f32_e32 v176, 0x35800000, v176
	v_fmamk_f32 v176, v176, 0x3a800000, v210
	s_add_u32 s0, s11, s0
	v_rsq_f32_e32 v176, v176
	s_addc_u32 s1, s25, 0
	v_lshl_add_u64 v[206:207], s[0:1], 0, v[144:145]
	v_readlane_b32 s48, v252, 27
	v_mov_b32_e32 v228, v176
	v_pk_mul_f32 v[230:231], v[124:125], v[228:229] op_sel_hi:[1,0]
	v_pk_mul_f32 v[232:233], v[126:127], v[228:229] op_sel_hi:[1,0]
	v_pk_mul_f32 v[236:237], v[230:231], v[230:231]
	v_pk_mul_f32 v[234:235], v[232:233], v[232:233]
	v_pk_mul_f32 v[250:251], v[114:115], v[228:229] op_sel_hi:[1,0]
	v_pk_mov_b32 v[238:239], v[236:237], v[234:235] op_sel:[1,0]
	v_mov_b32_e32 v237, v235
	v_pk_add_f32 v[234:235], v[238:239], v[236:237]
	v_pk_mul_f32 v[236:237], v[120:121], v[228:229] op_sel_hi:[1,0]
	v_pk_mul_f32 v[238:239], v[122:123], v[228:229] op_sel_hi:[1,0]
	v_pk_mul_f32 v[242:243], v[236:237], v[236:237]
	v_pk_mul_f32 v[240:241], v[238:239], v[238:239]
	v_pk_add_f32 v[234:235], v[234:235], v[234:235] op_sel_hi:[0,1]
	v_pk_mov_b32 v[244:245], v[242:243], v[240:241] op_sel:[1,0]
	v_mov_b32_e32 v243, v241
	v_pk_add_f32 v[240:241], v[244:245], v[242:243]
	v_pk_mul_f32 v[244:245], v[116:117], v[228:229] op_sel_hi:[1,0]
	v_pk_mul_f32 v[242:243], v[118:119], v[228:229] op_sel_hi:[1,0]
	v_mul_f32_e32 v234, v244, v244
	v_pk_fma_f32 v[246:247], v[244:245], v[244:245], v[234:235] op_sel_hi:[1,1,0]
	v_mul_f32_e32 v234, v242, v242
	v_pk_add_f32 v[240:241], v[240:241], v[240:241] op_sel_hi:[0,1]
	v_pk_fma_f32 v[248:249], v[242:243], v[242:243], v[234:235] op_sel_hi:[1,1,0]
	v_pk_mul_f32 v[176:177], v[112:113], v[228:229] op_sel_hi:[1,0]
	v_mul_f32_e32 v234, v250, v250
	v_mul_f32_e32 v246, v176, v176
	v_mul_f32_e32 v248, v177, v177
	v_mul_f32_e32 v240, v251, v251
	v_pk_add_f32 v[228:229], v[246:247], v[248:249]
	v_pk_add_f32 v[234:235], v[234:235], v[240:241]
	v_lshl_add_u64 v[240:241], v[206:207], 0, v[204:205]
	v_pk_add_f32 v[228:229], v[228:229], v[234:235]
	v_readlane_b32 s57, v254, 24
	v_add_f32_e32 v228, v228, v229
	ds_bpermute_b32 v229, v225, v228
	v_readlane_b32 s58, v254, 25
	v_readlane_b32 s59, v254, 26
	v_readlane_b32 s60, v254, 27
	v_readlane_b32 s61, v254, 28
	s_waitcnt lgkmcnt(0)
	v_add_f32_e32 v228, v228, v229
	ds_bpermute_b32 v229, v224, v228
	v_readlane_b32 s62, v254, 29
	v_readlane_b32 s63, v254, 30
	v_readlane_b32 s64, v254, 31
	v_readlane_b32 s65, v254, 32
	s_waitcnt lgkmcnt(0)
	v_add_f32_e32 v228, v228, v229
	v_fmamk_f32 v228, v228, 0x3c800000, v210
	v_readlane_b32 s66, v254, 33
	v_rsq_f32_e32 v228, v228
	v_readlane_b32 s67, v254, 34
	v_readlane_b32 s68, v254, 35
	v_readlane_b32 s69, v254, 36
	v_mul_f32_e32 v234, v223, v228
	v_pk_mul_f32 v[228:229], v[230:231], v[234:235] op_sel_hi:[1,0]
	v_pk_mul_f32 v[230:231], v[232:233], v[234:235] op_sel_hi:[1,0]
	s_waitcnt vmcnt(2)
	v_pk_mul_f32 v[228:229], v[140:141], v[228:229]
	v_pk_mul_f32 v[230:231], v[142:143], v[230:231]
	v_pk_mul_f32 v[232:233], v[236:237], v[234:235] op_sel_hi:[1,0]
	v_pk_mul_f32 v[236:237], v[238:239], v[234:235] op_sel_hi:[1,0]
	v_cvt_pk_bf16_f32 v228, v228, v229
	v_cvt_pk_bf16_f32 v229, v230, v231
	v_pk_mul_f32 v[232:233], v[136:137], v[232:233]
	v_pk_mul_f32 v[236:237], v[138:139], v[236:237]
	v_cvt_pk_bf16_f32 v230, v232, v233
	v_pk_mul_f32 v[176:177], v[176:177], v[234:235] op_sel_hi:[1,0]
	v_cvt_pk_bf16_f32 v231, v236, v237
	global_store_dwordx4 v[240:241], v[228:231], off
	v_pk_mul_f32 v[232:233], v[250:251], v[234:235] op_sel_hi:[1,0]
	s_waitcnt vmcnt(2)
	v_pk_mul_f32 v[176:177], v[128:129], v[176:177]
	v_pk_mul_f32 v[228:229], v[244:245], v[234:235] op_sel_hi:[1,0]
	v_pk_mul_f32 v[230:231], v[242:243], v[234:235] op_sel_hi:[1,0]
	s_waitcnt vmcnt(1)
	v_pk_mul_f32 v[228:229], v[132:133], v[228:229]
	v_pk_mul_f32 v[230:231], v[134:135], v[230:231]
	v_cvt_pk_bf16_f32 v228, v228, v229
	v_pk_mul_f32 v[232:233], v[130:131], v[232:233]
	v_cvt_pk_bf16_f32 v229, v230, v231
	v_cvt_pk_bf16_f32 v230, v176, v177
	s_nop 1
	v_readlane_b32 s38, v252, 17
	v_cvt_pk_bf16_f32 v231, v232, v233
	s_nop 1
	global_store_dwordx4 v[240:241], v[228:231], off offset:64
	v_readlane_b32 s39, v252, 18
	v_readlane_b32 s40, v252, 19
	v_min_u32_e32 v228, 32, v221
	v_lshlrev_b64 v[176:177], v228, v[200:201]
	v_min_u32_e32 v176, 1, v176
	v_or_b32_e32 v176, v177, v176
	v_cvt_f32_u32_e32 v176, v176
	v_sub_u32_e32 v177, 32, v228
	v_readlane_b32 s41, v252, 20
	v_readlane_b32 s42, v252, 21
	v_ldexp_f32 v176, v176, v177
	v_mul_f32_e32 v176, 0x35800000, v176
	v_fmamk_f32 v176, v176, 0x3a800000, v210
	v_readlane_b32 s43, v252, 22
	v_rsq_f32_e32 v176, v176
	v_readlane_b32 s44, v252, 23
	v_readlane_b32 s45, v252, 24
	v_readlane_b32 s46, v252, 25
	v_pk_mul_f32 v[228:229], v[108:109], v[176:177] op_sel_hi:[1,0]
	v_pk_mul_f32 v[230:231], v[110:111], v[176:177] op_sel_hi:[1,0]
	v_pk_mul_f32 v[234:235], v[228:229], v[228:229]
	v_pk_mul_f32 v[232:233], v[230:231], v[230:231]
	v_pk_mul_f32 v[248:249], v[98:99], v[176:177] op_sel_hi:[1,0]
	v_pk_mov_b32 v[236:237], v[234:235], v[232:233] op_sel:[1,0]
	v_mov_b32_e32 v235, v233
	v_pk_add_f32 v[232:233], v[236:237], v[234:235]
	v_pk_mul_f32 v[234:235], v[104:105], v[176:177] op_sel_hi:[1,0]
	v_pk_mul_f32 v[236:237], v[106:107], v[176:177] op_sel_hi:[1,0]
	v_pk_mul_f32 v[240:241], v[234:235], v[234:235]
	v_pk_mul_f32 v[238:239], v[236:237], v[236:237]
	v_pk_add_f32 v[232:233], v[232:233], v[232:233] op_sel_hi:[0,1]
	v_pk_mov_b32 v[242:243], v[240:241], v[238:239] op_sel:[1,0]
	v_mov_b32_e32 v241, v239
	v_pk_add_f32 v[238:239], v[242:243], v[240:241]
	v_pk_mul_f32 v[242:243], v[100:101], v[176:177] op_sel_hi:[1,0]
	v_pk_mul_f32 v[240:241], v[102:103], v[176:177] op_sel_hi:[1,0]
	v_mul_f32_e32 v232, v242, v242
	v_pk_fma_f32 v[244:245], v[242:243], v[242:243], v[232:233] op_sel_hi:[1,1,0]
	v_mul_f32_e32 v232, v240, v240
	v_pk_add_f32 v[238:239], v[238:239], v[238:239] op_sel_hi:[0,1]
	v_pk_fma_f32 v[246:247], v[240:241], v[240:241], v[232:233] op_sel_hi:[1,1,0]
	v_pk_mul_f32 v[176:177], v[96:97], v[176:177] op_sel_hi:[1,0]
	v_mul_f32_e32 v232, v248, v248
	v_mul_f32_e32 v244, v176, v176
	v_mul_f32_e32 v246, v177, v177
	v_mul_f32_e32 v238, v249, v249
	v_pk_add_f32 v[244:245], v[244:245], v[246:247]
	v_pk_add_f32 v[232:233], v[232:233], v[238:239]
	v_lshl_add_u64 v[238:239], v[206:207], 0, v[198:199]
	v_pk_add_f32 v[232:233], v[244:245], v[232:233]
	v_readlane_b32 s47, v252, 26
	v_add_f32_e32 v232, v232, v233
	ds_bpermute_b32 v233, v225, v232
	v_readlane_b32 s49, v252, 28
	v_readlane_b32 s50, v252, 29
	v_readlane_b32 s51, v252, 30
	v_readlane_b32 s48, v252, 40
	s_waitcnt lgkmcnt(0)
	v_add_f32_e32 v232, v232, v233
	ds_bpermute_b32 v233, v224, v232
	s_mov_b64 s[0:1], 0
	s_waitcnt lgkmcnt(0)
	v_add_f32_e32 v232, v232, v233
	v_fmamk_f32 v232, v232, 0x3c800000, v210
	s_nop 0
	v_rsq_f32_e32 v232, v232
	s_nop 0
	v_mul_f32_e32 v232, v223, v232
	v_pk_mul_f32 v[228:229], v[228:229], v[232:233] op_sel_hi:[1,0]
	v_pk_mul_f32 v[230:231], v[230:231], v[232:233] op_sel_hi:[1,0]
	v_pk_mul_f32 v[228:229], v[140:141], v[228:229]
	v_pk_mul_f32 v[230:231], v[142:143], v[230:231]
	v_pk_mul_f32 v[234:235], v[234:235], v[232:233] op_sel_hi:[1,0]
	v_pk_mul_f32 v[236:237], v[236:237], v[232:233] op_sel_hi:[1,0]
	v_cvt_pk_bf16_f32 v228, v228, v229
	v_cvt_pk_bf16_f32 v229, v230, v231
	v_pk_mul_f32 v[234:235], v[136:137], v[234:235]
	v_pk_mul_f32 v[236:237], v[138:139], v[236:237]
	v_cvt_pk_bf16_f32 v230, v234, v235
	v_pk_mul_f32 v[176:177], v[176:177], v[232:233] op_sel_hi:[1,0]
	v_cvt_pk_bf16_f32 v231, v236, v237
	global_store_dwordx4 v[238:239], v[228:231], off
	v_pk_mul_f32 v[176:177], v[128:129], v[176:177]
	s_nop 0
	v_pk_mul_f32 v[228:229], v[242:243], v[232:233] op_sel_hi:[1,0]
	v_pk_mul_f32 v[230:231], v[240:241], v[232:233] op_sel_hi:[1,0]
	v_pk_mul_f32 v[228:229], v[132:133], v[228:229]
	v_pk_mul_f32 v[230:231], v[134:135], v[230:231]
	v_pk_mul_f32 v[232:233], v[248:249], v[232:233] op_sel_hi:[1,0]
	v_cvt_pk_bf16_f32 v228, v228, v229
	v_cvt_pk_bf16_f32 v229, v230, v231
	v_cvt_pk_bf16_f32 v230, v176, v177
	s_nop 0
	v_pk_mul_f32 v[232:233], v[130:131], v[232:233]
	s_nop 0
	v_cvt_pk_bf16_f32 v231, v232, v233
	global_store_dwordx4 v[238:239], v[228:231], off offset:64
	s_nop 1
	v_min_u32_e32 v228, 32, v220
	v_lshlrev_b64 v[176:177], v228, v[192:193]
	v_min_u32_e32 v176, 1, v176
	v_or_b32_e32 v176, v177, v176
	v_cvt_f32_u32_e32 v176, v176
	v_sub_u32_e32 v177, 32, v228
	v_ldexp_f32 v176, v176, v177
	v_mul_f32_e32 v176, 0x35800000, v176
	v_fmamk_f32 v176, v176, 0x3a800000, v210
	s_nop 0
	v_rsq_f32_e32 v176, v176
	s_nop 0
	v_pk_mul_f32 v[228:229], v[92:93], v[176:177] op_sel_hi:[1,0]
	v_pk_mul_f32 v[230:231], v[94:95], v[176:177] op_sel_hi:[1,0]
	v_pk_mul_f32 v[234:235], v[228:229], v[228:229]
	v_pk_mul_f32 v[232:233], v[230:231], v[230:231]
	v_pk_mul_f32 v[248:249], v[82:83], v[176:177] op_sel_hi:[1,0]
	v_pk_mov_b32 v[236:237], v[234:235], v[232:233] op_sel:[1,0]
	v_mov_b32_e32 v235, v233
	v_pk_add_f32 v[232:233], v[236:237], v[234:235]
	v_pk_mul_f32 v[234:235], v[88:89], v[176:177] op_sel_hi:[1,0]
	v_pk_mul_f32 v[236:237], v[90:91], v[176:177] op_sel_hi:[1,0]
	v_pk_mul_f32 v[240:241], v[234:235], v[234:235]
	v_pk_mul_f32 v[238:239], v[236:237], v[236:237]
	v_pk_add_f32 v[232:233], v[232:233], v[232:233] op_sel_hi:[0,1]
	v_pk_mov_b32 v[242:243], v[240:241], v[238:239] op_sel:[1,0]
	v_mov_b32_e32 v241, v239
	v_pk_add_f32 v[238:239], v[242:243], v[240:241]
	v_pk_mul_f32 v[242:243], v[84:85], v[176:177] op_sel_hi:[1,0]
	v_pk_mul_f32 v[240:241], v[86:87], v[176:177] op_sel_hi:[1,0]
	v_mul_f32_e32 v232, v242, v242
	v_pk_fma_f32 v[244:245], v[242:243], v[242:243], v[232:233] op_sel_hi:[1,1,0]
	v_mul_f32_e32 v232, v240, v240
	v_pk_add_f32 v[238:239], v[238:239], v[238:239] op_sel_hi:[0,1]
	v_pk_fma_f32 v[246:247], v[240:241], v[240:241], v[232:233] op_sel_hi:[1,1,0]
	v_pk_mul_f32 v[176:177], v[80:81], v[176:177] op_sel_hi:[1,0]
	v_mul_f32_e32 v232, v248, v248
	v_mul_f32_e32 v244, v176, v176
	v_mul_f32_e32 v246, v177, v177
	v_mul_f32_e32 v238, v249, v249
	v_pk_add_f32 v[244:245], v[244:245], v[246:247]
	v_pk_add_f32 v[232:233], v[232:233], v[238:239]
	v_lshl_add_u64 v[238:239], v[206:207], 0, v[194:195]
	v_pk_add_f32 v[232:233], v[244:245], v[232:233]
	s_nop 0
	v_add_f32_e32 v232, v232, v233
	ds_bpermute_b32 v233, v225, v232
	s_waitcnt lgkmcnt(0)
	v_add_f32_e32 v232, v232, v233
	ds_bpermute_b32 v233, v224, v232
	s_waitcnt lgkmcnt(0)
	v_add_f32_e32 v232, v232, v233
	v_fmamk_f32 v232, v232, 0x3c800000, v210
	s_nop 0
	v_rsq_f32_e32 v232, v232
	s_nop 0
	v_mul_f32_e32 v232, v223, v232
	v_pk_mul_f32 v[228:229], v[228:229], v[232:233] op_sel_hi:[1,0]
	v_pk_mul_f32 v[230:231], v[230:231], v[232:233] op_sel_hi:[1,0]
	v_pk_mul_f32 v[228:229], v[140:141], v[228:229]
	v_pk_mul_f32 v[230:231], v[142:143], v[230:231]
	v_pk_mul_f32 v[234:235], v[234:235], v[232:233] op_sel_hi:[1,0]
	v_pk_mul_f32 v[236:237], v[236:237], v[232:233] op_sel_hi:[1,0]
	v_cvt_pk_bf16_f32 v228, v228, v229
	v_cvt_pk_bf16_f32 v229, v230, v231
	v_pk_mul_f32 v[234:235], v[136:137], v[234:235]
	v_pk_mul_f32 v[236:237], v[138:139], v[236:237]
	v_cvt_pk_bf16_f32 v230, v234, v235
	v_pk_mul_f32 v[176:177], v[176:177], v[232:233] op_sel_hi:[1,0]
	v_cvt_pk_bf16_f32 v231, v236, v237
	global_store_dwordx4 v[238:239], v[228:231], off
	v_pk_mul_f32 v[176:177], v[128:129], v[176:177]
	s_nop 0
	v_pk_mul_f32 v[228:229], v[242:243], v[232:233] op_sel_hi:[1,0]
	v_pk_mul_f32 v[230:231], v[240:241], v[232:233] op_sel_hi:[1,0]
	v_pk_mul_f32 v[228:229], v[132:133], v[228:229]
	v_pk_mul_f32 v[230:231], v[134:135], v[230:231]
	v_pk_mul_f32 v[232:233], v[248:249], v[232:233] op_sel_hi:[1,0]
	v_cvt_pk_bf16_f32 v228, v228, v229
	v_cvt_pk_bf16_f32 v229, v230, v231
	v_cvt_pk_bf16_f32 v230, v176, v177
	s_nop 0
	v_pk_mul_f32 v[232:233], v[130:131], v[232:233]
	s_nop 0
	v_cvt_pk_bf16_f32 v231, v232, v233
	global_store_dwordx4 v[238:239], v[228:231], off offset:64
	s_nop 1
	v_min_u32_e32 v228, 32, v219
	v_lshlrev_b64 v[176:177], v228, v[196:197]
	v_min_u32_e32 v176, 1, v176
	v_or_b32_e32 v176, v177, v176
	v_cvt_f32_u32_e32 v176, v176
	v_sub_u32_e32 v177, 32, v228
	v_ldexp_f32 v176, v176, v177
	v_mul_f32_e32 v176, 0x35800000, v176
	v_fmamk_f32 v176, v176, 0x3a800000, v210
	s_nop 0
	v_rsq_f32_e32 v176, v176
	s_nop 0
	v_pk_mul_f32 v[228:229], v[76:77], v[176:177] op_sel_hi:[1,0]
	v_pk_mul_f32 v[230:231], v[78:79], v[176:177] op_sel_hi:[1,0]
	v_pk_mul_f32 v[234:235], v[228:229], v[228:229]
	v_pk_mul_f32 v[232:233], v[230:231], v[230:231]
	v_pk_mul_f32 v[248:249], v[66:67], v[176:177] op_sel_hi:[1,0]
	v_pk_mov_b32 v[236:237], v[234:235], v[232:233] op_sel:[1,0]
	v_mov_b32_e32 v235, v233
	v_pk_add_f32 v[232:233], v[236:237], v[234:235]
	v_pk_mul_f32 v[234:235], v[72:73], v[176:177] op_sel_hi:[1,0]
	v_pk_mul_f32 v[236:237], v[74:75], v[176:177] op_sel_hi:[1,0]
	v_pk_mul_f32 v[240:241], v[234:235], v[234:235]
	v_pk_mul_f32 v[238:239], v[236:237], v[236:237]
	v_pk_add_f32 v[232:233], v[232:233], v[232:233] op_sel_hi:[0,1]
	v_pk_mov_b32 v[242:243], v[240:241], v[238:239] op_sel:[1,0]
	v_mov_b32_e32 v241, v239
	v_pk_add_f32 v[238:239], v[242:243], v[240:241]
	v_pk_mul_f32 v[242:243], v[68:69], v[176:177] op_sel_hi:[1,0]
	v_pk_mul_f32 v[240:241], v[70:71], v[176:177] op_sel_hi:[1,0]
	v_mul_f32_e32 v232, v242, v242
	v_pk_fma_f32 v[244:245], v[242:243], v[242:243], v[232:233] op_sel_hi:[1,1,0]
	v_mul_f32_e32 v232, v240, v240
	v_pk_add_f32 v[238:239], v[238:239], v[238:239] op_sel_hi:[0,1]
	v_pk_fma_f32 v[246:247], v[240:241], v[240:241], v[232:233] op_sel_hi:[1,1,0]
	v_pk_mul_f32 v[176:177], v[64:65], v[176:177] op_sel_hi:[1,0]
	v_mul_f32_e32 v232, v248, v248
	v_mul_f32_e32 v244, v176, v176
	v_mul_f32_e32 v246, v177, v177
	v_mul_f32_e32 v238, v249, v249
	v_pk_add_f32 v[244:245], v[244:245], v[246:247]
	v_pk_add_f32 v[232:233], v[232:233], v[238:239]
	v_lshl_add_u64 v[238:239], v[206:207], 0, v[190:191]
	v_pk_add_f32 v[232:233], v[244:245], v[232:233]
	s_nop 0
	v_add_f32_e32 v232, v232, v233
	ds_bpermute_b32 v233, v225, v232
	s_waitcnt lgkmcnt(0)
	v_add_f32_e32 v232, v232, v233
	ds_bpermute_b32 v233, v224, v232
	s_waitcnt lgkmcnt(0)
	v_add_f32_e32 v232, v232, v233
	v_fmamk_f32 v232, v232, 0x3c800000, v210
	s_nop 0
	v_rsq_f32_e32 v232, v232
	s_nop 0
	v_mul_f32_e32 v232, v223, v232
	v_pk_mul_f32 v[228:229], v[228:229], v[232:233] op_sel_hi:[1,0]
	v_pk_mul_f32 v[230:231], v[230:231], v[232:233] op_sel_hi:[1,0]
	v_pk_mul_f32 v[228:229], v[140:141], v[228:229]
	v_pk_mul_f32 v[230:231], v[142:143], v[230:231]
	v_pk_mul_f32 v[234:235], v[234:235], v[232:233] op_sel_hi:[1,0]
	v_pk_mul_f32 v[236:237], v[236:237], v[232:233] op_sel_hi:[1,0]
	v_pk_mul_f32 v[234:235], v[136:137], v[234:235]
	v_pk_mul_f32 v[236:237], v[138:139], v[236:237]
	v_cvt_pk_bf16_f32 v228, v228, v229
	v_cvt_pk_bf16_f32 v229, v230, v231
	v_cvt_pk_bf16_f32 v230, v234, v235
	v_pk_mul_f32 v[176:177], v[176:177], v[232:233] op_sel_hi:[1,0]
	v_cvt_pk_bf16_f32 v231, v236, v237
	global_store_dwordx4 v[238:239], v[228:231], off
	v_pk_mul_f32 v[176:177], v[128:129], v[176:177]
	s_nop 0
	v_pk_mul_f32 v[228:229], v[242:243], v[232:233] op_sel_hi:[1,0]
	v_pk_mul_f32 v[230:231], v[240:241], v[232:233] op_sel_hi:[1,0]
	v_pk_mul_f32 v[228:229], v[132:133], v[228:229]
	v_pk_mul_f32 v[230:231], v[134:135], v[230:231]
	v_pk_mul_f32 v[232:233], v[248:249], v[232:233] op_sel_hi:[1,0]
	v_cvt_pk_bf16_f32 v228, v228, v229
	v_cvt_pk_bf16_f32 v229, v230, v231
	v_cvt_pk_bf16_f32 v230, v176, v177
	v_ffbh_u32_e32 v176, v167
	v_pk_mul_f32 v[232:233], v[130:131], v[232:233]
	s_nop 0
	v_cvt_pk_bf16_f32 v231, v232, v233
	global_store_dwordx4 v[238:239], v[228:231], off offset:64
	s_nop 1
	v_min_u32_e32 v228, 32, v176
	v_lshlrev_b64 v[176:177], v228, v[166:167]
	v_min_u32_e32 v176, 1, v176
	v_or_b32_e32 v176, v177, v176
	v_cvt_f32_u32_e32 v176, v176
	v_sub_u32_e32 v177, 32, v228
	v_ldexp_f32 v176, v176, v177
	v_mul_f32_e32 v176, 0x35800000, v176
	v_fmamk_f32 v176, v176, 0x3a800000, v210
	s_nop 0
	v_rsq_f32_e32 v176, v176
	s_nop 0
	v_pk_mul_f32 v[228:229], v[60:61], v[176:177] op_sel_hi:[1,0]
	v_pk_mul_f32 v[230:231], v[62:63], v[176:177] op_sel_hi:[1,0]
	v_pk_mul_f32 v[234:235], v[228:229], v[228:229]
	v_pk_mul_f32 v[232:233], v[230:231], v[230:231]
	v_pk_mul_f32 v[248:249], v[50:51], v[176:177] op_sel_hi:[1,0]
	v_pk_mov_b32 v[236:237], v[234:235], v[232:233] op_sel:[1,0]
	v_mov_b32_e32 v235, v233
	v_pk_add_f32 v[232:233], v[236:237], v[234:235]
	v_pk_mul_f32 v[234:235], v[56:57], v[176:177] op_sel_hi:[1,0]
	v_pk_mul_f32 v[236:237], v[58:59], v[176:177] op_sel_hi:[1,0]
	v_pk_mul_f32 v[240:241], v[234:235], v[234:235]
	v_pk_mul_f32 v[238:239], v[236:237], v[236:237]
	v_pk_add_f32 v[232:233], v[232:233], v[232:233] op_sel_hi:[0,1]
	v_pk_mov_b32 v[242:243], v[240:241], v[238:239] op_sel:[1,0]
	v_mov_b32_e32 v241, v239
	v_pk_add_f32 v[238:239], v[242:243], v[240:241]
	v_pk_mul_f32 v[242:243], v[52:53], v[176:177] op_sel_hi:[1,0]
	v_pk_mul_f32 v[240:241], v[54:55], v[176:177] op_sel_hi:[1,0]
	v_mul_f32_e32 v232, v242, v242
	v_pk_fma_f32 v[244:245], v[242:243], v[242:243], v[232:233] op_sel_hi:[1,1,0]
	v_mul_f32_e32 v232, v240, v240
	v_pk_add_f32 v[238:239], v[238:239], v[238:239] op_sel_hi:[0,1]
	v_pk_fma_f32 v[246:247], v[240:241], v[240:241], v[232:233] op_sel_hi:[1,1,0]
	v_pk_mul_f32 v[176:177], v[48:49], v[176:177] op_sel_hi:[1,0]
	v_mul_f32_e32 v232, v248, v248
	v_mul_f32_e32 v244, v176, v176
	v_mul_f32_e32 v246, v177, v177
	v_mul_f32_e32 v238, v249, v249
	v_pk_add_f32 v[244:245], v[244:245], v[246:247]
	v_pk_add_f32 v[232:233], v[232:233], v[238:239]
	v_lshlrev_b64 v[238:239], 10, v[168:169]
	v_pk_add_f32 v[232:233], v[244:245], v[232:233]
	v_lshl_add_u64 v[238:239], v[206:207], 0, v[238:239]
	v_add_f32_e32 v232, v232, v233
	ds_bpermute_b32 v233, v225, v232
	s_waitcnt lgkmcnt(0)
	v_add_f32_e32 v232, v232, v233
	ds_bpermute_b32 v233, v224, v232
	s_waitcnt lgkmcnt(0)
	v_add_f32_e32 v232, v232, v233
	v_fmamk_f32 v232, v232, 0x3c800000, v210
	s_nop 0
	v_rsq_f32_e32 v232, v232
	s_nop 0
	v_mul_f32_e32 v232, v223, v232
	v_pk_mul_f32 v[228:229], v[228:229], v[232:233] op_sel_hi:[1,0]
	v_pk_mul_f32 v[230:231], v[230:231], v[232:233] op_sel_hi:[1,0]
	v_pk_mul_f32 v[228:229], v[140:141], v[228:229]
	v_pk_mul_f32 v[230:231], v[142:143], v[230:231]
	v_pk_mul_f32 v[234:235], v[234:235], v[232:233] op_sel_hi:[1,0]
	v_pk_mul_f32 v[236:237], v[236:237], v[232:233] op_sel_hi:[1,0]
	v_pk_mul_f32 v[234:235], v[136:137], v[234:235]
	v_pk_mul_f32 v[236:237], v[138:139], v[236:237]
	v_cvt_pk_bf16_f32 v228, v228, v229
	v_cvt_pk_bf16_f32 v229, v230, v231
	v_cvt_pk_bf16_f32 v230, v234, v235
	v_pk_mul_f32 v[176:177], v[176:177], v[232:233] op_sel_hi:[1,0]
	v_cvt_pk_bf16_f32 v231, v236, v237
	global_store_dwordx4 v[238:239], v[228:231], off
	v_pk_mul_f32 v[176:177], v[128:129], v[176:177]
	s_nop 0
	v_pk_mul_f32 v[228:229], v[242:243], v[232:233] op_sel_hi:[1,0]
	v_pk_mul_f32 v[230:231], v[240:241], v[232:233] op_sel_hi:[1,0]
	v_pk_mul_f32 v[228:229], v[132:133], v[228:229]
	v_pk_mul_f32 v[230:231], v[134:135], v[230:231]
	v_pk_mul_f32 v[232:233], v[248:249], v[232:233] op_sel_hi:[1,0]
	v_cvt_pk_bf16_f32 v228, v228, v229
	v_cvt_pk_bf16_f32 v229, v230, v231
	v_cvt_pk_bf16_f32 v230, v176, v177
	v_ffbh_u32_e32 v176, v189
	v_pk_mul_f32 v[232:233], v[130:131], v[232:233]
	s_nop 0
	v_cvt_pk_bf16_f32 v231, v232, v233
	global_store_dwordx4 v[238:239], v[228:231], off offset:64
	s_nop 1
	v_min_u32_e32 v228, 32, v176
	v_lshlrev_b64 v[176:177], v228, v[188:189]
	v_min_u32_e32 v176, 1, v176
	v_or_b32_e32 v176, v177, v176
	v_cvt_f32_u32_e32 v176, v176
	v_sub_u32_e32 v177, 32, v228
	v_ldexp_f32 v176, v176, v177
	v_mul_f32_e32 v176, 0x35800000, v176
	v_fmamk_f32 v176, v176, 0x3a800000, v210
	s_nop 0
	v_rsq_f32_e32 v176, v176
	s_nop 0
	v_pk_mul_f32 v[228:229], v[44:45], v[176:177] op_sel_hi:[1,0]
	v_pk_mul_f32 v[230:231], v[46:47], v[176:177] op_sel_hi:[1,0]
	v_pk_mul_f32 v[234:235], v[228:229], v[228:229]
	v_pk_mul_f32 v[232:233], v[230:231], v[230:231]
	v_pk_mul_f32 v[248:249], v[34:35], v[176:177] op_sel_hi:[1,0]
	v_pk_mov_b32 v[236:237], v[234:235], v[232:233] op_sel:[1,0]
	v_mov_b32_e32 v235, v233
	v_pk_add_f32 v[232:233], v[236:237], v[234:235]
	v_pk_mul_f32 v[234:235], v[40:41], v[176:177] op_sel_hi:[1,0]
	v_pk_mul_f32 v[236:237], v[42:43], v[176:177] op_sel_hi:[1,0]
	v_pk_mul_f32 v[240:241], v[234:235], v[234:235]
	v_pk_mul_f32 v[238:239], v[236:237], v[236:237]
	v_pk_add_f32 v[232:233], v[232:233], v[232:233] op_sel_hi:[0,1]
	v_pk_mov_b32 v[242:243], v[240:241], v[238:239] op_sel:[1,0]
	v_mov_b32_e32 v241, v239
	v_pk_add_f32 v[238:239], v[242:243], v[240:241]
	v_pk_mul_f32 v[242:243], v[36:37], v[176:177] op_sel_hi:[1,0]
	v_pk_mul_f32 v[240:241], v[38:39], v[176:177] op_sel_hi:[1,0]
	v_mul_f32_e32 v232, v242, v242
	v_pk_fma_f32 v[244:245], v[242:243], v[242:243], v[232:233] op_sel_hi:[1,1,0]
	v_mul_f32_e32 v232, v240, v240
	v_pk_add_f32 v[238:239], v[238:239], v[238:239] op_sel_hi:[0,1]
	v_pk_fma_f32 v[246:247], v[240:241], v[240:241], v[232:233] op_sel_hi:[1,1,0]
	v_pk_mul_f32 v[176:177], v[32:33], v[176:177] op_sel_hi:[1,0]
	v_mul_f32_e32 v232, v248, v248
	v_mul_f32_e32 v244, v176, v176
	v_mul_f32_e32 v246, v177, v177
	v_mul_f32_e32 v238, v249, v249
	v_pk_add_f32 v[244:245], v[244:245], v[246:247]
	v_pk_add_f32 v[232:233], v[232:233], v[238:239]
	v_lshlrev_b64 v[238:239], 10, v[164:165]
	v_pk_add_f32 v[232:233], v[244:245], v[232:233]
	v_lshl_add_u64 v[238:239], v[206:207], 0, v[238:239]
	v_add_f32_e32 v232, v232, v233
	ds_bpermute_b32 v233, v225, v232
	s_waitcnt lgkmcnt(0)
	v_add_f32_e32 v232, v232, v233
	ds_bpermute_b32 v233, v224, v232
	s_waitcnt lgkmcnt(0)
	v_add_f32_e32 v232, v232, v233
	v_fmamk_f32 v232, v232, 0x3c800000, v210
	s_nop 0
	v_rsq_f32_e32 v232, v232
	s_nop 0
	v_mul_f32_e32 v232, v223, v232
	v_pk_mul_f32 v[228:229], v[228:229], v[232:233] op_sel_hi:[1,0]
	v_pk_mul_f32 v[230:231], v[230:231], v[232:233] op_sel_hi:[1,0]
	v_pk_mul_f32 v[228:229], v[140:141], v[228:229]
	v_pk_mul_f32 v[230:231], v[142:143], v[230:231]
	v_pk_mul_f32 v[234:235], v[234:235], v[232:233] op_sel_hi:[1,0]
	v_pk_mul_f32 v[236:237], v[236:237], v[232:233] op_sel_hi:[1,0]
	v_pk_mul_f32 v[234:235], v[136:137], v[234:235]
	v_pk_mul_f32 v[236:237], v[138:139], v[236:237]
	v_cvt_pk_bf16_f32 v228, v228, v229
	v_cvt_pk_bf16_f32 v229, v230, v231
	v_cvt_pk_bf16_f32 v230, v234, v235
	v_pk_mul_f32 v[176:177], v[176:177], v[232:233] op_sel_hi:[1,0]
	v_cvt_pk_bf16_f32 v231, v236, v237
	global_store_dwordx4 v[238:239], v[228:231], off
	v_pk_mul_f32 v[176:177], v[128:129], v[176:177]
	s_nop 0
	v_pk_mul_f32 v[228:229], v[242:243], v[232:233] op_sel_hi:[1,0]
	v_pk_mul_f32 v[230:231], v[240:241], v[232:233] op_sel_hi:[1,0]
	v_pk_mul_f32 v[228:229], v[132:133], v[228:229]
	v_pk_mul_f32 v[230:231], v[134:135], v[230:231]
	v_pk_mul_f32 v[232:233], v[248:249], v[232:233] op_sel_hi:[1,0]
	v_cvt_pk_bf16_f32 v228, v228, v229
	v_cvt_pk_bf16_f32 v229, v230, v231
	v_cvt_pk_bf16_f32 v230, v176, v177
	v_ffbh_u32_e32 v176, v163
	v_pk_mul_f32 v[232:233], v[130:131], v[232:233]
	s_nop 0
	v_cvt_pk_bf16_f32 v231, v232, v233
	global_store_dwordx4 v[238:239], v[228:231], off offset:64
	s_nop 1
	v_min_u32_e32 v228, 32, v176
	v_lshlrev_b64 v[176:177], v228, v[162:163]
	v_min_u32_e32 v176, 1, v176
	v_or_b32_e32 v176, v177, v176
	v_cvt_f32_u32_e32 v176, v176
	v_sub_u32_e32 v177, 32, v228
	v_ldexp_f32 v176, v176, v177
	v_mul_f32_e32 v176, 0x35800000, v176
	v_fmamk_f32 v176, v176, 0x3a800000, v210
	s_nop 0
	v_rsq_f32_e32 v176, v176
	s_nop 0
	v_pk_mul_f32 v[228:229], v[28:29], v[176:177] op_sel_hi:[1,0]
	v_pk_mul_f32 v[230:231], v[30:31], v[176:177] op_sel_hi:[1,0]
	v_pk_mul_f32 v[234:235], v[228:229], v[228:229]
	v_pk_mul_f32 v[232:233], v[230:231], v[230:231]
	v_pk_mul_f32 v[248:249], v[18:19], v[176:177] op_sel_hi:[1,0]
	v_pk_mov_b32 v[236:237], v[234:235], v[232:233] op_sel:[1,0]
	v_mov_b32_e32 v235, v233
	v_pk_add_f32 v[232:233], v[236:237], v[234:235]
	v_pk_mul_f32 v[234:235], v[24:25], v[176:177] op_sel_hi:[1,0]
	v_pk_mul_f32 v[236:237], v[26:27], v[176:177] op_sel_hi:[1,0]
	v_pk_mul_f32 v[240:241], v[234:235], v[234:235]
	v_pk_mul_f32 v[238:239], v[236:237], v[236:237]
	v_pk_add_f32 v[232:233], v[232:233], v[232:233] op_sel_hi:[0,1]
	v_pk_mov_b32 v[242:243], v[240:241], v[238:239] op_sel:[1,0]
	v_mov_b32_e32 v241, v239
	v_pk_add_f32 v[238:239], v[242:243], v[240:241]
	v_pk_mul_f32 v[242:243], v[20:21], v[176:177] op_sel_hi:[1,0]
	v_pk_mul_f32 v[240:241], v[22:23], v[176:177] op_sel_hi:[1,0]
	v_mul_f32_e32 v232, v242, v242
	v_pk_fma_f32 v[244:245], v[242:243], v[242:243], v[232:233] op_sel_hi:[1,1,0]
	v_mul_f32_e32 v232, v240, v240
	v_pk_add_f32 v[238:239], v[238:239], v[238:239] op_sel_hi:[0,1]
	v_pk_fma_f32 v[246:247], v[240:241], v[240:241], v[232:233] op_sel_hi:[1,1,0]
	v_pk_mul_f32 v[176:177], v[16:17], v[176:177] op_sel_hi:[1,0]
	v_mul_f32_e32 v232, v248, v248
	v_mul_f32_e32 v244, v176, v176
	v_mul_f32_e32 v246, v177, v177
	v_mul_f32_e32 v238, v249, v249
	v_pk_add_f32 v[244:245], v[244:245], v[246:247]
	v_pk_add_f32 v[232:233], v[232:233], v[238:239]
	v_lshlrev_b64 v[238:239], 10, v[158:159]
	v_pk_add_f32 v[232:233], v[244:245], v[232:233]
	v_lshl_add_u64 v[238:239], v[206:207], 0, v[238:239]
	v_add_f32_e32 v232, v232, v233
	ds_bpermute_b32 v233, v225, v232
	s_waitcnt lgkmcnt(0)
	v_add_f32_e32 v232, v232, v233
	ds_bpermute_b32 v233, v224, v232
	s_waitcnt lgkmcnt(0)
	v_add_f32_e32 v232, v232, v233
	v_fmamk_f32 v232, v232, 0x3c800000, v210
	s_nop 0
	v_rsq_f32_e32 v232, v232
	s_nop 0
	v_mul_f32_e32 v232, v223, v232
	v_pk_mul_f32 v[228:229], v[228:229], v[232:233] op_sel_hi:[1,0]
	v_pk_mul_f32 v[230:231], v[230:231], v[232:233] op_sel_hi:[1,0]
	v_pk_mul_f32 v[228:229], v[140:141], v[228:229]
	v_pk_mul_f32 v[230:231], v[142:143], v[230:231]
	v_pk_mul_f32 v[234:235], v[234:235], v[232:233] op_sel_hi:[1,0]
	v_pk_mul_f32 v[236:237], v[236:237], v[232:233] op_sel_hi:[1,0]
	v_pk_mul_f32 v[234:235], v[136:137], v[234:235]
	v_pk_mul_f32 v[236:237], v[138:139], v[236:237]
	v_cvt_pk_bf16_f32 v228, v228, v229
	v_cvt_pk_bf16_f32 v229, v230, v231
	v_cvt_pk_bf16_f32 v230, v234, v235
	v_pk_mul_f32 v[176:177], v[176:177], v[232:233] op_sel_hi:[1,0]
	v_cvt_pk_bf16_f32 v231, v236, v237
	global_store_dwordx4 v[238:239], v[228:231], off
	v_pk_mul_f32 v[176:177], v[128:129], v[176:177]
	s_nop 0
	v_pk_mul_f32 v[228:229], v[242:243], v[232:233] op_sel_hi:[1,0]
	v_pk_mul_f32 v[230:231], v[240:241], v[232:233] op_sel_hi:[1,0]
	v_pk_mul_f32 v[228:229], v[132:133], v[228:229]
	v_pk_mul_f32 v[230:231], v[134:135], v[230:231]
	v_pk_mul_f32 v[232:233], v[248:249], v[232:233] op_sel_hi:[1,0]
	v_cvt_pk_bf16_f32 v228, v228, v229
	v_cvt_pk_bf16_f32 v229, v230, v231
	v_cvt_pk_bf16_f32 v230, v176, v177
	v_ffbh_u32_e32 v176, v161
	v_pk_mul_f32 v[232:233], v[130:131], v[232:233]
	s_nop 0
	v_cvt_pk_bf16_f32 v231, v232, v233
	global_store_dwordx4 v[238:239], v[228:231], off offset:64
	s_nop 1
	v_min_u32_e32 v228, 32, v176
	v_lshlrev_b64 v[176:177], v228, v[160:161]
	v_min_u32_e32 v176, 1, v176
	v_or_b32_e32 v176, v177, v176
	v_cvt_f32_u32_e32 v176, v176
	v_sub_u32_e32 v177, 32, v228
	v_ldexp_f32 v176, v176, v177
	v_mul_f32_e32 v176, 0x35800000, v176
	v_fmamk_f32 v176, v176, 0x3a800000, v210
	s_nop 0
	v_rsq_f32_e32 v176, v176
	s_nop 0
	v_pk_mul_f32 v[228:229], v[12:13], v[176:177] op_sel_hi:[1,0]
	v_pk_mul_f32 v[230:231], v[14:15], v[176:177] op_sel_hi:[1,0]
	v_pk_mul_f32 v[234:235], v[228:229], v[228:229]
	v_pk_mul_f32 v[232:233], v[230:231], v[230:231]
	v_pk_mul_f32 v[248:249], v[2:3], v[176:177] op_sel_hi:[1,0]
	v_pk_mov_b32 v[236:237], v[234:235], v[232:233] op_sel:[1,0]
	v_mov_b32_e32 v235, v233
	v_pk_add_f32 v[232:233], v[236:237], v[234:235]
	v_pk_mul_f32 v[234:235], v[8:9], v[176:177] op_sel_hi:[1,0]
	v_pk_mul_f32 v[236:237], v[10:11], v[176:177] op_sel_hi:[1,0]
	v_pk_mul_f32 v[240:241], v[234:235], v[234:235]
	v_pk_mul_f32 v[238:239], v[236:237], v[236:237]
	v_pk_add_f32 v[232:233], v[232:233], v[232:233] op_sel_hi:[0,1]
	v_pk_mov_b32 v[242:243], v[240:241], v[238:239] op_sel:[1,0]
	v_mov_b32_e32 v241, v239
	v_pk_add_f32 v[238:239], v[242:243], v[240:241]
	v_pk_mul_f32 v[242:243], v[4:5], v[176:177] op_sel_hi:[1,0]
	v_pk_mul_f32 v[240:241], v[6:7], v[176:177] op_sel_hi:[1,0]
	v_mul_f32_e32 v232, v242, v242
	v_pk_fma_f32 v[244:245], v[242:243], v[242:243], v[232:233] op_sel_hi:[1,1,0]
	v_mul_f32_e32 v232, v240, v240
	v_pk_add_f32 v[238:239], v[238:239], v[238:239] op_sel_hi:[0,1]
	v_pk_fma_f32 v[246:247], v[240:241], v[240:241], v[232:233] op_sel_hi:[1,1,0]
	v_pk_mul_f32 v[176:177], v[0:1], v[176:177] op_sel_hi:[1,0]
	v_mul_f32_e32 v232, v248, v248
	v_mul_f32_e32 v244, v176, v176
	v_mul_f32_e32 v246, v177, v177
	v_mul_f32_e32 v238, v249, v249
	v_pk_add_f32 v[244:245], v[244:245], v[246:247]
	v_pk_add_f32 v[232:233], v[232:233], v[238:239]
	s_nop 0
	v_pk_add_f32 v[232:233], v[244:245], v[232:233]
	s_nop 0
	v_add_f32_e32 v232, v232, v233
	ds_bpermute_b32 v225, v225, v232
	s_waitcnt lgkmcnt(0)
	v_add_f32_e32 v225, v232, v225
	ds_bpermute_b32 v224, v224, v225
	v_lshlrev_b64 v[232:233], 10, v[156:157]
	v_lshl_add_u64 v[206:207], v[206:207], 0, v[232:233]
	s_waitcnt lgkmcnt(0)
	v_add_f32_e32 v224, v225, v224
	v_fmamk_f32 v224, v224, 0x3c800000, v210
	s_nop 0
	v_rsq_f32_e32 v224, v224
	s_nop 0
	v_mul_f32_e32 v224, v223, v224
	v_pk_mul_f32 v[228:229], v[228:229], v[224:225] op_sel_hi:[1,0]
	v_pk_mul_f32 v[230:231], v[230:231], v[224:225] op_sel_hi:[1,0]
	v_pk_mul_f32 v[140:141], v[140:141], v[228:229]
	v_pk_mul_f32 v[142:143], v[142:143], v[230:231]
	v_pk_mul_f32 v[228:229], v[234:235], v[224:225] op_sel_hi:[1,0]
	v_pk_mul_f32 v[230:231], v[236:237], v[224:225] op_sel_hi:[1,0]
	s_nop 0
	v_pk_mul_f32 v[230:231], v[138:139], v[230:231]
	v_pk_mul_f32 v[138:139], v[136:137], v[228:229]
	v_cvt_pk_bf16_f32 v136, v140, v141
	v_cvt_pk_bf16_f32 v137, v142, v143
	s_nop 0
	v_cvt_pk_bf16_f32 v138, v138, v139
	v_cvt_pk_bf16_f32 v139, v230, v231
	global_store_dwordx4 v[206:207], v[136:139], off
	s_nop 1
	v_pk_mul_f32 v[136:137], v[242:243], v[224:225] op_sel_hi:[1,0]
	v_pk_mul_f32 v[138:139], v[240:241], v[224:225] op_sel_hi:[1,0]
	v_pk_mul_f32 v[132:133], v[132:133], v[136:137]
	v_pk_mul_f32 v[134:135], v[134:135], v[138:139]
	v_pk_mul_f32 v[136:137], v[176:177], v[224:225] op_sel_hi:[1,0]
	v_pk_mul_f32 v[138:139], v[248:249], v[224:225] op_sel_hi:[1,0]
	s_nop 0
	v_pk_mul_f32 v[138:139], v[130:131], v[138:139]
	v_pk_mul_f32 v[130:131], v[128:129], v[136:137]
	v_cvt_pk_bf16_f32 v128, v132, v133
	v_cvt_pk_bf16_f32 v129, v134, v135
	s_nop 0
	v_cvt_pk_bf16_f32 v130, v130, v131
	v_cvt_pk_bf16_f32 v131, v138, v139
	s_nop 1

.LBB0_350:
	s_nop 0
	s_lshl_b32 s25, s84, 1
	s_add_i32 s25, s85, s25
	s_and_b32 s85, s25, 3
	s_lshl_b32 s25, s85, 19
	s_add_u32 s92, s74, s25
	v_cmp_lt_i64_e32 vcc, s[52:53], v[180:181]
	s_addc_u32 s93, s75, 0
	s_and_b64 s[30:31], vcc, exec
	s_cselect_b32 s25, s93, s1
	s_cselect_b32 s30, s92, s0
	s_ashr_i32 s47, s46, 31
	s_lshl_b64 s[34:35], s[46:47], 19
	s_add_u32 s94, s54, s34
	s_addc_u32 s95, s55, s35
	s_and_b64 s[34:35], vcc, exec
	s_cselect_b32 s31, s95, s51
	s_cselect_b32 s33, s94, s50
	s_add_u32 s0, s0, 0x40080
	s_addc_u32 s1, s1, 0
	s_add_u32 s34, s50, 0x100
	s_addc_u32 s35, s51, 0
	s_mov_b32 s36, -2
	s_add_u32 s27, s0, 0xfffc0080
	s_addc_u32 s37, s1, -1
	s_add_i32 s47, 0, 0x10000
	ds_read_b128 v[128:131], v192
	ds_read_b128 v[132:135], v192 offset:1024
	ds_read_b128 v[136:139], v192 offset:2048
	ds_read_b128 v[140:143], v192 offset:3072
	s_cmp_eq_u32 s36, 12
	s_cselect_b32 s53, s25, s37
	s_cselect_b32 s52, s30, s27
	s_cselect_b32 s51, s31, s35
	s_cselect_b32 s50, s33, s34
	s_add_i32 m0, s77, 0xc000
	ds_read_b128 v[162:165], v194
	ds_read_b128 v[166:169], v194 offset:1024
	ds_read_b128 v[196:199], v194 offset:2048
	ds_read_b128 v[200:203], v194 offset:3072
	ds_read_b128 v[204:207], v194 offset:4096
	ds_read_b128 v[216:219], v194 offset:5120
	ds_read_b128 v[220:223], v194 offset:6144
	ds_read_b128 v[228:231], v194 offset:7168
	global_load_lds_dwordx4 v156, s[0:1]
	s_add_i32 m0, s77, 0xe000
	s_nop 0
	global_load_lds_dwordx4 v158, s[0:1]
	s_waitcnt lgkmcnt(0)
	s_barrier
	v_mfma_f32_16x16x32_bf16 v[124:127], v[128:131], v[162:165], 0
	v_mfma_f32_16x16x32_bf16 v[120:123], v[136:139], v[162:165], 0
	v_mfma_f32_16x16x32_bf16 v[116:119], v[128:131], v[196:199], 0
	v_mfma_f32_16x16x32_bf16 v[112:115], v[136:139], v[196:199], 0
	v_mfma_f32_16x16x32_bf16 v[108:111], v[128:131], v[204:207], 0
	v_mfma_f32_16x16x32_bf16 v[104:107], v[136:139], v[204:207], 0
	v_mfma_f32_16x16x32_bf16 v[100:103], v[128:131], v[220:223], 0
	v_mfma_f32_16x16x32_bf16 v[96:99], v[136:139], v[220:223], 0
	v_mfma_f32_16x16x32_bf16 v[124:127], v[132:135], v[166:169], v[124:127]
	v_mfma_f32_16x16x32_bf16 v[120:123], v[140:143], v[166:169], v[120:123]
	v_mfma_f32_16x16x32_bf16 v[116:119], v[132:135], v[200:203], v[116:119]
	v_mfma_f32_16x16x32_bf16 v[112:115], v[140:143], v[200:203], v[112:115]
	v_mfma_f32_16x16x32_bf16 v[108:111], v[132:135], v[216:219], v[108:111]
	v_mfma_f32_16x16x32_bf16 v[104:107], v[140:143], v[216:219], v[104:107]
	v_mfma_f32_16x16x32_bf16 v[100:103], v[132:135], v[228:231], v[100:103]
	v_mfma_f32_16x16x32_bf16 v[96:99], v[140:143], v[228:231], v[96:99]
	s_barrier
	s_add_i32 s27, 0, 0x14000
	s_add_i32 s37, s47, s76
	s_mov_b32 m0, s37
	ds_read_b128 v[232:235], v192 offset:16384
	ds_read_b128 v[236:239], v192 offset:17408
	ds_read_b128 v[240:243], v192 offset:18432
	ds_read_b128 v[244:247], v192 offset:19456
	global_load_lds_dwordx4 v148, s[50:51]
	s_add_i32 m0, s37, 0x2000
	s_nop 0
	global_load_lds_dwordx4 v152, s[50:51]
	s_waitcnt lgkmcnt(0)
	s_barrier
	v_mfma_f32_16x16x32_bf16 v[92:95], v[232:235], v[162:165], 0
	v_mfma_f32_16x16x32_bf16 v[88:91], v[240:243], v[162:165], 0
	v_mfma_f32_16x16x32_bf16 v[84:87], v[232:235], v[196:199], 0
	v_mfma_f32_16x16x32_bf16 v[80:83], v[240:243], v[196:199], 0
	v_mfma_f32_16x16x32_bf16 v[76:79], v[232:235], v[204:207], 0
	v_mfma_f32_16x16x32_bf16 v[72:75], v[240:243], v[204:207], 0
	v_mfma_f32_16x16x32_bf16 v[68:71], v[232:235], v[220:223], 0
	v_mfma_f32_16x16x32_bf16 v[64:67], v[240:243], v[220:223], 0
	v_mfma_f32_16x16x32_bf16 v[92:95], v[236:239], v[166:169], v[92:95]
	v_mfma_f32_16x16x32_bf16 v[88:91], v[244:247], v[166:169], v[88:91]
	v_mfma_f32_16x16x32_bf16 v[84:87], v[236:239], v[200:203], v[84:87]
	v_mfma_f32_16x16x32_bf16 v[80:83], v[244:247], v[200:203], v[80:83]
	v_mfma_f32_16x16x32_bf16 v[76:79], v[236:239], v[216:219], v[76:79]
	v_mfma_f32_16x16x32_bf16 v[72:75], v[244:247], v[216:219], v[72:75]
	v_mfma_f32_16x16x32_bf16 v[68:71], v[236:239], v[228:231], v[68:71]
	v_mfma_f32_16x16x32_bf16 v[64:67], v[244:247], v[228:231], v[64:67]
	s_barrier
	s_mov_b32 m0, s77
	v_lshl_add_u64 v[224:225], s[52:53], 0, v[146:147]
	ds_read_b128 v[162:165], v194 offset:16384
	ds_read_b128 v[166:169], v194 offset:17408
	ds_read_b128 v[196:199], v194 offset:18432
	ds_read_b128 v[200:203], v194 offset:19456
	ds_read_b128 v[204:207], v194 offset:20480
	ds_read_b128 v[216:219], v194 offset:21504
	ds_read_b128 v[220:223], v194 offset:22528
	ds_read_b128 v[228:231], v194 offset:23552
	global_load_lds_dwordx4 v[224:225], off
	v_lshl_add_u64 v[248:249], s[52:53], 0, v[150:151]
	s_mov_b32 m0, s78
	s_nop 0
	global_load_lds_dwordx4 v[248:249], off
	s_add_u32 s56, s50, 0x40000
	s_addc_u32 s57, s51, 0
	s_add_i32 s27, s27, s76
	s_mov_b32 m0, s27
	s_nop 0
	global_load_lds_dwordx4 v148, s[56:57]
	s_add_i32 m0, s27, 0x2000
	s_nop 0
	global_load_lds_dwordx4 v152, s[56:57]
	s_waitcnt lgkmcnt(0)
	s_waitcnt vmcnt(6)
	s_barrier
	v_mfma_f32_16x16x32_bf16 v[60:63], v[128:131], v[162:165], 0
	v_mfma_f32_16x16x32_bf16 v[56:59], v[136:139], v[162:165], 0
	v_mfma_f32_16x16x32_bf16 v[52:55], v[128:131], v[196:199], 0
	v_mfma_f32_16x16x32_bf16 v[48:51], v[136:139], v[196:199], 0
	v_mfma_f32_16x16x32_bf16 v[44:47], v[128:131], v[204:207], 0
	v_mfma_f32_16x16x32_bf16 v[40:43], v[136:139], v[204:207], 0
	v_mfma_f32_16x16x32_bf16 v[36:39], v[128:131], v[220:223], 0
	v_mfma_f32_16x16x32_bf16 v[32:35], v[136:139], v[220:223], 0
	v_mfma_f32_16x16x32_bf16 v[60:63], v[132:135], v[166:169], v[60:63]
	v_mfma_f32_16x16x32_bf16 v[56:59], v[140:143], v[166:169], v[56:59]
	v_mfma_f32_16x16x32_bf16 v[52:55], v[132:135], v[200:203], v[52:55]
	v_mfma_f32_16x16x32_bf16 v[48:51], v[140:143], v[200:203], v[48:51]
	v_mfma_f32_16x16x32_bf16 v[44:47], v[132:135], v[216:219], v[44:47]
	v_mfma_f32_16x16x32_bf16 v[40:43], v[140:143], v[216:219], v[40:43]
	v_mfma_f32_16x16x32_bf16 v[36:39], v[132:135], v[228:231], v[36:39]
	v_mfma_f32_16x16x32_bf16 v[32:35], v[140:143], v[228:231], v[32:35]
	v_mfma_f32_16x16x32_bf16 v[28:31], v[232:235], v[162:165], 0
	v_mfma_f32_16x16x32_bf16 v[24:27], v[240:243], v[162:165], 0
	v_mfma_f32_16x16x32_bf16 v[20:23], v[232:235], v[196:199], 0
	v_mfma_f32_16x16x32_bf16 v[16:19], v[240:243], v[196:199], 0
	v_mfma_f32_16x16x32_bf16 v[12:15], v[232:235], v[204:207], 0
	v_mfma_f32_16x16x32_bf16 v[8:11], v[240:243], v[204:207], 0
	v_mfma_f32_16x16x32_bf16 v[4:7], v[232:235], v[220:223], 0
	v_mfma_f32_16x16x32_bf16 v[0:3], v[240:243], v[220:223], 0
	v_mfma_f32_16x16x32_bf16 v[28:31], v[236:239], v[166:169], v[28:31]
	v_mfma_f32_16x16x32_bf16 v[24:27], v[244:247], v[166:169], v[24:27]
	v_mfma_f32_16x16x32_bf16 v[20:23], v[236:239], v[200:203], v[20:23]
	v_mfma_f32_16x16x32_bf16 v[16:19], v[244:247], v[200:203], v[16:19]
	v_mfma_f32_16x16x32_bf16 v[12:15], v[236:239], v[216:219], v[12:15]
	v_mfma_f32_16x16x32_bf16 v[8:11], v[244:247], v[216:219], v[8:11]
	v_mfma_f32_16x16x32_bf16 v[4:7], v[236:239], v[228:231], v[4:7]
	v_mfma_f32_16x16x32_bf16 v[0:3], v[244:247], v[228:231], v[0:3]
	s_barrier
	s_add_i32 s27, 0, 0x18000
	ds_read_b128 v[128:131], v192 offset:32768
	ds_read_b128 v[132:135], v192 offset:33792
	ds_read_b128 v[136:139], v192 offset:34816
	ds_read_b128 v[140:143], v192 offset:35840
	s_add_u32 s52, s52, 0x40000
	s_addc_u32 s53, s53, 0
	s_mov_b32 m0, s81
	ds_read_b128 v[162:165], v194 offset:32768
	ds_read_b128 v[166:169], v194 offset:33792
	ds_read_b128 v[196:199], v194 offset:34816
	ds_read_b128 v[200:203], v194 offset:35840
	ds_read_b128 v[204:207], v194 offset:36864
	ds_read_b128 v[216:219], v194 offset:37888
	ds_read_b128 v[220:223], v194 offset:38912
	ds_read_b128 v[228:231], v194 offset:39936
	global_load_lds_dwordx4 v146, s[52:53]
	s_mov_b32 m0, s82
	s_nop 0
	global_load_lds_dwordx4 v150, s[52:53]
	s_waitcnt lgkmcnt(0)
	s_barrier
	v_mfma_f32_16x16x32_bf16 v[124:127], v[128:131], v[162:165], v[124:127]
	v_mfma_f32_16x16x32_bf16 v[120:123], v[136:139], v[162:165], v[120:123]
	v_mfma_f32_16x16x32_bf16 v[116:119], v[128:131], v[196:199], v[116:119]
	v_mfma_f32_16x16x32_bf16 v[112:115], v[136:139], v[196:199], v[112:115]
	v_mfma_f32_16x16x32_bf16 v[108:111], v[128:131], v[204:207], v[108:111]
	v_mfma_f32_16x16x32_bf16 v[104:107], v[136:139], v[204:207], v[104:107]
	v_mfma_f32_16x16x32_bf16 v[100:103], v[128:131], v[220:223], v[100:103]
	v_mfma_f32_16x16x32_bf16 v[96:99], v[136:139], v[220:223], v[96:99]
	v_mfma_f32_16x16x32_bf16 v[124:127], v[132:135], v[166:169], v[124:127]
	v_mfma_f32_16x16x32_bf16 v[120:123], v[140:143], v[166:169], v[120:123]
	v_mfma_f32_16x16x32_bf16 v[116:119], v[132:135], v[200:203], v[116:119]
	v_mfma_f32_16x16x32_bf16 v[112:115], v[140:143], v[200:203], v[112:115]
	v_mfma_f32_16x16x32_bf16 v[108:111], v[132:135], v[216:219], v[108:111]
	v_mfma_f32_16x16x32_bf16 v[104:107], v[140:143], v[216:219], v[104:107]
	v_mfma_f32_16x16x32_bf16 v[100:103], v[132:135], v[228:231], v[100:103]
	v_mfma_f32_16x16x32_bf16 v[96:99], v[140:143], v[228:231], v[96:99]
	s_barrier
	s_add_i32 s37, 0, 0x1c000
	s_add_i32 s27, s27, s76
	s_add_u32 s56, s50, s18
	s_addc_u32 s57, s51, s19
	s_mov_b32 m0, s27
	ds_read_b128 v[232:235], v192 offset:49152
	ds_read_b128 v[236:239], v192 offset:50176
	ds_read_b128 v[240:243], v192 offset:51200
	ds_read_b128 v[244:247], v192 offset:52224
	global_load_lds_dwordx4 v148, s[56:57]
	s_add_u32 s56, s50, s18
	s_addc_u32 s57, s51, s19
	s_add_i32 m0, s27, 0x2000
	s_nop 0
	global_load_lds_dwordx4 v152, s[56:57]
	s_waitcnt lgkmcnt(0)
	s_barrier
	v_mfma_f32_16x16x32_bf16 v[92:95], v[232:235], v[162:165], v[92:95]
	v_mfma_f32_16x16x32_bf16 v[88:91], v[240:243], v[162:165], v[88:91]
	v_mfma_f32_16x16x32_bf16 v[84:87], v[232:235], v[196:199], v[84:87]
	v_mfma_f32_16x16x32_bf16 v[80:83], v[240:243], v[196:199], v[80:83]
	v_mfma_f32_16x16x32_bf16 v[76:79], v[232:235], v[204:207], v[76:79]
	v_mfma_f32_16x16x32_bf16 v[72:75], v[240:243], v[204:207], v[72:75]
	v_mfma_f32_16x16x32_bf16 v[68:71], v[232:235], v[220:223], v[68:71]
	v_mfma_f32_16x16x32_bf16 v[64:67], v[240:243], v[220:223], v[64:67]
	v_mfma_f32_16x16x32_bf16 v[92:95], v[236:239], v[166:169], v[92:95]
	v_mfma_f32_16x16x32_bf16 v[88:91], v[244:247], v[166:169], v[88:91]
	v_mfma_f32_16x16x32_bf16 v[84:87], v[236:239], v[200:203], v[84:87]
	v_mfma_f32_16x16x32_bf16 v[80:83], v[244:247], v[200:203], v[80:83]
	v_mfma_f32_16x16x32_bf16 v[76:79], v[236:239], v[216:219], v[76:79]
	v_mfma_f32_16x16x32_bf16 v[72:75], v[244:247], v[216:219], v[72:75]
	v_mfma_f32_16x16x32_bf16 v[68:71], v[236:239], v[228:231], v[68:71]
	v_mfma_f32_16x16x32_bf16 v[64:67], v[244:247], v[228:231], v[64:67]
	s_barrier
	s_mov_b32 m0, s80
	v_lshl_add_u64 v[176:177], v[224:225], 0, s[18:19]
	ds_read_b128 v[162:165], v194 offset:49152
	ds_read_b128 v[166:169], v194 offset:50176
	ds_read_b128 v[196:199], v194 offset:51200
	ds_read_b128 v[200:203], v194 offset:52224
	ds_read_b128 v[204:207], v194 offset:53248
	ds_read_b128 v[216:219], v194 offset:54272
	ds_read_b128 v[220:223], v194 offset:55296
	ds_read_b128 v[228:231], v194 offset:56320
	global_load_lds_dwordx4 v[176:177], off
	v_lshl_add_u64 v[176:177], v[248:249], 0, s[18:19]
	s_mov_b32 m0, s83
	s_nop 0
	global_load_lds_dwordx4 v[176:177], off
	s_add_u32 s50, s50, 0x40080
	s_addc_u32 s51, s51, 0
	s_add_i32 s27, s37, s76
	s_mov_b32 m0, s27
	s_nop 0
	global_load_lds_dwordx4 v148, s[50:51]
	s_add_i32 m0, s27, 0x2000
	s_nop 0
	global_load_lds_dwordx4 v152, s[50:51]
	s_waitcnt lgkmcnt(0)
	s_waitcnt vmcnt(6)
	s_barrier
	v_mfma_f32_16x16x32_bf16 v[60:63], v[128:131], v[162:165], v[60:63]
	v_mfma_f32_16x16x32_bf16 v[56:59], v[136:139], v[162:165], v[56:59]
	v_mfma_f32_16x16x32_bf16 v[52:55], v[128:131], v[196:199], v[52:55]
	v_mfma_f32_16x16x32_bf16 v[48:51], v[136:139], v[196:199], v[48:51]
	v_mfma_f32_16x16x32_bf16 v[44:47], v[128:131], v[204:207], v[44:47]
	v_mfma_f32_16x16x32_bf16 v[40:43], v[136:139], v[204:207], v[40:43]
	v_mfma_f32_16x16x32_bf16 v[36:39], v[128:131], v[220:223], v[36:39]
	v_mfma_f32_16x16x32_bf16 v[32:35], v[136:139], v[220:223], v[32:35]
	v_mfma_f32_16x16x32_bf16 v[60:63], v[132:135], v[166:169], v[60:63]
	v_mfma_f32_16x16x32_bf16 v[56:59], v[140:143], v[166:169], v[56:59]
	v_mfma_f32_16x16x32_bf16 v[52:55], v[132:135], v[200:203], v[52:55]
	v_mfma_f32_16x16x32_bf16 v[48:51], v[140:143], v[200:203], v[48:51]
	v_mfma_f32_16x16x32_bf16 v[44:47], v[132:135], v[216:219], v[44:47]
	v_mfma_f32_16x16x32_bf16 v[40:43], v[140:143], v[216:219], v[40:43]
	v_mfma_f32_16x16x32_bf16 v[36:39], v[132:135], v[228:231], v[36:39]
	v_mfma_f32_16x16x32_bf16 v[32:35], v[140:143], v[228:231], v[32:35]
	v_mfma_f32_16x16x32_bf16 v[28:31], v[232:235], v[162:165], v[28:31]
	v_mfma_f32_16x16x32_bf16 v[24:27], v[240:243], v[162:165], v[24:27]
	v_mfma_f32_16x16x32_bf16 v[20:23], v[232:235], v[196:199], v[20:23]
	v_mfma_f32_16x16x32_bf16 v[16:19], v[240:243], v[196:199], v[16:19]
	v_mfma_f32_16x16x32_bf16 v[12:15], v[232:235], v[204:207], v[12:15]
	v_mfma_f32_16x16x32_bf16 v[8:11], v[240:243], v[204:207], v[8:11]
	v_mfma_f32_16x16x32_bf16 v[4:7], v[232:235], v[220:223], v[4:7]
	v_mfma_f32_16x16x32_bf16 v[0:3], v[240:243], v[220:223], v[0:3]
	v_mfma_f32_16x16x32_bf16 v[28:31], v[236:239], v[166:169], v[28:31]
	v_mfma_f32_16x16x32_bf16 v[24:27], v[244:247], v[166:169], v[24:27]
	v_mfma_f32_16x16x32_bf16 v[20:23], v[236:239], v[200:203], v[20:23]
	v_mfma_f32_16x16x32_bf16 v[16:19], v[244:247], v[200:203], v[16:19]
	v_mfma_f32_16x16x32_bf16 v[12:15], v[236:239], v[216:219], v[12:15]
	v_mfma_f32_16x16x32_bf16 v[8:11], v[244:247], v[216:219], v[8:11]
	v_mfma_f32_16x16x32_bf16 v[4:7], v[236:239], v[228:231], v[4:7]
	v_mfma_f32_16x16x32_bf16 v[0:3], v[244:247], v[228:231], v[0:3]
	s_barrier
	s_add_i32 s36, s36, 2
	s_add_u32 s0, s0, 0x100
	s_addc_u32 s1, s1, 0
	s_add_u32 s34, s34, 0x100
	s_addc_u32 s35, s35, 0
	s_cmp_gt_u32 s36, 13
.LBB0_351:
	s_nop 0
	s_add_u32 s27, s0, 0xfffc0080
	s_addc_u32 s37, s1, -1
	s_add_i32 s47, 0, 0x10000
	ds_read_b128 v[128:131], v192
	ds_read_b128 v[132:135], v192 offset:1024
	ds_read_b128 v[136:139], v192 offset:2048
	ds_read_b128 v[140:143], v192 offset:3072
	s_cmp_eq_u32 s36, 12
	s_cselect_b32 s53, s25, s37
	s_cselect_b32 s52, s30, s27
	s_cselect_b32 s51, s31, s35
	s_cselect_b32 s50, s33, s34
	s_add_i32 m0, s77, 0xc000
	ds_read_b128 v[162:165], v194
	ds_read_b128 v[166:169], v194 offset:1024
	ds_read_b128 v[196:199], v194 offset:2048
	ds_read_b128 v[200:203], v194 offset:3072
	ds_read_b128 v[204:207], v194 offset:4096
	ds_read_b128 v[216:219], v194 offset:5120
	ds_read_b128 v[220:223], v194 offset:6144
	ds_read_b128 v[228:231], v194 offset:7168
	global_load_lds_dwordx4 v156, s[0:1]
	s_add_i32 m0, s77, 0xe000
	s_nop 0
	global_load_lds_dwordx4 v158, s[0:1]
	s_waitcnt lgkmcnt(0)
	s_barrier
	v_mfma_f32_16x16x32_bf16 v[124:127], v[128:131], v[162:165], v[124:127]
	v_mfma_f32_16x16x32_bf16 v[120:123], v[136:139], v[162:165], v[120:123]
	v_mfma_f32_16x16x32_bf16 v[116:119], v[128:131], v[196:199], v[116:119]
	v_mfma_f32_16x16x32_bf16 v[112:115], v[136:139], v[196:199], v[112:115]
	v_mfma_f32_16x16x32_bf16 v[108:111], v[128:131], v[204:207], v[108:111]
	v_mfma_f32_16x16x32_bf16 v[104:107], v[136:139], v[204:207], v[104:107]
	v_mfma_f32_16x16x32_bf16 v[100:103], v[128:131], v[220:223], v[100:103]
	v_mfma_f32_16x16x32_bf16 v[96:99], v[136:139], v[220:223], v[96:99]
	v_mfma_f32_16x16x32_bf16 v[124:127], v[132:135], v[166:169], v[124:127]
	v_mfma_f32_16x16x32_bf16 v[120:123], v[140:143], v[166:169], v[120:123]
	v_mfma_f32_16x16x32_bf16 v[116:119], v[132:135], v[200:203], v[116:119]
	v_mfma_f32_16x16x32_bf16 v[112:115], v[140:143], v[200:203], v[112:115]
	v_mfma_f32_16x16x32_bf16 v[108:111], v[132:135], v[216:219], v[108:111]
	v_mfma_f32_16x16x32_bf16 v[104:107], v[140:143], v[216:219], v[104:107]
	v_mfma_f32_16x16x32_bf16 v[100:103], v[132:135], v[228:231], v[100:103]
	v_mfma_f32_16x16x32_bf16 v[96:99], v[140:143], v[228:231], v[96:99]
	s_barrier
	s_add_i32 s27, 0, 0x14000
	s_add_i32 s37, s47, s76
	s_mov_b32 m0, s37
	ds_read_b128 v[232:235], v192 offset:16384
	ds_read_b128 v[236:239], v192 offset:17408
	ds_read_b128 v[240:243], v192 offset:18432
	ds_read_b128 v[244:247], v192 offset:19456
	global_load_lds_dwordx4 v148, s[50:51]
	s_add_i32 m0, s37, 0x2000
	s_nop 0
	global_load_lds_dwordx4 v152, s[50:51]
	s_waitcnt lgkmcnt(0)
	s_barrier
	v_mfma_f32_16x16x32_bf16 v[92:95], v[232:235], v[162:165], v[92:95]
	v_mfma_f32_16x16x32_bf16 v[88:91], v[240:243], v[162:165], v[88:91]
	v_mfma_f32_16x16x32_bf16 v[84:87], v[232:235], v[196:199], v[84:87]
	v_mfma_f32_16x16x32_bf16 v[80:83], v[240:243], v[196:199], v[80:83]
	v_mfma_f32_16x16x32_bf16 v[76:79], v[232:235], v[204:207], v[76:79]
	v_mfma_f32_16x16x32_bf16 v[72:75], v[240:243], v[204:207], v[72:75]
	v_mfma_f32_16x16x32_bf16 v[68:71], v[232:235], v[220:223], v[68:71]
	v_mfma_f32_16x16x32_bf16 v[64:67], v[240:243], v[220:223], v[64:67]
	v_mfma_f32_16x16x32_bf16 v[92:95], v[236:239], v[166:169], v[92:95]
	v_mfma_f32_16x16x32_bf16 v[88:91], v[244:247], v[166:169], v[88:91]
	v_mfma_f32_16x16x32_bf16 v[84:87], v[236:239], v[200:203], v[84:87]
	v_mfma_f32_16x16x32_bf16 v[80:83], v[244:247], v[200:203], v[80:83]
	v_mfma_f32_16x16x32_bf16 v[76:79], v[236:239], v[216:219], v[76:79]
	v_mfma_f32_16x16x32_bf16 v[72:75], v[244:247], v[216:219], v[72:75]
	v_mfma_f32_16x16x32_bf16 v[68:71], v[236:239], v[228:231], v[68:71]
	v_mfma_f32_16x16x32_bf16 v[64:67], v[244:247], v[228:231], v[64:67]
	s_barrier
	s_mov_b32 m0, s77
	v_lshl_add_u64 v[224:225], s[52:53], 0, v[146:147]
	ds_read_b128 v[162:165], v194 offset:16384
	ds_read_b128 v[166:169], v194 offset:17408
	ds_read_b128 v[196:199], v194 offset:18432
	ds_read_b128 v[200:203], v194 offset:19456
	ds_read_b128 v[204:207], v194 offset:20480
	ds_read_b128 v[216:219], v194 offset:21504
	ds_read_b128 v[220:223], v194 offset:22528
	ds_read_b128 v[228:231], v194 offset:23552
	global_load_lds_dwordx4 v[224:225], off
	v_lshl_add_u64 v[248:249], s[52:53], 0, v[150:151]
	s_mov_b32 m0, s78
	s_nop 0
	global_load_lds_dwordx4 v[248:249], off
	s_add_u32 s56, s50, 0x40000
	s_addc_u32 s57, s51, 0
	s_add_i32 s27, s27, s76
	s_mov_b32 m0, s27
	s_nop 0
	global_load_lds_dwordx4 v148, s[56:57]
	s_add_i32 m0, s27, 0x2000
	s_nop 0
	global_load_lds_dwordx4 v152, s[56:57]
	s_waitcnt lgkmcnt(0)
	s_waitcnt vmcnt(6)
	s_barrier
	v_mfma_f32_16x16x32_bf16 v[60:63], v[128:131], v[162:165], v[60:63]
	v_mfma_f32_16x16x32_bf16 v[56:59], v[136:139], v[162:165], v[56:59]
	v_mfma_f32_16x16x32_bf16 v[52:55], v[128:131], v[196:199], v[52:55]
	v_mfma_f32_16x16x32_bf16 v[48:51], v[136:139], v[196:199], v[48:51]
	v_mfma_f32_16x16x32_bf16 v[44:47], v[128:131], v[204:207], v[44:47]
	v_mfma_f32_16x16x32_bf16 v[40:43], v[136:139], v[204:207], v[40:43]
	v_mfma_f32_16x16x32_bf16 v[36:39], v[128:131], v[220:223], v[36:39]
	v_mfma_f32_16x16x32_bf16 v[32:35], v[136:139], v[220:223], v[32:35]
	v_mfma_f32_16x16x32_bf16 v[60:63], v[132:135], v[166:169], v[60:63]
	v_mfma_f32_16x16x32_bf16 v[56:59], v[140:143], v[166:169], v[56:59]
	v_mfma_f32_16x16x32_bf16 v[52:55], v[132:135], v[200:203], v[52:55]
	v_mfma_f32_16x16x32_bf16 v[48:51], v[140:143], v[200:203], v[48:51]
	v_mfma_f32_16x16x32_bf16 v[44:47], v[132:135], v[216:219], v[44:47]
	v_mfma_f32_16x16x32_bf16 v[40:43], v[140:143], v[216:219], v[40:43]
	v_mfma_f32_16x16x32_bf16 v[36:39], v[132:135], v[228:231], v[36:39]
	v_mfma_f32_16x16x32_bf16 v[32:35], v[140:143], v[228:231], v[32:35]
	v_mfma_f32_16x16x32_bf16 v[28:31], v[232:235], v[162:165], v[28:31]
	v_mfma_f32_16x16x32_bf16 v[24:27], v[240:243], v[162:165], v[24:27]
	v_mfma_f32_16x16x32_bf16 v[20:23], v[232:235], v[196:199], v[20:23]
	v_mfma_f32_16x16x32_bf16 v[16:19], v[240:243], v[196:199], v[16:19]
	v_mfma_f32_16x16x32_bf16 v[12:15], v[232:235], v[204:207], v[12:15]
	v_mfma_f32_16x16x32_bf16 v[8:11], v[240:243], v[204:207], v[8:11]
	v_mfma_f32_16x16x32_bf16 v[4:7], v[232:235], v[220:223], v[4:7]
	v_mfma_f32_16x16x32_bf16 v[0:3], v[240:243], v[220:223], v[0:3]
	v_mfma_f32_16x16x32_bf16 v[28:31], v[236:239], v[166:169], v[28:31]
	v_mfma_f32_16x16x32_bf16 v[24:27], v[244:247], v[166:169], v[24:27]
	v_mfma_f32_16x16x32_bf16 v[20:23], v[236:239], v[200:203], v[20:23]
	v_mfma_f32_16x16x32_bf16 v[16:19], v[244:247], v[200:203], v[16:19]
	v_mfma_f32_16x16x32_bf16 v[12:15], v[236:239], v[216:219], v[12:15]
	v_mfma_f32_16x16x32_bf16 v[8:11], v[244:247], v[216:219], v[8:11]
	v_mfma_f32_16x16x32_bf16 v[4:7], v[236:239], v[228:231], v[4:7]
	v_mfma_f32_16x16x32_bf16 v[0:3], v[244:247], v[228:231], v[0:3]
	s_barrier
	s_add_i32 s27, 0, 0x18000
	ds_read_b128 v[128:131], v192 offset:32768
	ds_read_b128 v[132:135], v192 offset:33792
	ds_read_b128 v[136:139], v192 offset:34816
	ds_read_b128 v[140:143], v192 offset:35840
	s_add_u32 s52, s52, 0x40000
	s_addc_u32 s53, s53, 0
	s_mov_b32 m0, s81
	ds_read_b128 v[162:165], v194 offset:32768
	ds_read_b128 v[166:169], v194 offset:33792
	ds_read_b128 v[196:199], v194 offset:34816
	ds_read_b128 v[200:203], v194 offset:35840
	ds_read_b128 v[204:207], v194 offset:36864
	ds_read_b128 v[216:219], v194 offset:37888
	ds_read_b128 v[220:223], v194 offset:38912
	ds_read_b128 v[228:231], v194 offset:39936
	global_load_lds_dwordx4 v146, s[52:53]
	s_mov_b32 m0, s82
	s_nop 0
	global_load_lds_dwordx4 v150, s[52:53]
	s_waitcnt lgkmcnt(0)
	s_barrier
	v_mfma_f32_16x16x32_bf16 v[124:127], v[128:131], v[162:165], v[124:127]
	v_mfma_f32_16x16x32_bf16 v[120:123], v[136:139], v[162:165], v[120:123]
	v_mfma_f32_16x16x32_bf16 v[116:119], v[128:131], v[196:199], v[116:119]
	v_mfma_f32_16x16x32_bf16 v[112:115], v[136:139], v[196:199], v[112:115]
	v_mfma_f32_16x16x32_bf16 v[108:111], v[128:131], v[204:207], v[108:111]
	v_mfma_f32_16x16x32_bf16 v[104:107], v[136:139], v[204:207], v[104:107]
	v_mfma_f32_16x16x32_bf16 v[100:103], v[128:131], v[220:223], v[100:103]
	v_mfma_f32_16x16x32_bf16 v[96:99], v[136:139], v[220:223], v[96:99]
	v_mfma_f32_16x16x32_bf16 v[124:127], v[132:135], v[166:169], v[124:127]
	v_mfma_f32_16x16x32_bf16 v[120:123], v[140:143], v[166:169], v[120:123]
	v_mfma_f32_16x16x32_bf16 v[116:119], v[132:135], v[200:203], v[116:119]
	v_mfma_f32_16x16x32_bf16 v[112:115], v[140:143], v[200:203], v[112:115]
	v_mfma_f32_16x16x32_bf16 v[108:111], v[132:135], v[216:219], v[108:111]
	v_mfma_f32_16x16x32_bf16 v[104:107], v[140:143], v[216:219], v[104:107]
	v_mfma_f32_16x16x32_bf16 v[100:103], v[132:135], v[228:231], v[100:103]
	v_mfma_f32_16x16x32_bf16 v[96:99], v[140:143], v[228:231], v[96:99]
	s_barrier
	s_add_i32 s37, 0, 0x1c000
	s_add_i32 s27, s27, s76
	s_add_u32 s56, s50, s18
	s_addc_u32 s57, s51, s19
	s_mov_b32 m0, s27
	ds_read_b128 v[232:235], v192 offset:49152
	ds_read_b128 v[236:239], v192 offset:50176
	ds_read_b128 v[240:243], v192 offset:51200
	ds_read_b128 v[244:247], v192 offset:52224
	global_load_lds_dwordx4 v148, s[56:57]
	s_add_u32 s56, s50, s18
	s_addc_u32 s57, s51, s19
	s_add_i32 m0, s27, 0x2000
	s_nop 0
	global_load_lds_dwordx4 v152, s[56:57]
	s_waitcnt lgkmcnt(0)
	s_barrier
	v_mfma_f32_16x16x32_bf16 v[92:95], v[232:235], v[162:165], v[92:95]
	v_mfma_f32_16x16x32_bf16 v[88:91], v[240:243], v[162:165], v[88:91]
	v_mfma_f32_16x16x32_bf16 v[84:87], v[232:235], v[196:199], v[84:87]
	v_mfma_f32_16x16x32_bf16 v[80:83], v[240:243], v[196:199], v[80:83]
	v_mfma_f32_16x16x32_bf16 v[76:79], v[232:235], v[204:207], v[76:79]
	v_mfma_f32_16x16x32_bf16 v[72:75], v[240:243], v[204:207], v[72:75]
	v_mfma_f32_16x16x32_bf16 v[68:71], v[232:235], v[220:223], v[68:71]
	v_mfma_f32_16x16x32_bf16 v[64:67], v[240:243], v[220:223], v[64:67]
	v_mfma_f32_16x16x32_bf16 v[92:95], v[236:239], v[166:169], v[92:95]
	v_mfma_f32_16x16x32_bf16 v[88:91], v[244:247], v[166:169], v[88:91]
	v_mfma_f32_16x16x32_bf16 v[84:87], v[236:239], v[200:203], v[84:87]
	v_mfma_f32_16x16x32_bf16 v[80:83], v[244:247], v[200:203], v[80:83]
	v_mfma_f32_16x16x32_bf16 v[76:79], v[236:239], v[216:219], v[76:79]
	v_mfma_f32_16x16x32_bf16 v[72:75], v[244:247], v[216:219], v[72:75]
	v_mfma_f32_16x16x32_bf16 v[68:71], v[236:239], v[228:231], v[68:71]
	v_mfma_f32_16x16x32_bf16 v[64:67], v[244:247], v[228:231], v[64:67]
	s_barrier
	s_mov_b32 m0, s80
	v_lshl_add_u64 v[176:177], v[224:225], 0, s[18:19]
	ds_read_b128 v[162:165], v194 offset:49152
	ds_read_b128 v[166:169], v194 offset:50176
	ds_read_b128 v[196:199], v194 offset:51200
	ds_read_b128 v[200:203], v194 offset:52224
	ds_read_b128 v[204:207], v194 offset:53248
	ds_read_b128 v[216:219], v194 offset:54272
	ds_read_b128 v[220:223], v194 offset:55296
	ds_read_b128 v[228:231], v194 offset:56320
	global_load_lds_dwordx4 v[176:177], off
	v_lshl_add_u64 v[176:177], v[248:249], 0, s[18:19]
	s_mov_b32 m0, s83
	s_nop 0
	global_load_lds_dwordx4 v[176:177], off
	s_add_u32 s50, s50, 0x40080
	s_addc_u32 s51, s51, 0
	s_add_i32 s27, s37, s76
	s_mov_b32 m0, s27
	s_nop 0
	global_load_lds_dwordx4 v148, s[50:51]
	s_add_i32 m0, s27, 0x2000
	s_nop 0
	global_load_lds_dwordx4 v152, s[50:51]
	s_waitcnt lgkmcnt(0)
	s_waitcnt vmcnt(6)
	s_barrier
	v_mfma_f32_16x16x32_bf16 v[60:63], v[128:131], v[162:165], v[60:63]
	v_mfma_f32_16x16x32_bf16 v[56:59], v[136:139], v[162:165], v[56:59]
	v_mfma_f32_16x16x32_bf16 v[52:55], v[128:131], v[196:199], v[52:55]
	v_mfma_f32_16x16x32_bf16 v[48:51], v[136:139], v[196:199], v[48:51]
	v_mfma_f32_16x16x32_bf16 v[44:47], v[128:131], v[204:207], v[44:47]
	v_mfma_f32_16x16x32_bf16 v[40:43], v[136:139], v[204:207], v[40:43]
	v_mfma_f32_16x16x32_bf16 v[36:39], v[128:131], v[220:223], v[36:39]
	v_mfma_f32_16x16x32_bf16 v[32:35], v[136:139], v[220:223], v[32:35]
	v_mfma_f32_16x16x32_bf16 v[60:63], v[132:135], v[166:169], v[60:63]
	v_mfma_f32_16x16x32_bf16 v[56:59], v[140:143], v[166:169], v[56:59]
	v_mfma_f32_16x16x32_bf16 v[52:55], v[132:135], v[200:203], v[52:55]
	v_mfma_f32_16x16x32_bf16 v[48:51], v[140:143], v[200:203], v[48:51]
	v_mfma_f32_16x16x32_bf16 v[44:47], v[132:135], v[216:219], v[44:47]
	v_mfma_f32_16x16x32_bf16 v[40:43], v[140:143], v[216:219], v[40:43]
	v_mfma_f32_16x16x32_bf16 v[36:39], v[132:135], v[228:231], v[36:39]
	v_mfma_f32_16x16x32_bf16 v[32:35], v[140:143], v[228:231], v[32:35]
	v_mfma_f32_16x16x32_bf16 v[28:31], v[232:235], v[162:165], v[28:31]
	v_mfma_f32_16x16x32_bf16 v[24:27], v[240:243], v[162:165], v[24:27]
	v_mfma_f32_16x16x32_bf16 v[20:23], v[232:235], v[196:199], v[20:23]
	v_mfma_f32_16x16x32_bf16 v[16:19], v[240:243], v[196:199], v[16:19]
	v_mfma_f32_16x16x32_bf16 v[12:15], v[232:235], v[204:207], v[12:15]
	v_mfma_f32_16x16x32_bf16 v[8:11], v[240:243], v[204:207], v[8:11]
	v_mfma_f32_16x16x32_bf16 v[4:7], v[232:235], v[220:223], v[4:7]
	v_mfma_f32_16x16x32_bf16 v[0:3], v[240:243], v[220:223], v[0:3]
	v_mfma_f32_16x16x32_bf16 v[28:31], v[236:239], v[166:169], v[28:31]
	v_mfma_f32_16x16x32_bf16 v[24:27], v[244:247], v[166:169], v[24:27]
	v_mfma_f32_16x16x32_bf16 v[20:23], v[236:239], v[200:203], v[20:23]
	v_mfma_f32_16x16x32_bf16 v[16:19], v[244:247], v[200:203], v[16:19]
	v_mfma_f32_16x16x32_bf16 v[12:15], v[236:239], v[216:219], v[12:15]
	v_mfma_f32_16x16x32_bf16 v[8:11], v[244:247], v[216:219], v[8:11]
	v_mfma_f32_16x16x32_bf16 v[4:7], v[236:239], v[228:231], v[4:7]
	v_mfma_f32_16x16x32_bf16 v[0:3], v[244:247], v[228:231], v[0:3]
	s_barrier
	s_add_i32 s36, s36, 2
	s_add_u32 s0, s0, 0x100
	s_addc_u32 s1, s1, 0
	s_add_u32 s34, s34, 0x100
	s_addc_u32 s35, s35, 0
	s_cmp_gt_u32 s36, 13
	s_cbranch_scc0 .LBB0_351
	s_lshl_b32 s0, s11, 8
	s_or_b32 s50, s0, s79
	s_ashr_i32 s51, s50, 31
	v_lshl_add_u64 v[140:141], s[50:51], 3, v[154:155]
	global_load_dwordx4 v[128:131], v[140:141], off offset:48
	global_load_dwordx4 v[132:135], v[140:141], off offset:32
	global_load_dwordx4 v[136:139], v[140:141], off offset:16
	global_load_dwordx4 v[162:165], v[140:141], off
	s_mov_b32 s34, 0x35800000
	s_mov_b32 s0, 0x358637bd
	v_mov_b64_e32 v[168:169], s[0:1]
	s_mov_b32 s30, 0x45800000
	s_cmp_lt_u32 s10, 2
	s_waitcnt vmcnt(0)
	v_ffbh_u32_e32 v142, v165
	v_min_u32_e32 v161, 32, v142
	v_lshlrev_b64 v[142:143], v161, v[164:165]
	v_min_u32_e32 v142, 1, v142
	v_or_b32_e32 v142, v143, v142
	v_cvt_f32_u32_e32 v142, v142
	v_sub_u32_e32 v143, 32, v161
	v_ldexp_f32 v143, v142, v143
	v_ffbh_u32_e32 v142, v163
	v_min_u32_e32 v142, 32, v142
	v_lshlrev_b64 v[162:163], v142, v[162:163]
	v_min_u32_e32 v161, 1, v162
	v_or_b32_e32 v161, v163, v161
	v_cvt_f32_u32_e32 v161, v161
	v_sub_u32_e32 v142, 32, v142
	v_ldexp_f32 v142, v161, v142
	v_pk_mul_f32 v[142:143], v[142:143], s[34:35] op_sel_hi:[1,0]
	s_nop 0
	v_pk_fma_f32 v[142:143], v[142:143], s[2:3], v[168:169] op_sel_hi:[1,0,0]
	s_nop 0
	v_mul_f32_e32 v161, 0x4b800000, v142
	v_cmp_gt_f32_e64 s[0:1], s89, v142
	v_cmp_gt_f32_e32 vcc, s89, v143
	s_nop 0
	v_cndmask_b32_e64 v142, v142, v161, s[0:1]
	v_mul_f32_e32 v161, 0x4b800000, v143
	v_cndmask_b32_e32 v143, v143, v161, vcc
	v_rsq_f32_e32 v142, v142
	v_rsq_f32_e32 v143, v143
	s_nop 0
	v_pk_mul_f32 v[162:163], v[142:143], s[30:31] op_sel_hi:[1,0]
	s_nop 0
	v_cndmask_b32_e64 v166, v142, v162, s[0:1]
	v_ffbh_u32_e32 v142, v139
	v_min_u32_e32 v142, 32, v142
	v_lshlrev_b64 v[138:139], v142, v[138:139]
	v_min_u32_e32 v138, 1, v138
	v_or_b32_e32 v138, v139, v138
	v_cvt_f32_u32_e32 v138, v138
	v_sub_u32_e32 v139, 32, v142
	v_cndmask_b32_e32 v167, v143, v163, vcc
	v_pk_mul_f32 v[60:61], v[60:61], v[166:167]
	v_ldexp_f32 v139, v138, v139
	v_ffbh_u32_e32 v138, v137
	v_min_u32_e32 v138, 32, v138
	v_lshlrev_b64 v[136:137], v138, v[136:137]
	v_min_u32_e32 v136, 1, v136
	v_or_b32_e32 v136, v137, v136
	v_cvt_f32_u32_e32 v136, v136
	v_sub_u32_e32 v137, 32, v138
	v_pk_mul_f32 v[52:53], v[52:53], v[166:167]
	v_pk_mul_f32 v[44:45], v[44:45], v[166:167]
	v_ldexp_f32 v138, v136, v137
	v_pk_mul_f32 v[136:137], v[138:139], s[34:35] op_sel_hi:[1,0]
	v_pk_mul_f32 v[36:37], v[36:37], v[166:167]
	v_pk_fma_f32 v[136:137], v[136:137], s[2:3], v[168:169] op_sel_hi:[1,0,0]
	s_nop 0
	v_mul_f32_e32 v138, 0x4b800000, v136
	v_cmp_gt_f32_e64 s[0:1], s89, v136
	v_cmp_gt_f32_e32 vcc, s89, v137
	s_nop 0
	v_cndmask_b32_e64 v136, v136, v138, s[0:1]
	v_mul_f32_e32 v138, 0x4b800000, v137
	v_cndmask_b32_e32 v137, v137, v138, vcc
	v_rsq_f32_e32 v136, v136
	v_rsq_f32_e32 v137, v137
	s_nop 0
	v_pk_mul_f32 v[138:139], v[136:137], s[30:31] op_sel_hi:[1,0]
	s_nop 0
	v_cndmask_b32_e64 v162, v136, v138, s[0:1]
	v_ffbh_u32_e32 v136, v135
	v_min_u32_e32 v136, 32, v136
	v_lshlrev_b64 v[134:135], v136, v[134:135]
	v_min_u32_e32 v134, 1, v134
	v_or_b32_e32 v134, v135, v134
	v_cvt_f32_u32_e32 v134, v134
	v_sub_u32_e32 v135, 32, v136
	v_cndmask_b32_e32 v163, v137, v139, vcc
	v_ldexp_f32 v135, v134, v135
	v_ffbh_u32_e32 v134, v133
	v_min_u32_e32 v134, 32, v134
	v_lshlrev_b64 v[132:133], v134, v[132:133]
	v_min_u32_e32 v132, 1, v132
	v_or_b32_e32 v132, v133, v132
	v_cvt_f32_u32_e32 v132, v132
	v_sub_u32_e32 v133, 32, v134
	v_ldexp_f32 v134, v132, v133
	v_pk_mul_f32 v[132:133], v[134:135], s[34:35] op_sel_hi:[1,0]
	s_nop 0
	v_pk_fma_f32 v[132:133], v[132:133], s[2:3], v[168:169] op_sel_hi:[1,0,0]
	s_nop 0
	v_mul_f32_e32 v134, 0x4b800000, v132
	v_cmp_gt_f32_e64 s[0:1], s89, v132
	v_cmp_gt_f32_e32 vcc, s89, v133
	s_nop 0
	v_cndmask_b32_e64 v132, v132, v134, s[0:1]
	v_mul_f32_e32 v134, 0x4b800000, v133
	v_cndmask_b32_e32 v133, v133, v134, vcc
	v_rsq_f32_e32 v132, v132
	v_rsq_f32_e32 v133, v133
	s_nop 0
	v_pk_mul_f32 v[134:135], v[132:133], s[30:31] op_sel_hi:[1,0]
	s_nop 0
	v_cndmask_b32_e64 v188, v132, v134, s[0:1]
	v_ffbh_u32_e32 v132, v131
	v_min_u32_e32 v132, 32, v132
	v_lshlrev_b64 v[130:131], v132, v[130:131]
	v_min_u32_e32 v130, 1, v130
	v_or_b32_e32 v130, v131, v130
	v_cvt_f32_u32_e32 v130, v130
	v_sub_u32_e32 v131, 32, v132
	v_cndmask_b32_e32 v189, v133, v135, vcc
	v_pk_mul_f32 v[56:57], v[56:57], v[188:189]
	v_ldexp_f32 v131, v130, v131
	v_ffbh_u32_e32 v130, v129
	v_min_u32_e32 v130, 32, v130
	v_lshlrev_b64 v[128:129], v130, v[128:129]
	v_min_u32_e32 v128, 1, v128
	v_or_b32_e32 v128, v129, v128
	v_cvt_f32_u32_e32 v128, v128
	v_sub_u32_e32 v129, 32, v130
	v_pk_mul_f32 v[48:49], v[48:49], v[188:189]
	v_pk_mul_f32 v[40:41], v[40:41], v[188:189]
	v_ldexp_f32 v130, v128, v129
	v_pk_mul_f32 v[128:129], v[130:131], s[34:35] op_sel_hi:[1,0]
	v_pk_mul_f32 v[32:33], v[32:33], v[188:189]
	v_pk_fma_f32 v[128:129], v[128:129], s[2:3], v[168:169] op_sel_hi:[1,0,0]
	s_nop 0
	v_mul_f32_e32 v130, 0x4b800000, v128
	v_cmp_gt_f32_e64 s[0:1], s89, v128
	v_cmp_gt_f32_e32 vcc, s89, v129
	s_nop 0
	v_cndmask_b32_e64 v128, v128, v130, s[0:1]
	v_mul_f32_e32 v130, 0x4b800000, v129
	v_cndmask_b32_e32 v129, v129, v130, vcc
	v_rsq_f32_e32 v128, v128
	v_rsq_f32_e32 v129, v129
	s_nop 0
	v_pk_mul_f32 v[130:131], v[128:129], s[30:31] op_sel_hi:[1,0]
	s_nop 0
	v_cndmask_b32_e32 v165, v129, v131, vcc
	v_cndmask_b32_e64 v164, v128, v130, s[0:1]
	global_load_dwordx4 v[128:131], v[140:141], off offset:1072
	global_load_dwordx4 v[132:135], v[140:141], off offset:1056
	global_load_dwordx4 v[136:139], v[140:141], off offset:1040
	s_nop 0
	global_load_dwordx4 v[140:143], v[140:141], off offset:1024
	s_waitcnt vmcnt(0)
	v_ffbh_u32_e32 v161, v143
	v_min_u32_e32 v161, 32, v161
	v_lshlrev_b64 v[142:143], v161, v[142:143]
	v_min_u32_e32 v142, 1, v142
	v_or_b32_e32 v142, v143, v142
	v_cvt_f32_u32_e32 v142, v142
	v_sub_u32_e32 v143, 32, v161
	v_ldexp_f32 v143, v142, v143
	v_ffbh_u32_e32 v142, v141
	v_min_u32_e32 v142, 32, v142
	v_lshlrev_b64 v[140:141], v142, v[140:141]
	v_min_u32_e32 v140, 1, v140
	v_or_b32_e32 v140, v141, v140
	v_cvt_f32_u32_e32 v140, v140
	v_sub_u32_e32 v141, 32, v142
	v_ldexp_f32 v142, v140, v141
	v_pk_mul_f32 v[140:141], v[142:143], s[34:35] op_sel_hi:[1,0]
	s_nop 0
	v_pk_fma_f32 v[140:141], v[140:141], s[2:3], v[168:169] op_sel_hi:[1,0,0]
	s_nop 0
	v_mul_f32_e32 v142, 0x4b800000, v140
	v_cmp_gt_f32_e64 s[0:1], s89, v140
	v_cmp_gt_f32_e32 vcc, s89, v141
	s_nop 0
	v_cndmask_b32_e64 v140, v140, v142, s[0:1]
	v_mul_f32_e32 v142, 0x4b800000, v141
	v_cndmask_b32_e32 v141, v141, v142, vcc
	v_rsq_f32_e32 v140, v140
	v_rsq_f32_e32 v141, v141
	s_nop 0
	v_pk_mul_f32 v[142:143], v[140:141], s[30:31] op_sel_hi:[1,0]
	s_nop 0
	v_cndmask_b32_e64 v142, v140, v142, s[0:1]
	v_ffbh_u32_e32 v140, v139
	v_min_u32_e32 v140, 32, v140
	v_lshlrev_b64 v[138:139], v140, v[138:139]
	v_min_u32_e32 v138, 1, v138
	v_or_b32_e32 v138, v139, v138
	v_cvt_f32_u32_e32 v138, v138
	v_sub_u32_e32 v139, 32, v140
	v_cndmask_b32_e32 v143, v141, v143, vcc
	v_pk_mul_f32 v[140:141], v[124:125], v[166:167]
	v_ldexp_f32 v139, v138, v139
	v_ffbh_u32_e32 v138, v137
	v_min_u32_e32 v138, 32, v138
	v_lshlrev_b64 v[136:137], v138, v[136:137]
	v_min_u32_e32 v136, 1, v136
	v_or_b32_e32 v136, v137, v136
	v_cvt_f32_u32_e32 v136, v136
	v_sub_u32_e32 v137, 32, v138
	v_pk_mul_f32 v[28:29], v[28:29], v[142:143]
	v_pk_mul_f32 v[20:21], v[20:21], v[142:143]
	v_ldexp_f32 v138, v136, v137
	v_pk_mul_f32 v[136:137], v[138:139], s[34:35] op_sel_hi:[1,0]
	v_pk_mul_f32 v[12:13], v[12:13], v[142:143]
	v_pk_fma_f32 v[136:137], v[136:137], s[2:3], v[168:169] op_sel_hi:[1,0,0]
	v_pk_mul_f32 v[4:5], v[4:5], v[142:143]
	v_mul_f32_e32 v138, 0x4b800000, v136
	v_cmp_gt_f32_e64 s[0:1], s89, v136
	v_cmp_gt_f32_e32 vcc, s89, v137
	s_nop 0
	v_cndmask_b32_e64 v136, v136, v138, s[0:1]
	v_mul_f32_e32 v138, 0x4b800000, v137
	v_cndmask_b32_e32 v137, v137, v138, vcc
	v_rsq_f32_e32 v136, v136
	v_rsq_f32_e32 v137, v137
	s_nop 0
	v_pk_mul_f32 v[138:139], v[136:137], s[30:31] op_sel_hi:[1,0]
	s_nop 0
	v_cndmask_b32_e64 v136, v136, v138, s[0:1]
	v_ffbh_u32_e32 v138, v135
	v_min_u32_e32 v138, 32, v138
	v_lshlrev_b64 v[134:135], v138, v[134:135]
	v_min_u32_e32 v134, 1, v134
	v_or_b32_e32 v134, v135, v134
	v_cvt_f32_u32_e32 v134, v134
	v_sub_u32_e32 v135, 32, v138
	v_cndmask_b32_e32 v137, v137, v139, vcc
	v_pk_mul_f32 v[138:139], v[120:121], v[188:189]
	v_ldexp_f32 v135, v134, v135
	v_ffbh_u32_e32 v134, v133
	v_min_u32_e32 v134, 32, v134
	v_lshlrev_b64 v[132:133], v134, v[132:133]
	v_min_u32_e32 v132, 1, v132
	v_or_b32_e32 v132, v133, v132
	v_cvt_f32_u32_e32 v132, v132
	v_sub_u32_e32 v133, 32, v134
	v_pk_mul_f32 v[120:121], v[84:85], v[142:143]
	v_ldexp_f32 v134, v132, v133
	v_pk_mul_f32 v[132:133], v[134:135], s[34:35] op_sel_hi:[1,0]
	s_nop 0
	v_pk_fma_f32 v[132:133], v[132:133], s[2:3], v[168:169] op_sel_hi:[1,0,0]
	s_nop 0
	v_mul_f32_e32 v134, 0x4b800000, v132
	v_cmp_gt_f32_e64 s[0:1], s89, v132
	v_cmp_gt_f32_e32 vcc, s89, v133
	s_nop 0
	v_cndmask_b32_e64 v132, v132, v134, s[0:1]
	v_mul_f32_e32 v134, 0x4b800000, v133
	v_cndmask_b32_e32 v133, v133, v134, vcc
	v_rsq_f32_e32 v132, v132
	v_rsq_f32_e32 v133, v133
	s_nop 0
	v_pk_mul_f32 v[134:135], v[132:133], s[30:31] op_sel_hi:[1,0]
	s_nop 0
	v_cndmask_b32_e64 v176, v132, v134, s[0:1]
	v_ffbh_u32_e32 v132, v131
	v_min_u32_e32 v132, 32, v132
	v_lshlrev_b64 v[130:131], v132, v[130:131]
	v_min_u32_e32 v130, 1, v130
	v_or_b32_e32 v130, v131, v130
	v_cvt_f32_u32_e32 v130, v130
	v_sub_u32_e32 v131, 32, v132
	v_cndmask_b32_e32 v177, v133, v135, vcc
	v_pk_mul_f32 v[124:125], v[88:89], v[176:177]
	v_ldexp_f32 v131, v130, v131
	v_ffbh_u32_e32 v130, v129
	v_min_u32_e32 v130, 32, v130
	v_lshlrev_b64 v[128:129], v130, v[128:129]
	v_min_u32_e32 v128, 1, v128
	v_or_b32_e32 v128, v129, v128
	v_cvt_f32_u32_e32 v128, v128
	v_sub_u32_e32 v129, 32, v130
	v_pk_mul_f32 v[134:135], v[116:117], v[166:167]
	v_pk_mul_f32 v[132:133], v[112:113], v[188:189]
	v_ldexp_f32 v130, v128, v129
	v_pk_mul_f32 v[128:129], v[130:131], s[34:35] op_sel_hi:[1,0]
	v_pk_mul_f32 v[116:117], v[80:81], v[176:177]
	v_pk_fma_f32 v[128:129], v[128:129], s[2:3], v[168:169] op_sel_hi:[1,0,0]
	v_pk_mul_f32 v[88:89], v[104:105], v[188:189]
	v_mul_f32_e32 v130, 0x4b800000, v128
	v_cmp_gt_f32_e64 s[0:1], s89, v128
	v_cmp_gt_f32_e32 vcc, s89, v129
	v_pk_mul_f32 v[112:113], v[76:77], v[142:143]
	v_cndmask_b32_e64 v128, v128, v130, s[0:1]
	v_mul_f32_e32 v130, 0x4b800000, v129
	v_cndmask_b32_e32 v129, v129, v130, vcc
	v_rsq_f32_e32 v128, v128
	v_rsq_f32_e32 v129, v129
	v_pk_mul_f32 v[76:77], v[100:101], v[166:167]
	v_pk_mul_f32 v[104:105], v[68:69], v[142:143]
	v_pk_mul_f32 v[24:25], v[24:25], v[176:177]
	v_pk_mul_f32 v[130:131], v[128:129], s[30:31] op_sel_hi:[1,0]
	v_pk_mul_f32 v[16:17], v[16:17], v[176:177]
	v_cndmask_b32_e32 v129, v129, v131, vcc
	v_cndmask_b32_e64 v128, v128, v130, s[0:1]
	s_mov_b64 s[0:1], -1
	v_pk_mul_f32 v[130:131], v[92:93], v[142:143]
	v_pk_mul_f32 v[92:93], v[108:109], v[166:167]
	v_pk_mul_f32 v[108:109], v[72:73], v[176:177]
	v_pk_mul_f32 v[72:73], v[96:97], v[188:189]
	v_pk_mul_f32 v[96:97], v[64:65], v[176:177]
	v_pk_mul_f32 v[8:9], v[8:9], v[176:177]
	v_pk_mul_f32 v[0:1], v[0:1], v[176:177]
	s_cbranch_scc1 .LBB0_354
	v_lshl_add_u32 v68, s10, 8, v193
	v_ashrrev_i32_e32 v69, 31, v68
	v_pk_mul_f32 v[64:65], v[126:127], v[162:163]
	v_cvt_pk_bf16_f32 v80, v140, v141
	s_lshl_b64 s[0:1], s[50:51], 1
	v_cvt_pk_bf16_f32 v81, v64, v65
	v_lshlrev_b64 v[64:65], 13, v[68:69]
	v_lshl_add_u64 v[64:65], s[44:45], 0, v[64:65]
	v_lshl_add_u64 v[64:65], v[64:65], 0, s[0:1]
	v_lshl_add_u64 v[64:65], v[64:65], 0, v[144:145]
	v_mov_b32_e32 v161, v145
	v_lshl_add_u64 v[64:65], v[64:65], 0, v[160:161]
	global_store_dwordx2 v[64:65], v[80:81], off
	v_pk_mul_f32 v[80:81], v[122:123], v[164:165]
	v_cvt_pk_bf16_f32 v84, v138, v139
	s_nop 0
	v_cvt_pk_bf16_f32 v85, v80, v81
	v_pk_mul_f32 v[80:81], v[94:95], v[136:137]
	global_store_dwordx2 v[64:65], v[84:85], off offset:16
	v_cvt_pk_bf16_f32 v84, v130, v131
	v_cvt_pk_bf16_f32 v85, v80, v81
	v_pk_mul_f32 v[80:81], v[90:91], v[128:129]
	global_store_dwordx2 v[64:65], v[84:85], off offset:256
	v_cvt_pk_bf16_f32 v84, v124, v125
	v_cvt_pk_bf16_f32 v85, v80, v81
	v_or_b32_e32 v80, 16, v68
	v_ashrrev_i32_e32 v81, 31, v80
	v_lshlrev_b64 v[80:81], 13, v[80:81]
	v_lshl_add_u64 v[80:81], s[44:45], 0, v[80:81]
	v_lshl_add_u64 v[80:81], v[80:81], 0, s[0:1]
	v_lshl_add_u64 v[80:81], v[80:81], 0, v[144:145]
	global_store_dwordx2 v[64:65], v[84:85], off offset:272
	v_pk_mul_f32 v[84:85], v[118:119], v[162:163]
	v_cvt_pk_bf16_f32 v100, v134, v135
	v_lshl_add_u64 v[80:81], v[80:81], 0, v[160:161]
	v_cvt_pk_bf16_f32 v101, v84, v85
	global_store_dwordx2 v[80:81], v[100:101], off
	v_pk_mul_f32 v[84:85], v[114:115], v[164:165]
	v_cvt_pk_bf16_f32 v100, v132, v133
	s_nop 0
	v_cvt_pk_bf16_f32 v101, v84, v85
	global_store_dwordx2 v[80:81], v[100:101], off offset:16
	v_pk_mul_f32 v[84:85], v[86:87], v[136:137]
	v_cvt_pk_bf16_f32 v100, v120, v121
	s_nop 0
	v_cvt_pk_bf16_f32 v101, v84, v85
	global_store_dwordx2 v[80:81], v[100:101], off offset:256
	v_pk_mul_f32 v[84:85], v[82:83], v[128:129]
	v_cvt_pk_bf16_f32 v100, v116, v117
	s_nop 0
	v_cvt_pk_bf16_f32 v101, v84, v85
	global_store_dwordx2 v[80:81], v[100:101], off offset:272
	v_or_b32_e32 v80, 32, v68
	v_ashrrev_i32_e32 v81, 31, v80
	v_lshlrev_b64 v[80:81], 13, v[80:81]
	v_lshl_add_u64 v[80:81], s[44:45], 0, v[80:81]
	v_or_b32_e32 v68, 48, v68
	v_lshl_add_u64 v[80:81], v[80:81], 0, s[0:1]
	v_ashrrev_i32_e32 v69, 31, v68
	v_pk_mul_f32 v[84:85], v[110:111], v[162:163]
	v_lshl_add_u64 v[80:81], v[80:81], 0, v[144:145]
	v_lshlrev_b64 v[68:69], 13, v[68:69]
	v_cvt_pk_bf16_f32 v100, v92, v93
	v_cvt_pk_bf16_f32 v101, v84, v85
	v_lshl_add_u64 v[80:81], v[80:81], 0, v[160:161]
	v_pk_mul_f32 v[84:85], v[106:107], v[164:165]
	v_lshl_add_u64 v[68:69], s[44:45], 0, v[68:69]
	global_store_dwordx2 v[80:81], v[100:101], off
	v_cvt_pk_bf16_f32 v100, v88, v89
	v_cvt_pk_bf16_f32 v101, v84, v85
	v_pk_mul_f32 v[84:85], v[78:79], v[136:137]
	v_lshl_add_u64 v[68:69], v[68:69], 0, s[0:1]
	global_store_dwordx2 v[80:81], v[100:101], off offset:16
	v_cvt_pk_bf16_f32 v100, v112, v113
	v_cvt_pk_bf16_f32 v101, v84, v85
	v_pk_mul_f32 v[84:85], v[74:75], v[128:129]
	v_lshl_add_u64 v[68:69], v[68:69], 0, v[144:145]
	global_store_dwordx2 v[80:81], v[100:101], off offset:256
	v_cvt_pk_bf16_f32 v100, v108, v109
	v_cvt_pk_bf16_f32 v101, v84, v85
	global_store_dwordx2 v[80:81], v[100:101], off offset:272
	v_cvt_pk_bf16_f32 v84, v76, v77
	v_lshl_add_u64 v[68:69], v[68:69], 0, v[160:161]
	v_pk_mul_f32 v[80:81], v[102:103], v[162:163]
	s_mov_b64 s[0:1], 0x100000
	v_cvt_pk_bf16_f32 v85, v80, v81
	global_store_dwordx2 v[68:69], v[84:85], off
	v_cvt_pk_bf16_f32 v84, v72, v73
	v_pk_mul_f32 v[80:81], v[98:99], v[164:165]
	s_nop 0
	v_cvt_pk_bf16_f32 v85, v80, v81
	global_store_dwordx2 v[68:69], v[84:85], off offset:16
	v_cvt_pk_bf16_f32 v84, v104, v105
	v_pk_mul_f32 v[80:81], v[70:71], v[136:137]
	s_nop 0
	v_cvt_pk_bf16_f32 v85, v80, v81
	global_store_dwordx2 v[68:69], v[84:85], off offset:256
	v_cvt_pk_bf16_f32 v84, v96, v97
	v_pk_mul_f32 v[80:81], v[66:67], v[128:129]
	s_nop 0
	v_cvt_pk_bf16_f32 v85, v80, v81
	global_store_dwordx2 v[68:69], v[84:85], off offset:272
	v_add_co_u32_e32 v84, vcc, s29, v64
	v_pk_mul_f32 v[68:69], v[62:63], v[162:163]
	s_nop 0
	v_addc_co_u32_e32 v85, vcc, 0, v65, vcc
	v_cvt_pk_bf16_f32 v80, v60, v61
	v_cvt_pk_bf16_f32 v81, v68, v69
	v_lshl_add_u64 v[68:69], v[64:65], 0, s[0:1]
	global_store_dwordx2 v[84:85], v[80:81], off
	v_cvt_pk_bf16_f32 v84, v56, v57
	v_pk_mul_f32 v[80:81], v[58:59], v[164:165]
	s_mov_b64 s[0:1], 0x120000
	v_cvt_pk_bf16_f32 v85, v80, v81
	global_store_dwordx2 v[68:69], v[84:85], off offset:16
	v_cvt_pk_bf16_f32 v84, v28, v29
	v_pk_mul_f32 v[80:81], v[30:31], v[136:137]
	s_nop 0
	v_cvt_pk_bf16_f32 v85, v80, v81
	global_store_dwordx2 v[68:69], v[84:85], off offset:256
	v_cvt_pk_bf16_f32 v84, v24, v25
	v_pk_mul_f32 v[80:81], v[26:27], v[128:129]
	s_nop 0
	v_cvt_pk_bf16_f32 v85, v80, v81
	global_store_dwordx2 v[68:69], v[84:85], off offset:272
	v_add_co_u32_e32 v84, vcc, s49, v64
	v_pk_mul_f32 v[68:69], v[54:55], v[162:163]
	v_cvt_pk_bf16_f32 v80, v52, v53
	s_nop 0
	v_addc_co_u32_e32 v85, vcc, 0, v65, vcc
	v_cvt_pk_bf16_f32 v81, v68, v69
	v_lshl_add_u64 v[68:69], v[64:65], 0, s[0:1]
	global_store_dwordx2 v[84:85], v[80:81], off
	v_pk_mul_f32 v[80:81], v[50:51], v[164:165]
	v_cvt_pk_bf16_f32 v84, v48, v49
	s_mov_b64 s[0:1], 0x140000
	v_cvt_pk_bf16_f32 v85, v80, v81
	global_store_dwordx2 v[68:69], v[84:85], off offset:16
	v_pk_mul_f32 v[80:81], v[22:23], v[136:137]
	v_cvt_pk_bf16_f32 v84, v20, v21
	s_nop 0
	v_cvt_pk_bf16_f32 v85, v80, v81
	global_store_dwordx2 v[68:69], v[84:85], off offset:256
	v_pk_mul_f32 v[80:81], v[18:19], v[128:129]
	v_cvt_pk_bf16_f32 v84, v16, v17
	s_nop 0
	v_cvt_pk_bf16_f32 v85, v80, v81
	global_store_dwordx2 v[68:69], v[84:85], off offset:272
	v_pk_mul_f32 v[68:69], v[46:47], v[162:163]
	v_cvt_pk_bf16_f32 v80, v44, v45
	s_nop 0
	v_cvt_pk_bf16_f32 v81, v68, v69
	v_lshl_add_u64 v[68:69], v[64:65], 0, s[0:1]
	s_mov_b32 s0, 0x140000
	v_add_co_u32_e32 v84, vcc, s0, v64
	s_mov_b64 s[0:1], 0x160000
	s_nop 0
	v_addc_co_u32_e32 v85, vcc, 0, v65, vcc
	global_store_dwordx2 v[84:85], v[80:81], off
	v_pk_mul_f32 v[80:81], v[42:43], v[164:165]
	v_cvt_pk_bf16_f32 v84, v40, v41
	s_nop 0
	v_cvt_pk_bf16_f32 v85, v80, v81
	global_store_dwordx2 v[68:69], v[84:85], off offset:16
	v_pk_mul_f32 v[80:81], v[14:15], v[136:137]
	v_cvt_pk_bf16_f32 v84, v12, v13
	s_nop 0
	v_cvt_pk_bf16_f32 v85, v80, v81
	global_store_dwordx2 v[68:69], v[84:85], off offset:256
	v_pk_mul_f32 v[80:81], v[10:11], v[128:129]
	v_cvt_pk_bf16_f32 v84, v8, v9
	s_nop 0
	v_cvt_pk_bf16_f32 v85, v80, v81
	global_store_dwordx2 v[68:69], v[84:85], off offset:272
	v_pk_mul_f32 v[68:69], v[38:39], v[162:163]
	v_cvt_pk_bf16_f32 v80, v36, v37
	s_nop 0
	v_cvt_pk_bf16_f32 v81, v68, v69
	v_lshl_add_u64 v[68:69], v[64:65], 0, s[0:1]
	s_mov_b32 s0, 0x160000
	v_add_co_u32_e32 v64, vcc, s0, v64
	s_mov_b64 s[0:1], 0
	s_nop 0
	v_addc_co_u32_e32 v65, vcc, 0, v65, vcc
	global_store_dwordx2 v[64:65], v[80:81], off
	v_pk_mul_f32 v[64:65], v[34:35], v[164:165]
	v_cvt_pk_bf16_f32 v80, v32, v33
	s_nop 0
	v_cvt_pk_bf16_f32 v81, v64, v65
	global_store_dwordx2 v[68:69], v[80:81], off offset:16
	v_pk_mul_f32 v[64:65], v[6:7], v[136:137]
	v_cvt_pk_bf16_f32 v80, v4, v5
	s_nop 0
	v_cvt_pk_bf16_f32 v81, v64, v65
	global_store_dwordx2 v[68:69], v[80:81], off offset:256
	v_pk_mul_f32 v[64:65], v[2:3], v[128:129]
	v_cvt_pk_bf16_f32 v80, v0, v1
	s_nop 0
	v_cvt_pk_bf16_f32 v81, v64, v65
	s_nop 1
	global_store_dwordx2 v[68:69], v[80:81], off offset:272
